# plus s_setprio 0 moved behind the phase-closing barrier
# baseline (speedup 1.0000x reference)
.LBB0_298:
	s_lshl_b64 s[4:5], s[20:21], 17
	s_add_u32 s24, s2, s4
	s_addc_u32 s25, s19, s5
	s_and_b64 s[4:5], s[36:37], exec
	s_cselect_b32 s37, s25, s31
	s_cselect_b32 s36, s24, s30
	s_add_u32 s56, s30, 0x100
	s_addc_u32 s57, s31, 0
	s_add_u32 s80, s34, 0x100
	s_addc_u32 s81, s35, 0
	s_add_u32 s38, s30, 0x180
	s_addc_u32 s39, s31, 0
	s_add_i32 s4, 0, 0x10000
	s_add_i32 s17, 0, 0x14000
	v_add_u32_e32 v128, s4, v134
	v_add_u32_e32 v129, s17, v134
	ds_read_b128 v[0:3], v128
	ds_read_b128 v[4:7], v128 offset:1024
	ds_read_b128 v[8:11], v128 offset:2048
	ds_read_b128 v[12:15], v128 offset:3072
	ds_read_b128 v[16:19], v129
	ds_read_b128 v[20:23], v129 offset:1024
	ds_read_b128 v[24:27], v129 offset:2048
	ds_read_b128 v[28:31], v129 offset:3072
	s_add_u32 s70, s30, 0x10080
	s_addc_u32 s71, s31, 0
	s_add_i32 s5, s13, 0xc000
	s_mov_b32 m0, s5
	s_add_i32 s15, s13, 0xe000
	ds_read_b128 v[32:35], v135
	ds_read_b128 v[36:39], v135 offset:1024
	ds_read_b128 v[40:43], v135 offset:2048
	ds_read_b128 v[44:47], v135 offset:3072
	ds_read_b128 v[48:51], v135 offset:4096
	ds_read_b128 v[52:55], v135 offset:5120
	ds_read_b128 v[56:59], v135 offset:6144
	ds_read_b128 v[60:63], v135 offset:7168
	s_nop 0
	global_load_lds_dwordx4 v130, s[70:71]
	s_mov_b32 m0, s15
	s_nop 0
	global_load_lds_dwordx4 v132, s[70:71]
	s_waitcnt vmcnt(8)
	s_waitcnt lgkmcnt(0)
	s_setprio 1
	s_barrier
	v_mfma_f32_16x16x32_bf16 v[64:67], v[0:3], v[32:35], 0
	v_mfma_f32_16x16x32_bf16 v[68:71], v[8:11], v[32:35], 0
	v_mfma_f32_16x16x32_bf16 v[72:75], v[0:3], v[40:43], 0
	v_mfma_f32_16x16x32_bf16 v[76:79], v[8:11], v[40:43], 0
	v_mfma_f32_16x16x32_bf16 v[80:83], v[0:3], v[48:51], 0
	v_mfma_f32_16x16x32_bf16 v[84:87], v[8:11], v[48:51], 0
	v_mfma_f32_16x16x32_bf16 v[88:91], v[0:3], v[56:59], 0
	v_mfma_f32_16x16x32_bf16 v[92:95], v[8:11], v[56:59], 0
	v_mfma_f32_16x16x32_bf16 v[64:67], v[4:7], v[36:39], v[64:67]
	v_mfma_f32_16x16x32_bf16 v[68:71], v[12:15], v[36:39], v[68:71]
	v_mfma_f32_16x16x32_bf16 v[72:75], v[4:7], v[44:47], v[72:75]
	v_mfma_f32_16x16x32_bf16 v[76:79], v[12:15], v[44:47], v[76:79]
	v_mfma_f32_16x16x32_bf16 v[80:83], v[4:7], v[52:55], v[80:83]
	v_mfma_f32_16x16x32_bf16 v[84:87], v[12:15], v[52:55], v[84:87]
	v_mfma_f32_16x16x32_bf16 v[88:91], v[4:7], v[60:63], v[88:91]
	v_mfma_f32_16x16x32_bf16 v[92:95], v[12:15], v[60:63], v[92:95]
	v_mfma_f32_16x16x32_bf16 v[96:99], v[16:19], v[32:35], 0
	v_mfma_f32_16x16x32_bf16 v[32:35], v[24:27], v[32:35], 0
	v_mfma_f32_16x16x32_bf16 v[96:99], v[20:23], v[36:39], v[96:99]
	v_mfma_f32_16x16x32_bf16 v[32:35], v[28:31], v[36:39], v[32:35]
	v_mfma_f32_16x16x32_bf16 v[36:39], v[16:19], v[40:43], 0
	v_mfma_f32_16x16x32_bf16 v[40:43], v[24:27], v[40:43], 0
	v_mfma_f32_16x16x32_bf16 v[36:39], v[20:23], v[44:47], v[36:39]
	v_mfma_f32_16x16x32_bf16 v[40:43], v[28:31], v[44:47], v[40:43]
	v_mfma_f32_16x16x32_bf16 v[44:47], v[16:19], v[48:51], 0
	v_mfma_f32_16x16x32_bf16 v[48:51], v[24:27], v[48:51], 0
	v_mfma_f32_16x16x32_bf16 v[44:47], v[20:23], v[52:55], v[44:47]
	v_mfma_f32_16x16x32_bf16 v[48:51], v[28:31], v[52:55], v[48:51]
	v_mfma_f32_16x16x32_bf16 v[52:55], v[16:19], v[56:59], 0
	v_mfma_f32_16x16x32_bf16 v[56:59], v[24:27], v[56:59], 0
	v_mfma_f32_16x16x32_bf16 v[52:55], v[20:23], v[60:63], v[52:55]
	v_mfma_f32_16x16x32_bf16 v[56:59], v[28:31], v[60:63], v[56:59]
	s_barrier
	s_setprio 0
	s_add_i32 s70, s4, s97
	s_add_i32 s4, s70, 0x2000
	s_mov_b32 m0, s70
	s_add_u32 s74, s34, 0x80100
	ds_read_b128 v[60:63], v135 offset:16384
	ds_read_b128 v[100:103], v135 offset:17408
	ds_read_b128 v[104:107], v135 offset:18432
	ds_read_b128 v[108:111], v135 offset:19456
	ds_read_b128 v[112:115], v135 offset:20480
	ds_read_b128 v[116:119], v135 offset:21504
	ds_read_b128 v[120:123], v135 offset:22528
	ds_read_b128 v[124:127], v135 offset:23552
	s_addc_u32 s75, s35, 0
	global_load_lds_dwordx4 v131, s[80:81]
	s_mov_b32 m0, s4
	s_add_i32 s17, s17, s97
	s_add_i32 s21, s17, 0x2000
	global_load_lds_dwordx4 v133, s[80:81]
	s_mov_b32 m0, s17
	s_nop 0
	global_load_lds_dwordx4 v131, s[74:75]
	s_mov_b32 m0, s21
	s_nop 0
	global_load_lds_dwordx4 v133, s[74:75]
	s_mov_b32 m0, s13
	s_nop 0
	global_load_lds_dwordx4 v130, s[56:57]
	s_mov_b32 m0, s27
	s_nop 0
	global_load_lds_dwordx4 v132, s[56:57]
	s_waitcnt vmcnt(8)
	s_waitcnt lgkmcnt(0)
	s_setprio 1
	s_barrier
	v_mfma_f32_16x16x32_bf16 v[136:139], v[0:3], v[60:63], 0
	v_mfma_f32_16x16x32_bf16 v[144:147], v[0:3], v[104:107], 0
	v_mfma_f32_16x16x32_bf16 v[152:155], v[0:3], v[112:115], 0
	v_mfma_f32_16x16x32_bf16 v[0:3], v[0:3], v[120:123], 0
	v_mfma_f32_16x16x32_bf16 v[136:139], v[4:7], v[100:103], v[136:139]
	v_mfma_f32_16x16x32_bf16 v[144:147], v[4:7], v[108:111], v[144:147]
	v_mfma_f32_16x16x32_bf16 v[152:155], v[4:7], v[116:119], v[152:155]
	v_mfma_f32_16x16x32_bf16 v[0:3], v[4:7], v[124:127], v[0:3]
	v_mfma_f32_16x16x32_bf16 v[4:7], v[8:11], v[120:123], 0
	v_mfma_f32_16x16x32_bf16 v[140:143], v[8:11], v[60:63], 0
	v_mfma_f32_16x16x32_bf16 v[148:151], v[8:11], v[104:107], 0
	v_mfma_f32_16x16x32_bf16 v[156:159], v[8:11], v[112:115], 0
	v_mfma_f32_16x16x32_bf16 v[4:7], v[12:15], v[124:127], v[4:7]
	v_mfma_f32_16x16x32_bf16 v[140:143], v[12:15], v[100:103], v[140:143]
	v_mfma_f32_16x16x32_bf16 v[148:151], v[12:15], v[108:111], v[148:151]
	v_mfma_f32_16x16x32_bf16 v[156:159], v[12:15], v[116:119], v[156:159]
	v_mfma_f32_16x16x32_bf16 v[8:11], v[16:19], v[60:63], 0
	v_mfma_f32_16x16x32_bf16 v[12:15], v[24:27], v[60:63], 0
	v_mfma_f32_16x16x32_bf16 v[8:11], v[20:23], v[100:103], v[8:11]
	v_mfma_f32_16x16x32_bf16 v[12:15], v[28:31], v[100:103], v[12:15]
	v_mfma_f32_16x16x32_bf16 v[60:63], v[16:19], v[104:107], 0
	v_mfma_f32_16x16x32_bf16 v[100:103], v[24:27], v[104:107], 0
	v_mfma_f32_16x16x32_bf16 v[104:107], v[16:19], v[112:115], 0
	v_mfma_f32_16x16x32_bf16 v[16:19], v[16:19], v[120:123], 0
	v_mfma_f32_16x16x32_bf16 v[60:63], v[20:23], v[108:111], v[60:63]
	v_mfma_f32_16x16x32_bf16 v[100:103], v[28:31], v[108:111], v[100:103]
	v_mfma_f32_16x16x32_bf16 v[104:107], v[20:23], v[116:119], v[104:107]
	v_mfma_f32_16x16x32_bf16 v[108:111], v[24:27], v[112:115], 0
	v_mfma_f32_16x16x32_bf16 v[16:19], v[20:23], v[124:127], v[16:19]
	v_mfma_f32_16x16x32_bf16 v[20:23], v[24:27], v[120:123], 0
	v_mfma_f32_16x16x32_bf16 v[108:111], v[28:31], v[116:119], v[108:111]
	v_mfma_f32_16x16x32_bf16 v[20:23], v[28:31], v[124:127], v[20:23]
	s_barrier
	s_setprio 0
	s_add_i32 s71, 0, 0x18000
	s_add_i32 s69, 0, 0x1c000
	v_add_u32_e32 v196, s71, v134
	v_add_u32_e32 v198, s69, v134
	ds_read_b128 v[24:27], v196
	ds_read_b128 v[28:31], v196 offset:1024
	ds_read_b128 v[112:115], v196 offset:2048
	ds_read_b128 v[116:119], v196 offset:3072
	ds_read_b128 v[120:123], v198
	ds_read_b128 v[124:127], v198 offset:1024
	ds_read_b128 v[160:163], v198 offset:2048
	ds_read_b128 v[164:167], v198 offset:3072
	s_add_u32 s56, s30, 0x10100
	s_addc_u32 s57, s31, 0
	s_mov_b32 m0, s29
	ds_read_b128 v[168:171], v135 offset:32768
	ds_read_b128 v[172:175], v135 offset:33792
	ds_read_b128 v[176:179], v135 offset:34816
	ds_read_b128 v[180:183], v135 offset:35840
	ds_read_b128 v[184:187], v135 offset:36864
	ds_read_b128 v[188:191], v135 offset:37888
	ds_read_b128 v[192:195], v135 offset:38912
	ds_read_b128 v[200:203], v135 offset:39936
	s_nop 0
	global_load_lds_dwordx4 v130, s[56:57]
	s_mov_b32 m0, s47
	s_nop 0
	global_load_lds_dwordx4 v132, s[56:57]
	s_waitcnt vmcnt(8)
	s_waitcnt lgkmcnt(0)
	s_setprio 1
	s_barrier
	v_mfma_f32_16x16x32_bf16 v[64:67], v[24:27], v[168:171], v[64:67]
	v_mfma_f32_16x16x32_bf16 v[64:67], v[28:31], v[172:175], v[64:67]
	v_mfma_f32_16x16x32_bf16 v[68:71], v[112:115], v[168:171], v[68:71]
	v_mfma_f32_16x16x32_bf16 v[68:71], v[116:119], v[172:175], v[68:71]
	v_mfma_f32_16x16x32_bf16 v[72:75], v[24:27], v[176:179], v[72:75]
	v_mfma_f32_16x16x32_bf16 v[72:75], v[28:31], v[180:183], v[72:75]
	v_mfma_f32_16x16x32_bf16 v[76:79], v[112:115], v[176:179], v[76:79]
	v_mfma_f32_16x16x32_bf16 v[76:79], v[116:119], v[180:183], v[76:79]
	v_mfma_f32_16x16x32_bf16 v[80:83], v[24:27], v[184:187], v[80:83]
	v_mfma_f32_16x16x32_bf16 v[80:83], v[28:31], v[188:191], v[80:83]
	v_mfma_f32_16x16x32_bf16 v[84:87], v[112:115], v[184:187], v[84:87]
	v_mfma_f32_16x16x32_bf16 v[84:87], v[116:119], v[188:191], v[84:87]
	v_mfma_f32_16x16x32_bf16 v[88:91], v[24:27], v[192:195], v[88:91]
	v_mfma_f32_16x16x32_bf16 v[88:91], v[28:31], v[200:203], v[88:91]
	v_mfma_f32_16x16x32_bf16 v[92:95], v[112:115], v[192:195], v[92:95]
	v_mfma_f32_16x16x32_bf16 v[92:95], v[116:119], v[200:203], v[92:95]
	v_mfma_f32_16x16x32_bf16 v[96:99], v[120:123], v[168:171], v[96:99]
	v_mfma_f32_16x16x32_bf16 v[96:99], v[124:127], v[172:175], v[96:99]
	v_mfma_f32_16x16x32_bf16 v[32:35], v[160:163], v[168:171], v[32:35]
	v_mfma_f32_16x16x32_bf16 v[32:35], v[164:167], v[172:175], v[32:35]
	v_mfma_f32_16x16x32_bf16 v[36:39], v[120:123], v[176:179], v[36:39]
	v_mfma_f32_16x16x32_bf16 v[36:39], v[124:127], v[180:183], v[36:39]
	v_mfma_f32_16x16x32_bf16 v[40:43], v[160:163], v[176:179], v[40:43]
	v_mfma_f32_16x16x32_bf16 v[40:43], v[164:167], v[180:183], v[40:43]
	v_mfma_f32_16x16x32_bf16 v[44:47], v[120:123], v[184:187], v[44:47]
	v_mfma_f32_16x16x32_bf16 v[44:47], v[124:127], v[188:191], v[44:47]
	v_mfma_f32_16x16x32_bf16 v[48:51], v[160:163], v[184:187], v[48:51]
	v_mfma_f32_16x16x32_bf16 v[48:51], v[164:167], v[188:191], v[48:51]
	v_mfma_f32_16x16x32_bf16 v[52:55], v[120:123], v[192:195], v[52:55]
	v_mfma_f32_16x16x32_bf16 v[52:55], v[124:127], v[200:203], v[52:55]
	v_mfma_f32_16x16x32_bf16 v[56:59], v[160:163], v[192:195], v[56:59]
	v_mfma_f32_16x16x32_bf16 v[56:59], v[164:167], v[200:203], v[56:59]
	s_barrier
	s_setprio 0
	s_add_u32 s74, s34, 0x180
	s_addc_u32 s75, s35, 0
	s_add_i32 s71, s71, s97
	s_add_i32 s56, s71, 0x2000
	s_mov_b32 m0, s71
	s_add_u32 s34, s34, 0x80180
	ds_read_b128 v[168:171], v135 offset:49152
	ds_read_b128 v[172:175], v135 offset:50176
	ds_read_b128 v[176:179], v135 offset:51200
	ds_read_b128 v[180:183], v135 offset:52224
	ds_read_b128 v[184:187], v135 offset:53248
	ds_read_b128 v[188:191], v135 offset:54272
	ds_read_b128 v[192:195], v135 offset:55296
	ds_read_b128 v[200:203], v135 offset:56320
	s_addc_u32 s35, s35, 0
	global_load_lds_dwordx4 v131, s[74:75]
	s_mov_b32 m0, s56
	s_add_i32 s57, s69, s97
	s_add_i32 s69, s57, 0x2000
	global_load_lds_dwordx4 v133, s[74:75]
	s_mov_b32 m0, s57
	s_nop 0
	global_load_lds_dwordx4 v131, s[34:35]
	s_mov_b32 m0, s69
	s_nop 0
	global_load_lds_dwordx4 v133, s[34:35]
	s_mov_b32 m0, s48
	s_nop 0
	global_load_lds_dwordx4 v130, s[38:39]
	s_mov_b32 m0, s49
	s_nop 0
	global_load_lds_dwordx4 v132, s[38:39]
	s_waitcnt vmcnt(8)
	s_waitcnt lgkmcnt(0)
	s_setprio 1
	s_barrier
	v_mfma_f32_16x16x32_bf16 v[0:3], v[24:27], v[192:195], v[0:3]
	v_mfma_f32_16x16x32_bf16 v[0:3], v[28:31], v[200:203], v[0:3]
	v_mfma_f32_16x16x32_bf16 v[4:7], v[112:115], v[192:195], v[4:7]
	v_mfma_f32_16x16x32_bf16 v[4:7], v[116:119], v[200:203], v[4:7]
	v_mfma_f32_16x16x32_bf16 v[136:139], v[24:27], v[168:171], v[136:139]
	v_mfma_f32_16x16x32_bf16 v[136:139], v[28:31], v[172:175], v[136:139]
	v_mfma_f32_16x16x32_bf16 v[140:143], v[112:115], v[168:171], v[140:143]
	v_mfma_f32_16x16x32_bf16 v[140:143], v[116:119], v[172:175], v[140:143]
	v_mfma_f32_16x16x32_bf16 v[144:147], v[24:27], v[176:179], v[144:147]
	v_mfma_f32_16x16x32_bf16 v[144:147], v[28:31], v[180:183], v[144:147]
	v_mfma_f32_16x16x32_bf16 v[148:151], v[112:115], v[176:179], v[148:151]
	v_mfma_f32_16x16x32_bf16 v[148:151], v[116:119], v[180:183], v[148:151]
	v_mfma_f32_16x16x32_bf16 v[152:155], v[24:27], v[184:187], v[152:155]
	v_mfma_f32_16x16x32_bf16 v[152:155], v[28:31], v[188:191], v[152:155]
	v_mfma_f32_16x16x32_bf16 v[156:159], v[112:115], v[184:187], v[156:159]
	v_mfma_f32_16x16x32_bf16 v[156:159], v[116:119], v[188:191], v[156:159]
	v_mfma_f32_16x16x32_bf16 v[8:11], v[120:123], v[168:171], v[8:11]
	v_mfma_f32_16x16x32_bf16 v[12:15], v[160:163], v[168:171], v[12:15]
	v_mfma_f32_16x16x32_bf16 v[24:27], v[120:123], v[176:179], v[60:63]
	v_mfma_f32_16x16x32_bf16 v[28:31], v[160:163], v[176:179], v[100:103]
	v_mfma_f32_16x16x32_bf16 v[60:63], v[120:123], v[184:187], v[104:107]
	v_mfma_f32_16x16x32_bf16 v[100:103], v[160:163], v[184:187], v[108:111]
	v_mfma_f32_16x16x32_bf16 v[16:19], v[120:123], v[192:195], v[16:19]
	v_mfma_f32_16x16x32_bf16 v[20:23], v[160:163], v[192:195], v[20:23]
	v_mfma_f32_16x16x32_bf16 v[8:11], v[124:127], v[172:175], v[8:11]
	v_mfma_f32_16x16x32_bf16 v[12:15], v[164:167], v[172:175], v[12:15]
	v_mfma_f32_16x16x32_bf16 v[24:27], v[124:127], v[180:183], v[24:27]
	v_mfma_f32_16x16x32_bf16 v[28:31], v[164:167], v[180:183], v[28:31]
	v_mfma_f32_16x16x32_bf16 v[60:63], v[124:127], v[188:191], v[60:63]
	v_mfma_f32_16x16x32_bf16 v[100:103], v[164:167], v[188:191], v[100:103]
	v_mfma_f32_16x16x32_bf16 v[16:19], v[124:127], v[200:203], v[16:19]
	v_mfma_f32_16x16x32_bf16 v[20:23], v[164:167], v[200:203], v[20:23]
	s_barrier
	s_setprio 0
	ds_read_b128 v[104:107], v128
	ds_read_b128 v[108:111], v128 offset:1024
	ds_read_b128 v[112:115], v128 offset:2048
	ds_read_b128 v[116:119], v128 offset:3072
	ds_read_b128 v[120:123], v129
	ds_read_b128 v[124:127], v129 offset:1024
	ds_read_b128 v[160:163], v129 offset:2048
	ds_read_b128 v[164:167], v129 offset:3072
	s_add_u32 s34, s36, 0x80
	s_addc_u32 s35, s37, 0
	s_add_u32 s30, s30, 0x10180
	s_addc_u32 s31, s31, 0
	s_mov_b32 m0, s5
	ds_read_b128 v[168:171], v135
	ds_read_b128 v[172:175], v135 offset:1024
	ds_read_b128 v[176:179], v135 offset:2048
	ds_read_b128 v[180:183], v135 offset:3072
	ds_read_b128 v[184:187], v135 offset:4096
	ds_read_b128 v[188:191], v135 offset:5120
	ds_read_b128 v[192:195], v135 offset:6144
	ds_read_b128 v[200:203], v135 offset:7168
	s_nop 0
	global_load_lds_dwordx4 v130, s[30:31]
	s_mov_b32 m0, s15
	s_nop 0
	global_load_lds_dwordx4 v132, s[30:31]
	s_waitcnt vmcnt(8)
	s_waitcnt lgkmcnt(0)
	s_setprio 1
	s_barrier
	v_mfma_f32_16x16x32_bf16 v[64:67], v[104:107], v[168:171], v[64:67]
	v_mfma_f32_16x16x32_bf16 v[64:67], v[108:111], v[172:175], v[64:67]
	v_mfma_f32_16x16x32_bf16 v[68:71], v[112:115], v[168:171], v[68:71]
	v_mfma_f32_16x16x32_bf16 v[68:71], v[116:119], v[172:175], v[68:71]
	v_mfma_f32_16x16x32_bf16 v[72:75], v[104:107], v[176:179], v[72:75]
	v_mfma_f32_16x16x32_bf16 v[72:75], v[108:111], v[180:183], v[72:75]
	v_mfma_f32_16x16x32_bf16 v[76:79], v[112:115], v[176:179], v[76:79]
	v_mfma_f32_16x16x32_bf16 v[76:79], v[116:119], v[180:183], v[76:79]
	v_mfma_f32_16x16x32_bf16 v[80:83], v[104:107], v[184:187], v[80:83]
	v_mfma_f32_16x16x32_bf16 v[80:83], v[108:111], v[188:191], v[80:83]
	v_mfma_f32_16x16x32_bf16 v[84:87], v[112:115], v[184:187], v[84:87]
	v_mfma_f32_16x16x32_bf16 v[84:87], v[116:119], v[188:191], v[84:87]
	v_mfma_f32_16x16x32_bf16 v[88:91], v[104:107], v[192:195], v[88:91]
	v_mfma_f32_16x16x32_bf16 v[88:91], v[108:111], v[200:203], v[88:91]
	v_mfma_f32_16x16x32_bf16 v[92:95], v[112:115], v[192:195], v[92:95]
	v_mfma_f32_16x16x32_bf16 v[92:95], v[116:119], v[200:203], v[92:95]
	v_mfma_f32_16x16x32_bf16 v[32:35], v[160:163], v[168:171], v[32:35]
	v_mfma_f32_16x16x32_bf16 v[96:99], v[120:123], v[168:171], v[96:99]
	v_mfma_f32_16x16x32_bf16 v[168:171], v[164:167], v[172:175], v[32:35]
	v_mfma_f32_16x16x32_bf16 v[32:35], v[120:123], v[176:179], v[36:39]
	v_mfma_f32_16x16x32_bf16 v[36:39], v[124:127], v[180:183], v[32:35]
	v_mfma_f32_16x16x32_bf16 v[32:35], v[160:163], v[176:179], v[40:43]
	v_mfma_f32_16x16x32_bf16 v[204:207], v[124:127], v[172:175], v[96:99]
	v_mfma_f32_16x16x32_bf16 v[172:175], v[164:167], v[180:183], v[32:35]
	v_mfma_f32_16x16x32_bf16 v[32:35], v[120:123], v[184:187], v[44:47]
	v_mfma_f32_16x16x32_bf16 v[44:47], v[124:127], v[188:191], v[32:35]
	v_mfma_f32_16x16x32_bf16 v[32:35], v[160:163], v[184:187], v[48:51]
	v_mfma_f32_16x16x32_bf16 v[48:51], v[164:167], v[188:191], v[32:35]
	v_mfma_f32_16x16x32_bf16 v[32:35], v[120:123], v[192:195], v[52:55]
	v_mfma_f32_16x16x32_bf16 v[52:55], v[124:127], v[200:203], v[32:35]
	v_mfma_f32_16x16x32_bf16 v[32:35], v[160:163], v[192:195], v[56:59]
	v_mfma_f32_16x16x32_bf16 v[56:59], v[164:167], v[200:203], v[32:35]
	s_barrier
	s_setprio 0
	s_mov_b32 m0, s70
	s_mov_b64 s[30:31], s[22:23]
	s_nop 2
	ds_read_b128 v[32:35], v135 offset:16384
	ds_read_b128 v[40:43], v135 offset:17408
	ds_read_b128 v[96:99], v135 offset:18432
	ds_read_b128 v[176:179], v135 offset:19456
	ds_read_b128 v[180:183], v135 offset:20480
	ds_read_b128 v[184:187], v135 offset:21504
	ds_read_b128 v[188:191], v135 offset:22528
	ds_read_b128 v[192:195], v135 offset:23552
	s_nop 0
	global_load_lds_dwordx4 v131, s[30:31]
	s_mov_b32 m0, s4
	s_add_u32 s4, s22, 0x80000
	s_addc_u32 s5, s23, 0
	global_load_lds_dwordx4 v133, s[30:31]
	s_mov_b32 m0, s17
	s_nop 0
	global_load_lds_dwordx4 v131, s[4:5]
	s_mov_b32 m0, s21
	s_nop 0
	global_load_lds_dwordx4 v133, s[4:5]
	s_mov_b64 s[4:5], s[36:37]
	s_mov_b32 m0, s13
	s_nop 0
	global_load_lds_dwordx4 v130, s[4:5]
	s_mov_b32 m0, s27
	s_nop 0
	global_load_lds_dwordx4 v132, s[4:5]
	s_waitcnt vmcnt(8)
	s_waitcnt lgkmcnt(0)
	s_setprio 1
	s_barrier
	v_mfma_f32_16x16x32_bf16 v[0:3], v[104:107], v[188:191], v[0:3]
	v_mfma_f32_16x16x32_bf16 v[0:3], v[108:111], v[192:195], v[0:3]
	v_mfma_f32_16x16x32_bf16 v[4:7], v[112:115], v[188:191], v[4:7]
	v_mfma_f32_16x16x32_bf16 v[4:7], v[116:119], v[192:195], v[4:7]
	v_mfma_f32_16x16x32_bf16 v[136:139], v[104:107], v[32:35], v[136:139]
	v_mfma_f32_16x16x32_bf16 v[136:139], v[108:111], v[40:43], v[136:139]
	v_mfma_f32_16x16x32_bf16 v[140:143], v[112:115], v[32:35], v[140:143]
	v_mfma_f32_16x16x32_bf16 v[140:143], v[116:119], v[40:43], v[140:143]
	v_mfma_f32_16x16x32_bf16 v[144:147], v[104:107], v[96:99], v[144:147]
	v_mfma_f32_16x16x32_bf16 v[144:147], v[108:111], v[176:179], v[144:147]
	v_mfma_f32_16x16x32_bf16 v[148:151], v[112:115], v[96:99], v[148:151]
	v_mfma_f32_16x16x32_bf16 v[148:151], v[116:119], v[176:179], v[148:151]
	v_mfma_f32_16x16x32_bf16 v[152:155], v[104:107], v[180:183], v[152:155]
	v_mfma_f32_16x16x32_bf16 v[152:155], v[108:111], v[184:187], v[152:155]
	v_mfma_f32_16x16x32_bf16 v[156:159], v[112:115], v[180:183], v[156:159]
	v_mfma_f32_16x16x32_bf16 v[156:159], v[116:119], v[184:187], v[156:159]
	v_mfma_f32_16x16x32_bf16 v[12:15], v[160:163], v[32:35], v[12:15]
	v_mfma_f32_16x16x32_bf16 v[200:203], v[164:167], v[40:43], v[12:15]
	v_mfma_f32_16x16x32_bf16 v[12:15], v[120:123], v[96:99], v[24:27]
	v_mfma_f32_16x16x32_bf16 v[24:27], v[124:127], v[176:179], v[12:15]
	v_mfma_f32_16x16x32_bf16 v[12:15], v[160:163], v[96:99], v[28:31]
	v_mfma_f32_16x16x32_bf16 v[176:179], v[164:167], v[176:179], v[12:15]
	v_mfma_f32_16x16x32_bf16 v[12:15], v[120:123], v[180:183], v[60:63]
	v_mfma_f32_16x16x32_bf16 v[208:211], v[124:127], v[184:187], v[12:15]
	v_mfma_f32_16x16x32_bf16 v[12:15], v[160:163], v[180:183], v[100:103]
	v_mfma_f32_16x16x32_bf16 v[8:11], v[120:123], v[32:35], v[8:11]
	v_mfma_f32_16x16x32_bf16 v[180:183], v[164:167], v[184:187], v[12:15]
	v_mfma_f32_16x16x32_bf16 v[12:15], v[120:123], v[188:191], v[16:19]
	v_mfma_f32_16x16x32_bf16 v[8:11], v[124:127], v[40:43], v[8:11]
	v_mfma_f32_16x16x32_bf16 v[184:187], v[124:127], v[192:195], v[12:15]
	v_mfma_f32_16x16x32_bf16 v[12:15], v[160:163], v[188:191], v[20:23]
	v_mfma_f32_16x16x32_bf16 v[160:163], v[164:167], v[192:195], v[12:15]
	s_barrier
	s_setprio 0
	s_nop 4
	ds_read_b128 v[12:15], v196
	ds_read_b128 v[16:19], v196 offset:1024
	ds_read_b128 v[164:167], v196 offset:2048
	ds_read_b128 v[188:191], v196 offset:3072
	ds_read_b128 v[192:195], v198
	ds_read_b128 v[220:223], v198 offset:1024
	ds_read_b128 v[224:227], v198 offset:2048
	ds_read_b128 v[228:231], v198 offset:3072
	s_add_u32 s4, s36, 0x10000
	s_addc_u32 s5, s37, 0
	s_mov_b32 m0, s29
	ds_read_b128 v[20:23], v135 offset:32768
	ds_read_b128 v[28:31], v135 offset:33792
	ds_read_b128 v[60:63], v135 offset:34816
	ds_read_b128 v[100:103], v135 offset:35840
	ds_read_b128 v[232:235], v135 offset:36864
	ds_read_b128 v[236:239], v135 offset:37888
	ds_read_b128 v[240:243], v135 offset:38912
	ds_read_b128 v[244:247], v135 offset:39936
	s_nop 0
	global_load_lds_dwordx4 v130, s[4:5]
	s_mov_b32 m0, s47
	s_nop 0
	global_load_lds_dwordx4 v132, s[4:5]
	s_waitcnt vmcnt(8)
	s_waitcnt lgkmcnt(0)
	s_setprio 1
	s_barrier
	v_mfma_f32_16x16x32_bf16 v[32:35], v[12:15], v[20:23], v[64:67]
	v_mfma_f32_16x16x32_bf16 v[120:123], v[16:19], v[28:31], v[32:35]
	v_mfma_f32_16x16x32_bf16 v[32:35], v[164:167], v[20:23], v[68:71]
	v_mfma_f32_16x16x32_bf16 v[112:115], v[188:191], v[28:31], v[32:35]
	v_mfma_f32_16x16x32_bf16 v[32:35], v[12:15], v[60:63], v[72:75]
	v_mfma_f32_16x16x32_bf16 v[104:107], v[16:19], v[100:103], v[32:35]
	v_mfma_f32_16x16x32_bf16 v[32:35], v[164:167], v[60:63], v[76:79]
	v_mfma_f32_16x16x32_bf16 v[96:99], v[188:191], v[100:103], v[32:35]
	v_mfma_f32_16x16x32_bf16 v[32:35], v[12:15], v[232:235], v[80:83]
	v_mfma_f32_16x16x32_bf16 v[72:75], v[16:19], v[236:239], v[32:35]
	v_mfma_f32_16x16x32_bf16 v[32:35], v[164:167], v[232:235], v[84:87]
	v_mfma_f32_16x16x32_bf16 v[64:67], v[188:191], v[236:239], v[32:35]
	v_mfma_f32_16x16x32_bf16 v[32:35], v[12:15], v[240:243], v[88:91]
	v_mfma_f32_16x16x32_bf16 v[40:43], v[16:19], v[244:247], v[32:35]
	v_mfma_f32_16x16x32_bf16 v[32:35], v[164:167], v[240:243], v[92:95]
	v_mfma_f32_16x16x32_bf16 v[32:35], v[188:191], v[244:247], v[32:35]
	v_mfma_f32_16x16x32_bf16 v[68:71], v[192:195], v[20:23], v[204:207]
	v_mfma_f32_16x16x32_bf16 v[20:23], v[224:227], v[20:23], v[168:171]
	v_mfma_f32_16x16x32_bf16 v[116:119], v[228:231], v[28:31], v[20:23]
	v_mfma_f32_16x16x32_bf16 v[20:23], v[192:195], v[60:63], v[36:39]
	v_mfma_f32_16x16x32_bf16 v[108:111], v[220:223], v[100:103], v[20:23]
	v_mfma_f32_16x16x32_bf16 v[20:23], v[224:227], v[60:63], v[172:175]
	v_mfma_f32_16x16x32_bf16 v[100:103], v[228:231], v[100:103], v[20:23]
	v_mfma_f32_16x16x32_bf16 v[20:23], v[192:195], v[232:235], v[44:47]
	v_mfma_f32_16x16x32_bf16 v[76:79], v[220:223], v[236:239], v[20:23]
	v_mfma_f32_16x16x32_bf16 v[20:23], v[224:227], v[232:235], v[48:51]
	v_mfma_f32_16x16x32_bf16 v[124:127], v[220:223], v[28:31], v[68:71]
	v_mfma_f32_16x16x32_bf16 v[68:71], v[228:231], v[236:239], v[20:23]
	v_mfma_f32_16x16x32_bf16 v[20:23], v[192:195], v[240:243], v[52:55]
	v_mfma_f32_16x16x32_bf16 v[44:47], v[220:223], v[244:247], v[20:23]
	v_mfma_f32_16x16x32_bf16 v[20:23], v[224:227], v[240:243], v[56:59]
	v_mfma_f32_16x16x32_bf16 v[36:39], v[228:231], v[244:247], v[20:23]
	s_barrier
	s_setprio 0
	s_add_u32 s4, s22, 0x80
	s_mov_b32 m0, s71
	s_addc_u32 s5, s23, 0
	ds_read_b128 v[48:51], v135 offset:49152
	ds_read_b128 v[56:59], v135 offset:50176
	ds_read_b128 v[168:171], v135 offset:51200
	ds_read_b128 v[172:175], v135 offset:52224
	ds_read_b128 v[204:207], v135 offset:53248
	ds_read_b128 v[232:235], v135 offset:54272
	ds_read_b128 v[236:239], v135 offset:55296
	ds_read_b128 v[240:243], v135 offset:56320
	s_nop 0
	global_load_lds_dwordx4 v131, s[4:5]
	s_mov_b32 m0, s56
	s_nop 0
	global_load_lds_dwordx4 v133, s[4:5]
	s_add_u32 s4, s22, 0x80080
	s_addc_u32 s5, s23, 0
	s_mov_b32 m0, s57
	s_nop 0
	global_load_lds_dwordx4 v131, s[4:5]
	s_mov_b32 m0, s69
	s_nop 0
	global_load_lds_dwordx4 v133, s[4:5]
	s_mov_b32 m0, s48
	s_nop 0
	global_load_lds_dwordx4 v130, s[34:35]
	s_mov_b32 m0, s49
	s_nop 0
	global_load_lds_dwordx4 v132, s[34:35]
	s_waitcnt vmcnt(8)
	s_waitcnt lgkmcnt(0)
	s_setprio 1
	s_barrier
	v_mfma_f32_16x16x32_bf16 v[20:23], v[12:15], v[48:51], v[136:139]
	v_mfma_f32_16x16x32_bf16 v[92:95], v[16:19], v[56:59], v[20:23]
	v_mfma_f32_16x16x32_bf16 v[20:23], v[164:167], v[48:51], v[140:143]
	v_mfma_f32_16x16x32_bf16 v[84:87], v[188:191], v[56:59], v[20:23]
	v_mfma_f32_16x16x32_bf16 v[20:23], v[12:15], v[168:171], v[144:147]
	v_mfma_f32_16x16x32_bf16 v[60:63], v[16:19], v[172:175], v[20:23]
	v_mfma_f32_16x16x32_bf16 v[20:23], v[164:167], v[168:171], v[148:151]
	v_mfma_f32_16x16x32_bf16 v[52:55], v[188:191], v[172:175], v[20:23]
	v_mfma_f32_16x16x32_bf16 v[20:23], v[12:15], v[204:207], v[152:155]
	v_mfma_f32_16x16x32_bf16 v[0:3], v[12:15], v[236:239], v[0:3]
	v_mfma_f32_16x16x32_bf16 v[28:31], v[16:19], v[232:235], v[20:23]
	v_mfma_f32_16x16x32_bf16 v[20:23], v[164:167], v[204:207], v[156:159]
	v_mfma_f32_16x16x32_bf16 v[12:15], v[16:19], v[240:243], v[0:3]
	v_mfma_f32_16x16x32_bf16 v[0:3], v[164:167], v[236:239], v[4:7]
	v_mfma_f32_16x16x32_bf16 v[20:23], v[188:191], v[232:235], v[20:23]
	v_mfma_f32_16x16x32_bf16 v[4:7], v[188:191], v[240:243], v[0:3]
	v_mfma_f32_16x16x32_bf16 v[0:3], v[192:195], v[48:51], v[8:11]
	v_mfma_f32_16x16x32_bf16 v[88:91], v[220:223], v[56:59], v[0:3]
	v_mfma_f32_16x16x32_bf16 v[0:3], v[224:227], v[48:51], v[200:203]
	v_mfma_f32_16x16x32_bf16 v[80:83], v[228:231], v[56:59], v[0:3]
	v_mfma_f32_16x16x32_bf16 v[0:3], v[192:195], v[168:171], v[24:27]
	v_mfma_f32_16x16x32_bf16 v[56:59], v[220:223], v[172:175], v[0:3]
	v_mfma_f32_16x16x32_bf16 v[0:3], v[224:227], v[168:171], v[176:179]
	v_mfma_f32_16x16x32_bf16 v[48:51], v[228:231], v[172:175], v[0:3]
	v_mfma_f32_16x16x32_bf16 v[0:3], v[192:195], v[204:207], v[208:211]
	v_mfma_f32_16x16x32_bf16 v[24:27], v[220:223], v[232:235], v[0:3]
	v_mfma_f32_16x16x32_bf16 v[0:3], v[224:227], v[204:207], v[180:183]
	v_mfma_f32_16x16x32_bf16 v[16:19], v[228:231], v[232:235], v[0:3]
	v_mfma_f32_16x16x32_bf16 v[0:3], v[192:195], v[236:239], v[184:187]
	v_mfma_f32_16x16x32_bf16 v[8:11], v[220:223], v[240:243], v[0:3]
	v_mfma_f32_16x16x32_bf16 v[0:3], v[224:227], v[236:239], v[160:163]
	v_mfma_f32_16x16x32_bf16 v[0:3], v[228:231], v[240:243], v[0:3]
	s_barrier
	s_setprio 0
	s_andn2_b64 vcc, exec, s[60:61]
	s_cbranch_vccnz .LBB0_300
	s_barrier

.LBB0_313:
	s_ashr_i32 s15, s14, 31
	s_lshl_b64 s[4:5], s[14:15], 17
	s_add_u32 s20, s2, s4
	s_addc_u32 s21, s19, s5
	s_and_b64 s[4:5], s[16:17], exec
	s_cselect_b32 s39, s21, s31
	s_cselect_b32 s38, s20, s30
	s_ashr_i32 s11, s10, 31
	s_lshl_b64 s[4:5], s[10:11], 9
	s_add_u32 s11, s44, s4
	s_addc_u32 s15, s46, s5
	s_ashr_i32 s13, s12, 31
	s_lshl_b64 s[4:5], s[12:13], 20
	s_add_u32 s22, s11, s4
	s_addc_u32 s23, s15, s5
	s_and_b64 s[4:5], s[16:17], exec
	s_cselect_b32 s35, s23, s37
	s_cselect_b32 s34, s22, s36
	s_add_u32 s56, s30, 0x100
	s_addc_u32 s57, s31, 0
	s_add_u32 s82, s36, 0x100
	s_addc_u32 s83, s37, 0
	s_add_u32 s80, s30, 0x180
	s_addc_u32 s81, s31, 0
	s_add_i32 s4, 0, 0x10000
	s_add_i32 s13, 0, 0x14000
	v_add_u32_e32 v128, s4, v134
	v_add_u32_e32 v129, s13, v134
	ds_read_b128 v[0:3], v128
	ds_read_b128 v[4:7], v128 offset:1024
	ds_read_b128 v[8:11], v128 offset:2048
	ds_read_b128 v[12:15], v128 offset:3072
	ds_read_b128 v[16:19], v129
	ds_read_b128 v[20:23], v129 offset:1024
	ds_read_b128 v[24:27], v129 offset:2048
	ds_read_b128 v[28:31], v129 offset:3072
	s_add_u32 s70, s30, 0x10080
	s_addc_u32 s71, s31, 0
	s_add_i32 s5, s25, 0xc000
	s_mov_b32 m0, s5
	s_add_i32 s11, s25, 0xe000
	ds_read_b128 v[32:35], v135
	ds_read_b128 v[36:39], v135 offset:1024
	ds_read_b128 v[40:43], v135 offset:2048
	ds_read_b128 v[44:47], v135 offset:3072
	ds_read_b128 v[48:51], v135 offset:4096
	ds_read_b128 v[52:55], v135 offset:5120
	ds_read_b128 v[56:59], v135 offset:6144
	ds_read_b128 v[60:63], v135 offset:7168
	s_nop 0
	global_load_lds_dwordx4 v133, s[70:71]
	s_mov_b32 m0, s11
	s_nop 0
	global_load_lds_dwordx4 v131, s[70:71]
	s_waitcnt vmcnt(8)
	s_waitcnt lgkmcnt(0)
	s_setprio 1
	s_barrier
	v_mfma_f32_16x16x32_bf16 v[64:67], v[0:3], v[32:35], 0
	v_mfma_f32_16x16x32_bf16 v[68:71], v[8:11], v[32:35], 0
	v_mfma_f32_16x16x32_bf16 v[72:75], v[0:3], v[40:43], 0
	v_mfma_f32_16x16x32_bf16 v[76:79], v[8:11], v[40:43], 0
	v_mfma_f32_16x16x32_bf16 v[80:83], v[0:3], v[48:51], 0
	v_mfma_f32_16x16x32_bf16 v[84:87], v[8:11], v[48:51], 0
	v_mfma_f32_16x16x32_bf16 v[88:91], v[0:3], v[56:59], 0
	v_mfma_f32_16x16x32_bf16 v[92:95], v[8:11], v[56:59], 0
	v_mfma_f32_16x16x32_bf16 v[64:67], v[4:7], v[36:39], v[64:67]
	v_mfma_f32_16x16x32_bf16 v[68:71], v[12:15], v[36:39], v[68:71]
	v_mfma_f32_16x16x32_bf16 v[72:75], v[4:7], v[44:47], v[72:75]
	v_mfma_f32_16x16x32_bf16 v[76:79], v[12:15], v[44:47], v[76:79]
	v_mfma_f32_16x16x32_bf16 v[80:83], v[4:7], v[52:55], v[80:83]
	v_mfma_f32_16x16x32_bf16 v[84:87], v[12:15], v[52:55], v[84:87]
	v_mfma_f32_16x16x32_bf16 v[88:91], v[4:7], v[60:63], v[88:91]
	v_mfma_f32_16x16x32_bf16 v[92:95], v[12:15], v[60:63], v[92:95]
	v_mfma_f32_16x16x32_bf16 v[96:99], v[16:19], v[32:35], 0
	v_mfma_f32_16x16x32_bf16 v[32:35], v[24:27], v[32:35], 0
	v_mfma_f32_16x16x32_bf16 v[96:99], v[20:23], v[36:39], v[96:99]
	v_mfma_f32_16x16x32_bf16 v[32:35], v[28:31], v[36:39], v[32:35]
	v_mfma_f32_16x16x32_bf16 v[36:39], v[16:19], v[40:43], 0
	v_mfma_f32_16x16x32_bf16 v[40:43], v[24:27], v[40:43], 0
	v_mfma_f32_16x16x32_bf16 v[36:39], v[20:23], v[44:47], v[36:39]
	v_mfma_f32_16x16x32_bf16 v[40:43], v[28:31], v[44:47], v[40:43]
	v_mfma_f32_16x16x32_bf16 v[44:47], v[16:19], v[48:51], 0
	v_mfma_f32_16x16x32_bf16 v[48:51], v[24:27], v[48:51], 0
	v_mfma_f32_16x16x32_bf16 v[44:47], v[20:23], v[52:55], v[44:47]
	v_mfma_f32_16x16x32_bf16 v[48:51], v[28:31], v[52:55], v[48:51]
	v_mfma_f32_16x16x32_bf16 v[52:55], v[16:19], v[56:59], 0
	v_mfma_f32_16x16x32_bf16 v[56:59], v[24:27], v[56:59], 0
	v_mfma_f32_16x16x32_bf16 v[52:55], v[20:23], v[60:63], v[52:55]
	v_mfma_f32_16x16x32_bf16 v[56:59], v[28:31], v[60:63], v[56:59]
	s_barrier
	s_setprio 0
	s_add_i32 s70, s4, s97
	s_add_i32 s4, s70, 0x2000
	s_mov_b32 m0, s70
	s_add_u32 s74, s36, 0x80100
	ds_read_b128 v[60:63], v135 offset:16384
	ds_read_b128 v[100:103], v135 offset:17408
	ds_read_b128 v[104:107], v135 offset:18432
	ds_read_b128 v[108:111], v135 offset:19456
	ds_read_b128 v[112:115], v135 offset:20480
	ds_read_b128 v[116:119], v135 offset:21504
	ds_read_b128 v[120:123], v135 offset:22528
	ds_read_b128 v[124:127], v135 offset:23552
	s_addc_u32 s75, s37, 0
	global_load_lds_dwordx4 v132, s[82:83]
	s_mov_b32 m0, s4
	s_add_i32 s13, s13, s97
	s_add_i32 s15, s13, 0x2000
	global_load_lds_dwordx4 v130, s[82:83]
	s_mov_b32 m0, s13
	s_nop 0
	global_load_lds_dwordx4 v132, s[74:75]
	s_mov_b32 m0, s15
	s_nop 0
	global_load_lds_dwordx4 v130, s[74:75]
	s_mov_b32 m0, s25
	s_nop 0
	global_load_lds_dwordx4 v133, s[56:57]
	s_mov_b32 m0, s27
	s_nop 0
	global_load_lds_dwordx4 v131, s[56:57]
	s_waitcnt vmcnt(8)
	s_waitcnt lgkmcnt(0)
	s_setprio 1
	s_barrier
	v_mfma_f32_16x16x32_bf16 v[136:139], v[0:3], v[60:63], 0
	v_mfma_f32_16x16x32_bf16 v[144:147], v[0:3], v[104:107], 0
	v_mfma_f32_16x16x32_bf16 v[152:155], v[0:3], v[112:115], 0
	v_mfma_f32_16x16x32_bf16 v[0:3], v[0:3], v[120:123], 0
	v_mfma_f32_16x16x32_bf16 v[136:139], v[4:7], v[100:103], v[136:139]
	v_mfma_f32_16x16x32_bf16 v[144:147], v[4:7], v[108:111], v[144:147]
	v_mfma_f32_16x16x32_bf16 v[152:155], v[4:7], v[116:119], v[152:155]
	v_mfma_f32_16x16x32_bf16 v[0:3], v[4:7], v[124:127], v[0:3]
	v_mfma_f32_16x16x32_bf16 v[4:7], v[8:11], v[120:123], 0
	v_mfma_f32_16x16x32_bf16 v[140:143], v[8:11], v[60:63], 0
	v_mfma_f32_16x16x32_bf16 v[148:151], v[8:11], v[104:107], 0
	v_mfma_f32_16x16x32_bf16 v[156:159], v[8:11], v[112:115], 0
	v_mfma_f32_16x16x32_bf16 v[4:7], v[12:15], v[124:127], v[4:7]
	v_mfma_f32_16x16x32_bf16 v[140:143], v[12:15], v[100:103], v[140:143]
	v_mfma_f32_16x16x32_bf16 v[148:151], v[12:15], v[108:111], v[148:151]
	v_mfma_f32_16x16x32_bf16 v[156:159], v[12:15], v[116:119], v[156:159]
	v_mfma_f32_16x16x32_bf16 v[8:11], v[16:19], v[60:63], 0
	v_mfma_f32_16x16x32_bf16 v[12:15], v[24:27], v[60:63], 0
	v_mfma_f32_16x16x32_bf16 v[8:11], v[20:23], v[100:103], v[8:11]
	v_mfma_f32_16x16x32_bf16 v[12:15], v[28:31], v[100:103], v[12:15]
	v_mfma_f32_16x16x32_bf16 v[60:63], v[16:19], v[104:107], 0
	v_mfma_f32_16x16x32_bf16 v[100:103], v[24:27], v[104:107], 0
	v_mfma_f32_16x16x32_bf16 v[104:107], v[16:19], v[112:115], 0
	v_mfma_f32_16x16x32_bf16 v[16:19], v[16:19], v[120:123], 0
	v_mfma_f32_16x16x32_bf16 v[60:63], v[20:23], v[108:111], v[60:63]
	v_mfma_f32_16x16x32_bf16 v[100:103], v[28:31], v[108:111], v[100:103]
	v_mfma_f32_16x16x32_bf16 v[104:107], v[20:23], v[116:119], v[104:107]
	v_mfma_f32_16x16x32_bf16 v[108:111], v[24:27], v[112:115], 0
	v_mfma_f32_16x16x32_bf16 v[16:19], v[20:23], v[124:127], v[16:19]
	v_mfma_f32_16x16x32_bf16 v[20:23], v[24:27], v[120:123], 0
	v_mfma_f32_16x16x32_bf16 v[108:111], v[28:31], v[116:119], v[108:111]
	v_mfma_f32_16x16x32_bf16 v[20:23], v[28:31], v[124:127], v[20:23]
	s_barrier
	s_setprio 0
	s_add_i32 s71, 0, 0x18000
	s_add_i32 s69, 0, 0x1c000
	v_add_u32_e32 v196, s71, v134
	v_add_u32_e32 v198, s69, v134
	ds_read_b128 v[24:27], v196
	ds_read_b128 v[28:31], v196 offset:1024
	ds_read_b128 v[112:115], v196 offset:2048
	ds_read_b128 v[116:119], v196 offset:3072
	ds_read_b128 v[120:123], v198
	ds_read_b128 v[124:127], v198 offset:1024
	ds_read_b128 v[160:163], v198 offset:2048
	ds_read_b128 v[164:167], v198 offset:3072
	s_add_u32 s56, s30, 0x10100
	s_addc_u32 s57, s31, 0
	s_mov_b32 m0, s29
	ds_read_b128 v[168:171], v135 offset:32768
	ds_read_b128 v[172:175], v135 offset:33792
	ds_read_b128 v[176:179], v135 offset:34816
	ds_read_b128 v[180:183], v135 offset:35840
	ds_read_b128 v[184:187], v135 offset:36864
	ds_read_b128 v[188:191], v135 offset:37888
	ds_read_b128 v[192:195], v135 offset:38912
	ds_read_b128 v[200:203], v135 offset:39936
	s_nop 0
	global_load_lds_dwordx4 v133, s[56:57]
	s_mov_b32 m0, s47
	s_nop 0
	global_load_lds_dwordx4 v131, s[56:57]
	s_waitcnt vmcnt(8)
	s_waitcnt lgkmcnt(0)
	s_setprio 1
	s_barrier
	v_mfma_f32_16x16x32_bf16 v[64:67], v[24:27], v[168:171], v[64:67]
	v_mfma_f32_16x16x32_bf16 v[64:67], v[28:31], v[172:175], v[64:67]
	v_mfma_f32_16x16x32_bf16 v[68:71], v[112:115], v[168:171], v[68:71]
	v_mfma_f32_16x16x32_bf16 v[68:71], v[116:119], v[172:175], v[68:71]
	v_mfma_f32_16x16x32_bf16 v[72:75], v[24:27], v[176:179], v[72:75]
	v_mfma_f32_16x16x32_bf16 v[72:75], v[28:31], v[180:183], v[72:75]
	v_mfma_f32_16x16x32_bf16 v[76:79], v[112:115], v[176:179], v[76:79]
	v_mfma_f32_16x16x32_bf16 v[76:79], v[116:119], v[180:183], v[76:79]
	v_mfma_f32_16x16x32_bf16 v[80:83], v[24:27], v[184:187], v[80:83]
	v_mfma_f32_16x16x32_bf16 v[80:83], v[28:31], v[188:191], v[80:83]
	v_mfma_f32_16x16x32_bf16 v[84:87], v[112:115], v[184:187], v[84:87]
	v_mfma_f32_16x16x32_bf16 v[84:87], v[116:119], v[188:191], v[84:87]
	v_mfma_f32_16x16x32_bf16 v[88:91], v[24:27], v[192:195], v[88:91]
	v_mfma_f32_16x16x32_bf16 v[88:91], v[28:31], v[200:203], v[88:91]
	v_mfma_f32_16x16x32_bf16 v[92:95], v[112:115], v[192:195], v[92:95]
	v_mfma_f32_16x16x32_bf16 v[92:95], v[116:119], v[200:203], v[92:95]
	v_mfma_f32_16x16x32_bf16 v[96:99], v[120:123], v[168:171], v[96:99]
	v_mfma_f32_16x16x32_bf16 v[96:99], v[124:127], v[172:175], v[96:99]
	v_mfma_f32_16x16x32_bf16 v[32:35], v[160:163], v[168:171], v[32:35]
	v_mfma_f32_16x16x32_bf16 v[32:35], v[164:167], v[172:175], v[32:35]
	v_mfma_f32_16x16x32_bf16 v[36:39], v[120:123], v[176:179], v[36:39]
	v_mfma_f32_16x16x32_bf16 v[36:39], v[124:127], v[180:183], v[36:39]
	v_mfma_f32_16x16x32_bf16 v[40:43], v[160:163], v[176:179], v[40:43]
	v_mfma_f32_16x16x32_bf16 v[40:43], v[164:167], v[180:183], v[40:43]
	v_mfma_f32_16x16x32_bf16 v[44:47], v[120:123], v[184:187], v[44:47]
	v_mfma_f32_16x16x32_bf16 v[44:47], v[124:127], v[188:191], v[44:47]
	v_mfma_f32_16x16x32_bf16 v[48:51], v[160:163], v[184:187], v[48:51]
	v_mfma_f32_16x16x32_bf16 v[48:51], v[164:167], v[188:191], v[48:51]
	v_mfma_f32_16x16x32_bf16 v[52:55], v[120:123], v[192:195], v[52:55]
	v_mfma_f32_16x16x32_bf16 v[52:55], v[124:127], v[200:203], v[52:55]
	v_mfma_f32_16x16x32_bf16 v[56:59], v[160:163], v[192:195], v[56:59]
	v_mfma_f32_16x16x32_bf16 v[56:59], v[164:167], v[200:203], v[56:59]
	s_barrier
	s_setprio 0
	s_add_u32 s74, s36, 0x180
	s_addc_u32 s75, s37, 0
	s_add_i32 s71, s71, s97
	s_add_i32 s56, s71, 0x2000
	s_mov_b32 m0, s71
	s_add_u32 s36, s36, 0x80180
	ds_read_b128 v[168:171], v135 offset:49152
	ds_read_b128 v[172:175], v135 offset:50176
	ds_read_b128 v[176:179], v135 offset:51200
	ds_read_b128 v[180:183], v135 offset:52224
	ds_read_b128 v[184:187], v135 offset:53248
	ds_read_b128 v[188:191], v135 offset:54272
	ds_read_b128 v[192:195], v135 offset:55296
	ds_read_b128 v[200:203], v135 offset:56320
	s_addc_u32 s37, s37, 0
	global_load_lds_dwordx4 v132, s[74:75]
	s_mov_b32 m0, s56
	s_add_i32 s57, s69, s97
	s_add_i32 s69, s57, 0x2000
	global_load_lds_dwordx4 v130, s[74:75]
	s_mov_b32 m0, s57
	s_nop 0
	global_load_lds_dwordx4 v132, s[36:37]
	s_mov_b32 m0, s69
	s_nop 0
	global_load_lds_dwordx4 v130, s[36:37]
	s_mov_b32 m0, s48
	s_nop 0
	global_load_lds_dwordx4 v133, s[80:81]
	s_mov_b32 m0, s49
	s_nop 0
	global_load_lds_dwordx4 v131, s[80:81]
	s_waitcnt vmcnt(8)
	s_waitcnt lgkmcnt(0)
	s_setprio 1
	s_barrier
	v_mfma_f32_16x16x32_bf16 v[0:3], v[24:27], v[192:195], v[0:3]
	v_mfma_f32_16x16x32_bf16 v[0:3], v[28:31], v[200:203], v[0:3]
	v_mfma_f32_16x16x32_bf16 v[4:7], v[112:115], v[192:195], v[4:7]
	v_mfma_f32_16x16x32_bf16 v[4:7], v[116:119], v[200:203], v[4:7]
	v_mfma_f32_16x16x32_bf16 v[136:139], v[24:27], v[168:171], v[136:139]
	v_mfma_f32_16x16x32_bf16 v[136:139], v[28:31], v[172:175], v[136:139]
	v_mfma_f32_16x16x32_bf16 v[140:143], v[112:115], v[168:171], v[140:143]
	v_mfma_f32_16x16x32_bf16 v[140:143], v[116:119], v[172:175], v[140:143]
	v_mfma_f32_16x16x32_bf16 v[144:147], v[24:27], v[176:179], v[144:147]
	v_mfma_f32_16x16x32_bf16 v[144:147], v[28:31], v[180:183], v[144:147]
	v_mfma_f32_16x16x32_bf16 v[148:151], v[112:115], v[176:179], v[148:151]
	v_mfma_f32_16x16x32_bf16 v[148:151], v[116:119], v[180:183], v[148:151]
	v_mfma_f32_16x16x32_bf16 v[152:155], v[24:27], v[184:187], v[152:155]
	v_mfma_f32_16x16x32_bf16 v[152:155], v[28:31], v[188:191], v[152:155]
	v_mfma_f32_16x16x32_bf16 v[156:159], v[112:115], v[184:187], v[156:159]
	v_mfma_f32_16x16x32_bf16 v[156:159], v[116:119], v[188:191], v[156:159]
	v_mfma_f32_16x16x32_bf16 v[8:11], v[120:123], v[168:171], v[8:11]
	v_mfma_f32_16x16x32_bf16 v[12:15], v[160:163], v[168:171], v[12:15]
	v_mfma_f32_16x16x32_bf16 v[24:27], v[120:123], v[176:179], v[60:63]
	v_mfma_f32_16x16x32_bf16 v[28:31], v[160:163], v[176:179], v[100:103]
	v_mfma_f32_16x16x32_bf16 v[60:63], v[120:123], v[184:187], v[104:107]
	v_mfma_f32_16x16x32_bf16 v[100:103], v[160:163], v[184:187], v[108:111]
	v_mfma_f32_16x16x32_bf16 v[16:19], v[120:123], v[192:195], v[16:19]
	v_mfma_f32_16x16x32_bf16 v[20:23], v[160:163], v[192:195], v[20:23]
	v_mfma_f32_16x16x32_bf16 v[8:11], v[124:127], v[172:175], v[8:11]
	v_mfma_f32_16x16x32_bf16 v[12:15], v[164:167], v[172:175], v[12:15]
	v_mfma_f32_16x16x32_bf16 v[24:27], v[124:127], v[180:183], v[24:27]
	v_mfma_f32_16x16x32_bf16 v[28:31], v[164:167], v[180:183], v[28:31]
	v_mfma_f32_16x16x32_bf16 v[60:63], v[124:127], v[188:191], v[60:63]
	v_mfma_f32_16x16x32_bf16 v[100:103], v[164:167], v[188:191], v[100:103]
	v_mfma_f32_16x16x32_bf16 v[16:19], v[124:127], v[200:203], v[16:19]
	v_mfma_f32_16x16x32_bf16 v[20:23], v[164:167], v[200:203], v[20:23]
	s_barrier
	s_setprio 0
	ds_read_b128 v[104:107], v128
	ds_read_b128 v[108:111], v128 offset:1024
	ds_read_b128 v[112:115], v128 offset:2048
	ds_read_b128 v[116:119], v128 offset:3072
	ds_read_b128 v[120:123], v129
	ds_read_b128 v[124:127], v129 offset:1024
	ds_read_b128 v[160:163], v129 offset:2048
	ds_read_b128 v[164:167], v129 offset:3072
	s_add_u32 s36, s38, 0x80
	s_addc_u32 s37, s39, 0
	s_add_u32 s30, s30, 0x10180
	s_addc_u32 s31, s31, 0
	s_mov_b32 m0, s5
	ds_read_b128 v[168:171], v135
	ds_read_b128 v[172:175], v135 offset:1024
	ds_read_b128 v[176:179], v135 offset:2048
	ds_read_b128 v[180:183], v135 offset:3072
	ds_read_b128 v[184:187], v135 offset:4096
	ds_read_b128 v[188:191], v135 offset:5120
	ds_read_b128 v[192:195], v135 offset:6144
	ds_read_b128 v[200:203], v135 offset:7168
	s_nop 0
	global_load_lds_dwordx4 v133, s[30:31]
	s_mov_b32 m0, s11
	s_nop 0
	global_load_lds_dwordx4 v131, s[30:31]
	s_waitcnt vmcnt(8)
	s_waitcnt lgkmcnt(0)
	s_setprio 1
	s_barrier
	v_mfma_f32_16x16x32_bf16 v[64:67], v[104:107], v[168:171], v[64:67]
	v_mfma_f32_16x16x32_bf16 v[64:67], v[108:111], v[172:175], v[64:67]
	v_mfma_f32_16x16x32_bf16 v[68:71], v[112:115], v[168:171], v[68:71]
	v_mfma_f32_16x16x32_bf16 v[68:71], v[116:119], v[172:175], v[68:71]
	v_mfma_f32_16x16x32_bf16 v[72:75], v[104:107], v[176:179], v[72:75]
	v_mfma_f32_16x16x32_bf16 v[72:75], v[108:111], v[180:183], v[72:75]
	v_mfma_f32_16x16x32_bf16 v[76:79], v[112:115], v[176:179], v[76:79]
	v_mfma_f32_16x16x32_bf16 v[76:79], v[116:119], v[180:183], v[76:79]
	v_mfma_f32_16x16x32_bf16 v[80:83], v[104:107], v[184:187], v[80:83]
	v_mfma_f32_16x16x32_bf16 v[80:83], v[108:111], v[188:191], v[80:83]
	v_mfma_f32_16x16x32_bf16 v[84:87], v[112:115], v[184:187], v[84:87]
	v_mfma_f32_16x16x32_bf16 v[84:87], v[116:119], v[188:191], v[84:87]
	v_mfma_f32_16x16x32_bf16 v[88:91], v[104:107], v[192:195], v[88:91]
	v_mfma_f32_16x16x32_bf16 v[88:91], v[108:111], v[200:203], v[88:91]
	v_mfma_f32_16x16x32_bf16 v[92:95], v[112:115], v[192:195], v[92:95]
	v_mfma_f32_16x16x32_bf16 v[92:95], v[116:119], v[200:203], v[92:95]
	v_mfma_f32_16x16x32_bf16 v[32:35], v[160:163], v[168:171], v[32:35]
	v_mfma_f32_16x16x32_bf16 v[96:99], v[120:123], v[168:171], v[96:99]
	v_mfma_f32_16x16x32_bf16 v[168:171], v[164:167], v[172:175], v[32:35]
	v_mfma_f32_16x16x32_bf16 v[32:35], v[120:123], v[176:179], v[36:39]
	v_mfma_f32_16x16x32_bf16 v[36:39], v[124:127], v[180:183], v[32:35]
	v_mfma_f32_16x16x32_bf16 v[32:35], v[160:163], v[176:179], v[40:43]
	v_mfma_f32_16x16x32_bf16 v[204:207], v[124:127], v[172:175], v[96:99]
	v_mfma_f32_16x16x32_bf16 v[172:175], v[164:167], v[180:183], v[32:35]
	v_mfma_f32_16x16x32_bf16 v[32:35], v[120:123], v[184:187], v[44:47]
	v_mfma_f32_16x16x32_bf16 v[44:47], v[124:127], v[188:191], v[32:35]
	v_mfma_f32_16x16x32_bf16 v[32:35], v[160:163], v[184:187], v[48:51]
	v_mfma_f32_16x16x32_bf16 v[48:51], v[164:167], v[188:191], v[32:35]
	v_mfma_f32_16x16x32_bf16 v[32:35], v[120:123], v[192:195], v[52:55]
	v_mfma_f32_16x16x32_bf16 v[52:55], v[124:127], v[200:203], v[32:35]
	v_mfma_f32_16x16x32_bf16 v[32:35], v[160:163], v[192:195], v[56:59]
	v_mfma_f32_16x16x32_bf16 v[56:59], v[164:167], v[200:203], v[32:35]
	s_barrier
	s_setprio 0
	s_mov_b32 m0, s70
	s_mov_b64 s[30:31], s[34:35]
	s_nop 2
	ds_read_b128 v[32:35], v135 offset:16384
	ds_read_b128 v[40:43], v135 offset:17408
	ds_read_b128 v[96:99], v135 offset:18432
	ds_read_b128 v[176:179], v135 offset:19456
	ds_read_b128 v[180:183], v135 offset:20480
	ds_read_b128 v[184:187], v135 offset:21504
	ds_read_b128 v[188:191], v135 offset:22528
	ds_read_b128 v[192:195], v135 offset:23552
	s_nop 0
	global_load_lds_dwordx4 v132, s[30:31]
	s_mov_b32 m0, s4
	s_add_u32 s4, s34, 0x80000
	s_addc_u32 s5, s35, 0
	global_load_lds_dwordx4 v130, s[30:31]
	s_mov_b32 m0, s13
	s_nop 0
	global_load_lds_dwordx4 v132, s[4:5]
	s_mov_b32 m0, s15
	s_nop 0
	global_load_lds_dwordx4 v130, s[4:5]
	s_mov_b64 s[4:5], s[38:39]
	s_mov_b32 m0, s25
	s_nop 0
	global_load_lds_dwordx4 v133, s[4:5]
	s_mov_b32 m0, s27
	s_nop 0
	global_load_lds_dwordx4 v131, s[4:5]
	s_waitcnt vmcnt(8)
	s_waitcnt lgkmcnt(0)
	s_setprio 1
	s_barrier
	v_mfma_f32_16x16x32_bf16 v[0:3], v[104:107], v[188:191], v[0:3]
	v_mfma_f32_16x16x32_bf16 v[0:3], v[108:111], v[192:195], v[0:3]
	v_mfma_f32_16x16x32_bf16 v[4:7], v[112:115], v[188:191], v[4:7]
	v_mfma_f32_16x16x32_bf16 v[4:7], v[116:119], v[192:195], v[4:7]
	v_mfma_f32_16x16x32_bf16 v[136:139], v[104:107], v[32:35], v[136:139]
	v_mfma_f32_16x16x32_bf16 v[136:139], v[108:111], v[40:43], v[136:139]
	v_mfma_f32_16x16x32_bf16 v[140:143], v[112:115], v[32:35], v[140:143]
	v_mfma_f32_16x16x32_bf16 v[140:143], v[116:119], v[40:43], v[140:143]
	v_mfma_f32_16x16x32_bf16 v[144:147], v[104:107], v[96:99], v[144:147]
	v_mfma_f32_16x16x32_bf16 v[144:147], v[108:111], v[176:179], v[144:147]
	v_mfma_f32_16x16x32_bf16 v[148:151], v[112:115], v[96:99], v[148:151]
	v_mfma_f32_16x16x32_bf16 v[148:151], v[116:119], v[176:179], v[148:151]
	v_mfma_f32_16x16x32_bf16 v[152:155], v[104:107], v[180:183], v[152:155]
	v_mfma_f32_16x16x32_bf16 v[152:155], v[108:111], v[184:187], v[152:155]
	v_mfma_f32_16x16x32_bf16 v[156:159], v[112:115], v[180:183], v[156:159]
	v_mfma_f32_16x16x32_bf16 v[156:159], v[116:119], v[184:187], v[156:159]
	v_mfma_f32_16x16x32_bf16 v[12:15], v[160:163], v[32:35], v[12:15]
	v_mfma_f32_16x16x32_bf16 v[200:203], v[164:167], v[40:43], v[12:15]
	v_mfma_f32_16x16x32_bf16 v[12:15], v[120:123], v[96:99], v[24:27]
	v_mfma_f32_16x16x32_bf16 v[24:27], v[124:127], v[176:179], v[12:15]
	v_mfma_f32_16x16x32_bf16 v[12:15], v[160:163], v[96:99], v[28:31]
	v_mfma_f32_16x16x32_bf16 v[176:179], v[164:167], v[176:179], v[12:15]
	v_mfma_f32_16x16x32_bf16 v[12:15], v[120:123], v[180:183], v[60:63]
	v_mfma_f32_16x16x32_bf16 v[208:211], v[124:127], v[184:187], v[12:15]
	v_mfma_f32_16x16x32_bf16 v[12:15], v[160:163], v[180:183], v[100:103]
	v_mfma_f32_16x16x32_bf16 v[8:11], v[120:123], v[32:35], v[8:11]
	v_mfma_f32_16x16x32_bf16 v[180:183], v[164:167], v[184:187], v[12:15]
	v_mfma_f32_16x16x32_bf16 v[12:15], v[120:123], v[188:191], v[16:19]
	v_mfma_f32_16x16x32_bf16 v[8:11], v[124:127], v[40:43], v[8:11]
	v_mfma_f32_16x16x32_bf16 v[184:187], v[124:127], v[192:195], v[12:15]
	v_mfma_f32_16x16x32_bf16 v[12:15], v[160:163], v[188:191], v[20:23]
	v_mfma_f32_16x16x32_bf16 v[160:163], v[164:167], v[192:195], v[12:15]
	s_barrier
	s_setprio 0
	s_nop 4
	ds_read_b128 v[12:15], v196
	ds_read_b128 v[16:19], v196 offset:1024
	ds_read_b128 v[164:167], v196 offset:2048
	ds_read_b128 v[188:191], v196 offset:3072
	ds_read_b128 v[192:195], v198
	ds_read_b128 v[220:223], v198 offset:1024
	ds_read_b128 v[224:227], v198 offset:2048
	ds_read_b128 v[228:231], v198 offset:3072
	s_add_u32 s4, s38, 0x10000
	s_addc_u32 s5, s39, 0
	s_mov_b32 m0, s29
	ds_read_b128 v[20:23], v135 offset:32768
	ds_read_b128 v[28:31], v135 offset:33792
	ds_read_b128 v[60:63], v135 offset:34816
	ds_read_b128 v[100:103], v135 offset:35840
	ds_read_b128 v[232:235], v135 offset:36864
	ds_read_b128 v[236:239], v135 offset:37888
	ds_read_b128 v[240:243], v135 offset:38912
	ds_read_b128 v[244:247], v135 offset:39936
	s_nop 0
	global_load_lds_dwordx4 v133, s[4:5]
	s_mov_b32 m0, s47
	s_nop 0
	global_load_lds_dwordx4 v131, s[4:5]
	s_waitcnt vmcnt(8)
	s_waitcnt lgkmcnt(0)
	s_setprio 1
	s_barrier
	v_mfma_f32_16x16x32_bf16 v[32:35], v[12:15], v[20:23], v[64:67]
	v_mfma_f32_16x16x32_bf16 v[120:123], v[16:19], v[28:31], v[32:35]
	v_mfma_f32_16x16x32_bf16 v[32:35], v[164:167], v[20:23], v[68:71]
	v_mfma_f32_16x16x32_bf16 v[112:115], v[188:191], v[28:31], v[32:35]
	v_mfma_f32_16x16x32_bf16 v[32:35], v[12:15], v[60:63], v[72:75]
	v_mfma_f32_16x16x32_bf16 v[104:107], v[16:19], v[100:103], v[32:35]
	v_mfma_f32_16x16x32_bf16 v[32:35], v[164:167], v[60:63], v[76:79]
	v_mfma_f32_16x16x32_bf16 v[96:99], v[188:191], v[100:103], v[32:35]
	v_mfma_f32_16x16x32_bf16 v[32:35], v[12:15], v[232:235], v[80:83]
	v_mfma_f32_16x16x32_bf16 v[72:75], v[16:19], v[236:239], v[32:35]
	v_mfma_f32_16x16x32_bf16 v[32:35], v[164:167], v[232:235], v[84:87]
	v_mfma_f32_16x16x32_bf16 v[64:67], v[188:191], v[236:239], v[32:35]
	v_mfma_f32_16x16x32_bf16 v[32:35], v[12:15], v[240:243], v[88:91]
	v_mfma_f32_16x16x32_bf16 v[40:43], v[16:19], v[244:247], v[32:35]
	v_mfma_f32_16x16x32_bf16 v[32:35], v[164:167], v[240:243], v[92:95]
	v_mfma_f32_16x16x32_bf16 v[32:35], v[188:191], v[244:247], v[32:35]
	v_mfma_f32_16x16x32_bf16 v[68:71], v[192:195], v[20:23], v[204:207]
	v_mfma_f32_16x16x32_bf16 v[20:23], v[224:227], v[20:23], v[168:171]
	v_mfma_f32_16x16x32_bf16 v[116:119], v[228:231], v[28:31], v[20:23]
	v_mfma_f32_16x16x32_bf16 v[20:23], v[192:195], v[60:63], v[36:39]
	v_mfma_f32_16x16x32_bf16 v[108:111], v[220:223], v[100:103], v[20:23]
	v_mfma_f32_16x16x32_bf16 v[20:23], v[224:227], v[60:63], v[172:175]
	v_mfma_f32_16x16x32_bf16 v[100:103], v[228:231], v[100:103], v[20:23]
	v_mfma_f32_16x16x32_bf16 v[20:23], v[192:195], v[232:235], v[44:47]
	v_mfma_f32_16x16x32_bf16 v[76:79], v[220:223], v[236:239], v[20:23]
	v_mfma_f32_16x16x32_bf16 v[20:23], v[224:227], v[232:235], v[48:51]
	v_mfma_f32_16x16x32_bf16 v[124:127], v[220:223], v[28:31], v[68:71]
	v_mfma_f32_16x16x32_bf16 v[68:71], v[228:231], v[236:239], v[20:23]
	v_mfma_f32_16x16x32_bf16 v[20:23], v[192:195], v[240:243], v[52:55]
	v_mfma_f32_16x16x32_bf16 v[44:47], v[220:223], v[244:247], v[20:23]
	v_mfma_f32_16x16x32_bf16 v[20:23], v[224:227], v[240:243], v[56:59]
	v_mfma_f32_16x16x32_bf16 v[36:39], v[228:231], v[244:247], v[20:23]
	s_barrier
	s_setprio 0
	s_add_u32 s4, s34, 0x80
	s_mov_b32 m0, s71
	s_addc_u32 s5, s35, 0
	ds_read_b128 v[48:51], v135 offset:49152
	ds_read_b128 v[56:59], v135 offset:50176
	ds_read_b128 v[168:171], v135 offset:51200
	ds_read_b128 v[172:175], v135 offset:52224
	ds_read_b128 v[204:207], v135 offset:53248
	ds_read_b128 v[232:235], v135 offset:54272
	ds_read_b128 v[236:239], v135 offset:55296
	ds_read_b128 v[240:243], v135 offset:56320
	s_nop 0
	global_load_lds_dwordx4 v132, s[4:5]
	s_mov_b32 m0, s56
	s_nop 0
	global_load_lds_dwordx4 v130, s[4:5]
	s_add_u32 s4, s34, 0x80080
	s_addc_u32 s5, s35, 0
	s_mov_b32 m0, s57
	s_nop 0
	global_load_lds_dwordx4 v132, s[4:5]
	s_mov_b32 m0, s69
	s_nop 0
	global_load_lds_dwordx4 v130, s[4:5]
	s_mov_b32 m0, s48
	s_nop 0
	global_load_lds_dwordx4 v133, s[36:37]
	s_mov_b32 m0, s49
	s_nop 0
	global_load_lds_dwordx4 v131, s[36:37]
	s_waitcnt vmcnt(8)
	s_waitcnt lgkmcnt(0)
	s_setprio 1
	s_barrier
	v_mfma_f32_16x16x32_bf16 v[20:23], v[12:15], v[48:51], v[136:139]
	v_mfma_f32_16x16x32_bf16 v[92:95], v[16:19], v[56:59], v[20:23]
	v_mfma_f32_16x16x32_bf16 v[20:23], v[164:167], v[48:51], v[140:143]
	v_mfma_f32_16x16x32_bf16 v[84:87], v[188:191], v[56:59], v[20:23]
	v_mfma_f32_16x16x32_bf16 v[20:23], v[12:15], v[168:171], v[144:147]
	v_mfma_f32_16x16x32_bf16 v[60:63], v[16:19], v[172:175], v[20:23]
	v_mfma_f32_16x16x32_bf16 v[20:23], v[164:167], v[168:171], v[148:151]
	v_mfma_f32_16x16x32_bf16 v[52:55], v[188:191], v[172:175], v[20:23]
	v_mfma_f32_16x16x32_bf16 v[20:23], v[12:15], v[204:207], v[152:155]
	v_mfma_f32_16x16x32_bf16 v[0:3], v[12:15], v[236:239], v[0:3]
	v_mfma_f32_16x16x32_bf16 v[28:31], v[16:19], v[232:235], v[20:23]
	v_mfma_f32_16x16x32_bf16 v[20:23], v[164:167], v[204:207], v[156:159]
	v_mfma_f32_16x16x32_bf16 v[12:15], v[16:19], v[240:243], v[0:3]
	v_mfma_f32_16x16x32_bf16 v[0:3], v[164:167], v[236:239], v[4:7]
	v_mfma_f32_16x16x32_bf16 v[20:23], v[188:191], v[232:235], v[20:23]
	v_mfma_f32_16x16x32_bf16 v[4:7], v[188:191], v[240:243], v[0:3]
	v_mfma_f32_16x16x32_bf16 v[0:3], v[192:195], v[48:51], v[8:11]
	v_mfma_f32_16x16x32_bf16 v[88:91], v[220:223], v[56:59], v[0:3]
	v_mfma_f32_16x16x32_bf16 v[0:3], v[224:227], v[48:51], v[200:203]
	v_mfma_f32_16x16x32_bf16 v[80:83], v[228:231], v[56:59], v[0:3]
	v_mfma_f32_16x16x32_bf16 v[0:3], v[192:195], v[168:171], v[24:27]
	v_mfma_f32_16x16x32_bf16 v[56:59], v[220:223], v[172:175], v[0:3]
	v_mfma_f32_16x16x32_bf16 v[0:3], v[224:227], v[168:171], v[176:179]
	v_mfma_f32_16x16x32_bf16 v[48:51], v[228:231], v[172:175], v[0:3]
	v_mfma_f32_16x16x32_bf16 v[0:3], v[192:195], v[204:207], v[208:211]
	v_mfma_f32_16x16x32_bf16 v[24:27], v[220:223], v[232:235], v[0:3]
	v_mfma_f32_16x16x32_bf16 v[0:3], v[224:227], v[204:207], v[180:183]
	v_mfma_f32_16x16x32_bf16 v[16:19], v[228:231], v[232:235], v[0:3]
	v_mfma_f32_16x16x32_bf16 v[0:3], v[192:195], v[236:239], v[184:187]
	v_mfma_f32_16x16x32_bf16 v[8:11], v[220:223], v[240:243], v[0:3]
	v_mfma_f32_16x16x32_bf16 v[0:3], v[224:227], v[236:239], v[160:163]
	v_mfma_f32_16x16x32_bf16 v[0:3], v[228:231], v[240:243], v[0:3]
	s_barrier
	s_setprio 0
	s_andn2_b64 vcc, exec, s[60:61]
	s_cbranch_vccnz .LBB0_315
	s_barrier

.LBB0_380:
	s_cmp_eq_u32 s15, 28
	s_cselect_b32 s36, s20, s4
	s_cselect_b32 s37, s21, s5
	s_cselect_b32 s34, s26, s11
	s_cselect_b32 s35, s27, s13
	s_add_u32 s30, s36, 0x80
	s_addc_u32 s31, s37, 0
	s_add_i32 s17, 0, 0x10000
	v_add_u32_e32 v128, s17, v134
	s_add_i32 s69, 0, 0x14000
	ds_read_b128 v[136:139], v128
	ds_read_b128 v[140:143], v128 offset:1024
	ds_read_b128 v[144:147], v128 offset:2048
	ds_read_b128 v[148:151], v128 offset:3072
	v_add_u32_e32 v128, s69, v134
	ds_read_b128 v[152:155], v128
	ds_read_b128 v[156:159], v128 offset:1024
	ds_read_b128 v[160:163], v128 offset:2048
	ds_read_b128 v[164:167], v128 offset:3072
	s_mov_b64 s[70:71], s[28:29]
	s_add_i32 m0, s23, 0xc000
	ds_read_b128 v[168:171], v135
	ds_read_b128 v[172:175], v135 offset:1024
	ds_read_b128 v[176:179], v135 offset:2048
	ds_read_b128 v[180:183], v135 offset:3072
	ds_read_b128 v[184:187], v135 offset:4096
	ds_read_b128 v[188:191], v135 offset:5120
	ds_read_b128 v[192:195], v135 offset:6144
	ds_read_b128 v[200:203], v135 offset:7168
	s_nop 0
	global_load_lds_dwordx4 v133, s[70:71]
	s_add_i32 m0, s23, 0xe000
	s_nop 0
	global_load_lds_dwordx4 v131, s[70:71]
	s_waitcnt vmcnt(8)
	s_waitcnt lgkmcnt(0)
	s_setprio 1
	s_barrier
	v_mfma_f32_16x16x32_bf16 v[124:127], v[136:139], v[168:171], v[124:127]
	v_mfma_f32_16x16x32_bf16 v[124:127], v[140:143], v[172:175], v[124:127]
	v_mfma_f32_16x16x32_bf16 v[120:123], v[144:147], v[168:171], v[120:123]
	v_mfma_f32_16x16x32_bf16 v[120:123], v[148:151], v[172:175], v[120:123]
	v_mfma_f32_16x16x32_bf16 v[116:119], v[136:139], v[176:179], v[116:119]
	v_mfma_f32_16x16x32_bf16 v[116:119], v[140:143], v[180:183], v[116:119]
	v_mfma_f32_16x16x32_bf16 v[108:111], v[144:147], v[176:179], v[108:111]
	v_mfma_f32_16x16x32_bf16 v[108:111], v[148:151], v[180:183], v[108:111]
	v_mfma_f32_16x16x32_bf16 v[100:103], v[136:139], v[184:187], v[100:103]
	v_mfma_f32_16x16x32_bf16 v[100:103], v[140:143], v[188:191], v[100:103]
	v_mfma_f32_16x16x32_bf16 v[92:95], v[144:147], v[184:187], v[92:95]
	v_mfma_f32_16x16x32_bf16 v[92:95], v[148:151], v[188:191], v[92:95]
	v_mfma_f32_16x16x32_bf16 v[84:87], v[136:139], v[192:195], v[84:87]
	v_mfma_f32_16x16x32_bf16 v[84:87], v[140:143], v[200:203], v[84:87]
	v_mfma_f32_16x16x32_bf16 v[76:79], v[144:147], v[192:195], v[76:79]
	v_mfma_f32_16x16x32_bf16 v[76:79], v[148:151], v[200:203], v[76:79]
	v_mfma_f32_16x16x32_bf16 v[112:115], v[152:155], v[168:171], v[112:115]
	v_mfma_f32_16x16x32_bf16 v[112:115], v[156:159], v[172:175], v[112:115]
	v_mfma_f32_16x16x32_bf16 v[104:107], v[160:163], v[168:171], v[104:107]
	v_mfma_f32_16x16x32_bf16 v[104:107], v[164:167], v[172:175], v[104:107]
	v_mfma_f32_16x16x32_bf16 v[96:99], v[152:155], v[176:179], v[96:99]
	v_mfma_f32_16x16x32_bf16 v[96:99], v[156:159], v[180:183], v[96:99]
	v_mfma_f32_16x16x32_bf16 v[88:91], v[160:163], v[176:179], v[88:91]
	v_mfma_f32_16x16x32_bf16 v[88:91], v[164:167], v[180:183], v[88:91]
	v_mfma_f32_16x16x32_bf16 v[80:83], v[152:155], v[184:187], v[80:83]
	v_mfma_f32_16x16x32_bf16 v[80:83], v[156:159], v[188:191], v[80:83]
	v_mfma_f32_16x16x32_bf16 v[72:75], v[160:163], v[184:187], v[72:75]
	v_mfma_f32_16x16x32_bf16 v[72:75], v[164:167], v[188:191], v[72:75]
	v_mfma_f32_16x16x32_bf16 v[68:71], v[152:155], v[192:195], v[68:71]
	v_mfma_f32_16x16x32_bf16 v[68:71], v[156:159], v[200:203], v[68:71]
	v_mfma_f32_16x16x32_bf16 v[64:67], v[160:163], v[192:195], v[64:67]
	v_mfma_f32_16x16x32_bf16 v[64:67], v[164:167], v[200:203], v[64:67]
	s_barrier
	s_setprio 0
	s_add_i32 s17, s17, s97
	s_mov_b64 s[70:71], s[34:35]
	s_mov_b32 m0, s17
	ds_read_b128 v[168:171], v135 offset:16384
	ds_read_b128 v[172:175], v135 offset:17408
	ds_read_b128 v[176:179], v135 offset:18432
	ds_read_b128 v[180:183], v135 offset:19456
	ds_read_b128 v[184:187], v135 offset:20480
	ds_read_b128 v[188:191], v135 offset:21504
	ds_read_b128 v[192:195], v135 offset:22528
	ds_read_b128 v[200:203], v135 offset:23552
	s_nop 0
	global_load_lds_dwordx4 v132, s[70:71]
	s_add_i32 m0, s17, 0x2000
	s_nop 0
	global_load_lds_dwordx4 v130, s[70:71]
	s_add_u32 s70, s34, 0x200000
	s_addc_u32 s71, s35, 0
	s_add_i32 s17, s69, s97
	s_mov_b32 m0, s17
	s_nop 0
	global_load_lds_dwordx4 v132, s[70:71]
	s_add_i32 m0, s17, 0x2000
	s_nop 0
	global_load_lds_dwordx4 v130, s[70:71]
	s_mov_b64 s[70:71], s[36:37]
	s_mov_b32 m0, s23
	s_nop 0
	global_load_lds_dwordx4 v133, s[70:71]
	s_mov_b32 m0, s25
	s_nop 0
	global_load_lds_dwordx4 v131, s[70:71]
	s_waitcnt vmcnt(8)
	s_waitcnt lgkmcnt(0)
	s_setprio 1
	s_barrier
	v_mfma_f32_16x16x32_bf16 v[60:63], v[136:139], v[168:171], v[60:63]
	v_mfma_f32_16x16x32_bf16 v[60:63], v[140:143], v[172:175], v[60:63]
	v_mfma_f32_16x16x32_bf16 v[56:59], v[144:147], v[168:171], v[56:59]
	v_mfma_f32_16x16x32_bf16 v[56:59], v[148:151], v[172:175], v[56:59]
	v_mfma_f32_16x16x32_bf16 v[52:55], v[136:139], v[176:179], v[52:55]
	v_mfma_f32_16x16x32_bf16 v[52:55], v[140:143], v[180:183], v[52:55]
	v_mfma_f32_16x16x32_bf16 v[44:47], v[144:147], v[176:179], v[44:47]
	v_mfma_f32_16x16x32_bf16 v[44:47], v[148:151], v[180:183], v[44:47]
	v_mfma_f32_16x16x32_bf16 v[36:39], v[136:139], v[184:187], v[36:39]
	v_mfma_f32_16x16x32_bf16 v[36:39], v[140:143], v[188:191], v[36:39]
	v_mfma_f32_16x16x32_bf16 v[28:31], v[144:147], v[184:187], v[28:31]
	v_mfma_f32_16x16x32_bf16 v[28:31], v[148:151], v[188:191], v[28:31]
	v_mfma_f32_16x16x32_bf16 v[20:23], v[136:139], v[192:195], v[20:23]
	v_mfma_f32_16x16x32_bf16 v[20:23], v[140:143], v[200:203], v[20:23]
	v_mfma_f32_16x16x32_bf16 v[12:15], v[144:147], v[192:195], v[12:15]
	v_mfma_f32_16x16x32_bf16 v[12:15], v[148:151], v[200:203], v[12:15]
	v_mfma_f32_16x16x32_bf16 v[48:51], v[152:155], v[168:171], v[48:51]
	v_mfma_f32_16x16x32_bf16 v[48:51], v[156:159], v[172:175], v[48:51]
	v_mfma_f32_16x16x32_bf16 v[40:43], v[160:163], v[168:171], v[40:43]
	v_mfma_f32_16x16x32_bf16 v[40:43], v[164:167], v[172:175], v[40:43]
	v_mfma_f32_16x16x32_bf16 v[32:35], v[152:155], v[176:179], v[32:35]
	v_mfma_f32_16x16x32_bf16 v[32:35], v[156:159], v[180:183], v[32:35]
	v_mfma_f32_16x16x32_bf16 v[24:27], v[160:163], v[176:179], v[24:27]
	v_mfma_f32_16x16x32_bf16 v[24:27], v[164:167], v[180:183], v[24:27]
	v_mfma_f32_16x16x32_bf16 v[16:19], v[152:155], v[184:187], v[16:19]
	v_mfma_f32_16x16x32_bf16 v[16:19], v[156:159], v[188:191], v[16:19]
	v_mfma_f32_16x16x32_bf16 v[8:11], v[160:163], v[184:187], v[8:11]
	v_mfma_f32_16x16x32_bf16 v[8:11], v[164:167], v[188:191], v[8:11]
	v_mfma_f32_16x16x32_bf16 v[4:7], v[152:155], v[192:195], v[4:7]
	v_mfma_f32_16x16x32_bf16 v[4:7], v[156:159], v[200:203], v[4:7]
	v_mfma_f32_16x16x32_bf16 v[0:3], v[160:163], v[192:195], v[0:3]
	v_mfma_f32_16x16x32_bf16 v[0:3], v[164:167], v[200:203], v[0:3]
	s_barrier
	s_setprio 0
	s_add_i32 s17, 0, 0x18000
	v_add_u32_e32 v128, s17, v134
	s_add_i32 s69, 0, 0x1c000
	ds_read_b128 v[136:139], v128
	ds_read_b128 v[140:143], v128 offset:1024
	ds_read_b128 v[144:147], v128 offset:2048
	ds_read_b128 v[148:151], v128 offset:3072
	v_add_u32_e32 v128, s69, v134
	ds_read_b128 v[152:155], v128
	ds_read_b128 v[156:159], v128 offset:1024
	ds_read_b128 v[160:163], v128 offset:2048
	ds_read_b128 v[164:167], v128 offset:3072
	s_add_u32 s36, s36, 0x80000
	s_addc_u32 s37, s37, 0
	s_mov_b32 m0, s46
	ds_read_b128 v[168:171], v135 offset:32768
	ds_read_b128 v[172:175], v135 offset:33792
	ds_read_b128 v[176:179], v135 offset:34816
	ds_read_b128 v[180:183], v135 offset:35840
	ds_read_b128 v[184:187], v135 offset:36864
	ds_read_b128 v[188:191], v135 offset:37888
	ds_read_b128 v[192:195], v135 offset:38912
	ds_read_b128 v[200:203], v135 offset:39936
	s_nop 0
	global_load_lds_dwordx4 v133, s[36:37]
	s_mov_b32 m0, s47
	s_nop 0
	global_load_lds_dwordx4 v131, s[36:37]
	s_waitcnt vmcnt(8)
	s_waitcnt lgkmcnt(0)
	s_setprio 1
	s_barrier
	v_mfma_f32_16x16x32_bf16 v[124:127], v[136:139], v[168:171], v[124:127]
	v_mfma_f32_16x16x32_bf16 v[124:127], v[140:143], v[172:175], v[124:127]
	v_mfma_f32_16x16x32_bf16 v[120:123], v[144:147], v[168:171], v[120:123]
	v_mfma_f32_16x16x32_bf16 v[120:123], v[148:151], v[172:175], v[120:123]
	v_mfma_f32_16x16x32_bf16 v[116:119], v[136:139], v[176:179], v[116:119]
	v_mfma_f32_16x16x32_bf16 v[116:119], v[140:143], v[180:183], v[116:119]
	v_mfma_f32_16x16x32_bf16 v[108:111], v[144:147], v[176:179], v[108:111]
	v_mfma_f32_16x16x32_bf16 v[108:111], v[148:151], v[180:183], v[108:111]
	v_mfma_f32_16x16x32_bf16 v[100:103], v[136:139], v[184:187], v[100:103]
	v_mfma_f32_16x16x32_bf16 v[100:103], v[140:143], v[188:191], v[100:103]
	v_mfma_f32_16x16x32_bf16 v[92:95], v[144:147], v[184:187], v[92:95]
	v_mfma_f32_16x16x32_bf16 v[92:95], v[148:151], v[188:191], v[92:95]
	v_mfma_f32_16x16x32_bf16 v[84:87], v[136:139], v[192:195], v[84:87]
	v_mfma_f32_16x16x32_bf16 v[84:87], v[140:143], v[200:203], v[84:87]
	v_mfma_f32_16x16x32_bf16 v[76:79], v[144:147], v[192:195], v[76:79]
	v_mfma_f32_16x16x32_bf16 v[76:79], v[148:151], v[200:203], v[76:79]
	v_mfma_f32_16x16x32_bf16 v[112:115], v[152:155], v[168:171], v[112:115]
	v_mfma_f32_16x16x32_bf16 v[112:115], v[156:159], v[172:175], v[112:115]
	v_mfma_f32_16x16x32_bf16 v[104:107], v[160:163], v[168:171], v[104:107]
	v_mfma_f32_16x16x32_bf16 v[104:107], v[164:167], v[172:175], v[104:107]
	v_mfma_f32_16x16x32_bf16 v[96:99], v[152:155], v[176:179], v[96:99]
	v_mfma_f32_16x16x32_bf16 v[96:99], v[156:159], v[180:183], v[96:99]
	v_mfma_f32_16x16x32_bf16 v[88:91], v[160:163], v[176:179], v[88:91]
	v_mfma_f32_16x16x32_bf16 v[88:91], v[164:167], v[180:183], v[88:91]
	v_mfma_f32_16x16x32_bf16 v[80:83], v[152:155], v[184:187], v[80:83]
	v_mfma_f32_16x16x32_bf16 v[80:83], v[156:159], v[188:191], v[80:83]
	v_mfma_f32_16x16x32_bf16 v[72:75], v[160:163], v[184:187], v[72:75]
	v_mfma_f32_16x16x32_bf16 v[72:75], v[164:167], v[188:191], v[72:75]
	v_mfma_f32_16x16x32_bf16 v[68:71], v[152:155], v[192:195], v[68:71]
	v_mfma_f32_16x16x32_bf16 v[68:71], v[156:159], v[200:203], v[68:71]
	v_mfma_f32_16x16x32_bf16 v[64:67], v[160:163], v[192:195], v[64:67]
	v_mfma_f32_16x16x32_bf16 v[64:67], v[164:167], v[200:203], v[64:67]
	s_barrier
	s_setprio 0
	s_add_u32 s36, s34, 0x80
	s_addc_u32 s37, s35, 0
	s_add_i32 s17, s17, s97
	s_mov_b32 m0, s17
	ds_read_b128 v[168:171], v135 offset:49152
	ds_read_b128 v[172:175], v135 offset:50176
	ds_read_b128 v[176:179], v135 offset:51200
	ds_read_b128 v[180:183], v135 offset:52224
	ds_read_b128 v[184:187], v135 offset:53248
	ds_read_b128 v[188:191], v135 offset:54272
	ds_read_b128 v[192:195], v135 offset:55296
	ds_read_b128 v[200:203], v135 offset:56320
	s_nop 0
	global_load_lds_dwordx4 v132, s[36:37]
	s_add_i32 m0, s17, 0x2000
	s_add_u32 s34, s34, 0x200080
	s_addc_u32 s35, s35, 0
	s_add_i32 s17, s69, s97
	s_nop 0
	global_load_lds_dwordx4 v130, s[36:37]
	s_mov_b32 m0, s17
	s_nop 0
	global_load_lds_dwordx4 v132, s[34:35]
	s_add_i32 m0, s17, 0x2000
	s_nop 0
	global_load_lds_dwordx4 v130, s[34:35]
	s_mov_b32 m0, s56
	s_nop 0
	global_load_lds_dwordx4 v133, s[30:31]
	s_mov_b32 m0, s57
	s_nop 0
	global_load_lds_dwordx4 v131, s[30:31]
	s_waitcnt vmcnt(8)
	s_waitcnt lgkmcnt(0)
	s_setprio 1
	s_barrier
	v_mfma_f32_16x16x32_bf16 v[60:63], v[136:139], v[168:171], v[60:63]
	v_mfma_f32_16x16x32_bf16 v[60:63], v[140:143], v[172:175], v[60:63]
	v_mfma_f32_16x16x32_bf16 v[56:59], v[144:147], v[168:171], v[56:59]
	v_mfma_f32_16x16x32_bf16 v[56:59], v[148:151], v[172:175], v[56:59]
	v_mfma_f32_16x16x32_bf16 v[52:55], v[136:139], v[176:179], v[52:55]
	v_mfma_f32_16x16x32_bf16 v[52:55], v[140:143], v[180:183], v[52:55]
	v_mfma_f32_16x16x32_bf16 v[44:47], v[144:147], v[176:179], v[44:47]
	v_mfma_f32_16x16x32_bf16 v[44:47], v[148:151], v[180:183], v[44:47]
	v_mfma_f32_16x16x32_bf16 v[36:39], v[136:139], v[184:187], v[36:39]
	v_mfma_f32_16x16x32_bf16 v[36:39], v[140:143], v[188:191], v[36:39]
	v_mfma_f32_16x16x32_bf16 v[28:31], v[144:147], v[184:187], v[28:31]
	v_mfma_f32_16x16x32_bf16 v[28:31], v[148:151], v[188:191], v[28:31]
	v_mfma_f32_16x16x32_bf16 v[20:23], v[136:139], v[192:195], v[20:23]
	v_mfma_f32_16x16x32_bf16 v[20:23], v[140:143], v[200:203], v[20:23]
	v_mfma_f32_16x16x32_bf16 v[12:15], v[144:147], v[192:195], v[12:15]
	v_mfma_f32_16x16x32_bf16 v[12:15], v[148:151], v[200:203], v[12:15]
	v_mfma_f32_16x16x32_bf16 v[48:51], v[152:155], v[168:171], v[48:51]
	v_mfma_f32_16x16x32_bf16 v[48:51], v[156:159], v[172:175], v[48:51]
	v_mfma_f32_16x16x32_bf16 v[40:43], v[160:163], v[168:171], v[40:43]
	v_mfma_f32_16x16x32_bf16 v[40:43], v[164:167], v[172:175], v[40:43]
	v_mfma_f32_16x16x32_bf16 v[32:35], v[152:155], v[176:179], v[32:35]
	v_mfma_f32_16x16x32_bf16 v[32:35], v[156:159], v[180:183], v[32:35]
	v_mfma_f32_16x16x32_bf16 v[24:27], v[160:163], v[176:179], v[24:27]
	v_mfma_f32_16x16x32_bf16 v[24:27], v[164:167], v[180:183], v[24:27]
	v_mfma_f32_16x16x32_bf16 v[16:19], v[152:155], v[184:187], v[16:19]
	v_mfma_f32_16x16x32_bf16 v[16:19], v[156:159], v[188:191], v[16:19]
	v_mfma_f32_16x16x32_bf16 v[8:11], v[160:163], v[184:187], v[8:11]
	v_mfma_f32_16x16x32_bf16 v[8:11], v[164:167], v[188:191], v[8:11]
	v_mfma_f32_16x16x32_bf16 v[4:7], v[152:155], v[192:195], v[4:7]
	v_mfma_f32_16x16x32_bf16 v[4:7], v[156:159], v[200:203], v[4:7]
	v_mfma_f32_16x16x32_bf16 v[0:3], v[160:163], v[192:195], v[0:3]
	v_mfma_f32_16x16x32_bf16 v[0:3], v[164:167], v[200:203], v[0:3]
	s_barrier
	s_setprio 0
	s_add_i32 s15, s15, 2
	s_add_u32 s4, s4, 0x100
	s_addc_u32 s5, s5, 0
	s_add_u32 s11, s11, 0x100
	s_addc_u32 s13, s13, 0
	s_add_u32 s28, s28, 0x100
	s_addc_u32 s29, s29, 0
	s_cmp_gt_u32 s15, 29
	s_cbranch_scc0 .LBB0_380
	s_and_b64 vcc, exec, s[60:61]
	s_cbranch_vccz .LBB0_383
	s_barrier

.LBB0_397:
	s_cmp_eq_u32 s69, 4
	s_cselect_b32 s34, s15, s49
	s_cselect_b32 s35, s5, s56
	s_cselect_b32 s30, s48, s57
	s_cselect_b32 s31, s13, s65
	s_add_u32 s28, s34, 0x80
	s_addc_u32 s29, s35, 0
	s_add_i32 s72, 0, 0x10000
	v_add_u32_e32 v128, s72, v134
	s_add_i32 s74, 0, 0x14000
	ds_read_b128 v[136:139], v128
	ds_read_b128 v[140:143], v128 offset:1024
	ds_read_b128 v[144:147], v128 offset:2048
	ds_read_b128 v[148:151], v128 offset:3072
	v_add_u32_e32 v128, s74, v134
	ds_read_b128 v[152:155], v128
	ds_read_b128 v[156:159], v128 offset:1024
	ds_read_b128 v[160:163], v128 offset:2048
	ds_read_b128 v[164:167], v128 offset:3072
	s_mov_b64 s[70:71], s[26:27]
	s_add_i32 m0, s25, 0xc000
	ds_read_b128 v[168:171], v135
	ds_read_b128 v[172:175], v135 offset:1024
	ds_read_b128 v[176:179], v135 offset:2048
	ds_read_b128 v[180:183], v135 offset:3072
	ds_read_b128 v[184:187], v135 offset:4096
	ds_read_b128 v[188:191], v135 offset:5120
	ds_read_b128 v[192:195], v135 offset:6144
	ds_read_b128 v[200:203], v135 offset:7168
	s_nop 0
	global_load_lds_dwordx4 v133, s[70:71]
	s_add_i32 m0, s25, 0xe000
	s_nop 0
	global_load_lds_dwordx4 v131, s[70:71]
	s_waitcnt vmcnt(8)
	s_waitcnt lgkmcnt(0)
	s_setprio 1
	s_barrier
	v_mfma_f32_16x16x32_bf16 v[124:127], v[136:139], v[168:171], v[124:127]
	v_mfma_f32_16x16x32_bf16 v[124:127], v[140:143], v[172:175], v[124:127]
	v_mfma_f32_16x16x32_bf16 v[120:123], v[144:147], v[168:171], v[120:123]
	v_mfma_f32_16x16x32_bf16 v[120:123], v[148:151], v[172:175], v[120:123]
	v_mfma_f32_16x16x32_bf16 v[116:119], v[136:139], v[176:179], v[116:119]
	v_mfma_f32_16x16x32_bf16 v[116:119], v[140:143], v[180:183], v[116:119]
	v_mfma_f32_16x16x32_bf16 v[108:111], v[144:147], v[176:179], v[108:111]
	v_mfma_f32_16x16x32_bf16 v[108:111], v[148:151], v[180:183], v[108:111]
	v_mfma_f32_16x16x32_bf16 v[100:103], v[136:139], v[184:187], v[100:103]
	v_mfma_f32_16x16x32_bf16 v[100:103], v[140:143], v[188:191], v[100:103]
	v_mfma_f32_16x16x32_bf16 v[92:95], v[144:147], v[184:187], v[92:95]
	v_mfma_f32_16x16x32_bf16 v[92:95], v[148:151], v[188:191], v[92:95]
	v_mfma_f32_16x16x32_bf16 v[84:87], v[136:139], v[192:195], v[84:87]
	v_mfma_f32_16x16x32_bf16 v[84:87], v[140:143], v[200:203], v[84:87]
	v_mfma_f32_16x16x32_bf16 v[76:79], v[144:147], v[192:195], v[76:79]
	v_mfma_f32_16x16x32_bf16 v[76:79], v[148:151], v[200:203], v[76:79]
	v_mfma_f32_16x16x32_bf16 v[112:115], v[152:155], v[168:171], v[112:115]
	v_mfma_f32_16x16x32_bf16 v[112:115], v[156:159], v[172:175], v[112:115]
	v_mfma_f32_16x16x32_bf16 v[104:107], v[160:163], v[168:171], v[104:107]
	v_mfma_f32_16x16x32_bf16 v[104:107], v[164:167], v[172:175], v[104:107]
	v_mfma_f32_16x16x32_bf16 v[96:99], v[152:155], v[176:179], v[96:99]
	v_mfma_f32_16x16x32_bf16 v[96:99], v[156:159], v[180:183], v[96:99]
	v_mfma_f32_16x16x32_bf16 v[88:91], v[160:163], v[176:179], v[88:91]
	v_mfma_f32_16x16x32_bf16 v[88:91], v[164:167], v[180:183], v[88:91]
	v_mfma_f32_16x16x32_bf16 v[80:83], v[152:155], v[184:187], v[80:83]
	v_mfma_f32_16x16x32_bf16 v[80:83], v[156:159], v[188:191], v[80:83]
	v_mfma_f32_16x16x32_bf16 v[72:75], v[160:163], v[184:187], v[72:75]
	v_mfma_f32_16x16x32_bf16 v[72:75], v[164:167], v[188:191], v[72:75]
	v_mfma_f32_16x16x32_bf16 v[68:71], v[152:155], v[192:195], v[68:71]
	v_mfma_f32_16x16x32_bf16 v[68:71], v[156:159], v[200:203], v[68:71]
	v_mfma_f32_16x16x32_bf16 v[64:67], v[160:163], v[192:195], v[64:67]
	v_mfma_f32_16x16x32_bf16 v[64:67], v[164:167], v[200:203], v[64:67]
	s_barrier
	s_setprio 0
	s_add_i32 s72, s72, s97
	s_mov_b64 s[70:71], s[30:31]
	s_mov_b32 m0, s72
	ds_read_b128 v[168:171], v135 offset:16384
	ds_read_b128 v[172:175], v135 offset:17408
	ds_read_b128 v[176:179], v135 offset:18432
	ds_read_b128 v[180:183], v135 offset:19456
	ds_read_b128 v[184:187], v135 offset:20480
	ds_read_b128 v[188:191], v135 offset:21504
	ds_read_b128 v[192:195], v135 offset:22528
	ds_read_b128 v[200:203], v135 offset:23552
	s_nop 0
	global_load_lds_dwordx4 v132, s[70:71]
	s_add_i32 m0, s72, 0x2000
	s_nop 0
	global_load_lds_dwordx4 v130, s[70:71]
	s_add_u32 s70, s30, 0x20000
	s_addc_u32 s71, s31, 0
	s_add_i32 s72, s74, s97
	s_mov_b32 m0, s72
	s_nop 0
	global_load_lds_dwordx4 v132, s[70:71]
	s_add_i32 m0, s72, 0x2000
	s_nop 0
	global_load_lds_dwordx4 v130, s[70:71]
	s_mov_b64 s[70:71], s[34:35]
	s_mov_b32 m0, s25
	s_nop 0
	global_load_lds_dwordx4 v133, s[70:71]
	s_mov_b32 m0, s37
	s_nop 0
	global_load_lds_dwordx4 v131, s[70:71]
	s_waitcnt vmcnt(8)
	s_waitcnt lgkmcnt(0)
	s_setprio 1
	s_barrier
	v_mfma_f32_16x16x32_bf16 v[60:63], v[136:139], v[168:171], v[60:63]
	v_mfma_f32_16x16x32_bf16 v[60:63], v[140:143], v[172:175], v[60:63]
	v_mfma_f32_16x16x32_bf16 v[56:59], v[144:147], v[168:171], v[56:59]
	v_mfma_f32_16x16x32_bf16 v[56:59], v[148:151], v[172:175], v[56:59]
	v_mfma_f32_16x16x32_bf16 v[52:55], v[136:139], v[176:179], v[52:55]
	v_mfma_f32_16x16x32_bf16 v[52:55], v[140:143], v[180:183], v[52:55]
	v_mfma_f32_16x16x32_bf16 v[44:47], v[144:147], v[176:179], v[44:47]
	v_mfma_f32_16x16x32_bf16 v[44:47], v[148:151], v[180:183], v[44:47]
	v_mfma_f32_16x16x32_bf16 v[36:39], v[136:139], v[184:187], v[36:39]
	v_mfma_f32_16x16x32_bf16 v[36:39], v[140:143], v[188:191], v[36:39]
	v_mfma_f32_16x16x32_bf16 v[28:31], v[144:147], v[184:187], v[28:31]
	v_mfma_f32_16x16x32_bf16 v[28:31], v[148:151], v[188:191], v[28:31]
	v_mfma_f32_16x16x32_bf16 v[20:23], v[136:139], v[192:195], v[20:23]
	v_mfma_f32_16x16x32_bf16 v[20:23], v[140:143], v[200:203], v[20:23]
	v_mfma_f32_16x16x32_bf16 v[12:15], v[144:147], v[192:195], v[12:15]
	v_mfma_f32_16x16x32_bf16 v[12:15], v[148:151], v[200:203], v[12:15]
	v_mfma_f32_16x16x32_bf16 v[48:51], v[152:155], v[168:171], v[48:51]
	v_mfma_f32_16x16x32_bf16 v[48:51], v[156:159], v[172:175], v[48:51]
	v_mfma_f32_16x16x32_bf16 v[40:43], v[160:163], v[168:171], v[40:43]
	v_mfma_f32_16x16x32_bf16 v[40:43], v[164:167], v[172:175], v[40:43]
	v_mfma_f32_16x16x32_bf16 v[32:35], v[152:155], v[176:179], v[32:35]
	v_mfma_f32_16x16x32_bf16 v[32:35], v[156:159], v[180:183], v[32:35]
	v_mfma_f32_16x16x32_bf16 v[24:27], v[160:163], v[176:179], v[24:27]
	v_mfma_f32_16x16x32_bf16 v[24:27], v[164:167], v[180:183], v[24:27]
	v_mfma_f32_16x16x32_bf16 v[16:19], v[152:155], v[184:187], v[16:19]
	v_mfma_f32_16x16x32_bf16 v[16:19], v[156:159], v[188:191], v[16:19]
	v_mfma_f32_16x16x32_bf16 v[8:11], v[160:163], v[184:187], v[8:11]
	v_mfma_f32_16x16x32_bf16 v[8:11], v[164:167], v[188:191], v[8:11]
	v_mfma_f32_16x16x32_bf16 v[4:7], v[152:155], v[192:195], v[4:7]
	v_mfma_f32_16x16x32_bf16 v[4:7], v[156:159], v[200:203], v[4:7]
	v_mfma_f32_16x16x32_bf16 v[0:3], v[160:163], v[192:195], v[0:3]
	v_mfma_f32_16x16x32_bf16 v[0:3], v[164:167], v[200:203], v[0:3]
	s_barrier
	s_setprio 0
	s_add_i32 s70, 0, 0x18000
	v_add_u32_e32 v128, s70, v134
	s_add_i32 s71, 0, 0x1c000
	ds_read_b128 v[136:139], v128
	ds_read_b128 v[140:143], v128 offset:1024
	ds_read_b128 v[144:147], v128 offset:2048
	ds_read_b128 v[148:151], v128 offset:3072
	v_add_u32_e32 v128, s71, v134
	ds_read_b128 v[152:155], v128
	ds_read_b128 v[156:159], v128 offset:1024
	ds_read_b128 v[160:163], v128 offset:2048
	ds_read_b128 v[164:167], v128 offset:3072
	s_add_u32 s34, s34, 0x20000
	s_addc_u32 s35, s35, 0
	s_mov_b32 m0, s38
	ds_read_b128 v[168:171], v135 offset:32768
	ds_read_b128 v[172:175], v135 offset:33792
	ds_read_b128 v[176:179], v135 offset:34816
	ds_read_b128 v[180:183], v135 offset:35840
	ds_read_b128 v[184:187], v135 offset:36864
	ds_read_b128 v[188:191], v135 offset:37888
	ds_read_b128 v[192:195], v135 offset:38912
	ds_read_b128 v[200:203], v135 offset:39936
	s_nop 0
	global_load_lds_dwordx4 v133, s[34:35]
	s_mov_b32 m0, s39
	s_nop 0
	global_load_lds_dwordx4 v131, s[34:35]
	s_waitcnt vmcnt(8)
	s_waitcnt lgkmcnt(0)
	s_setprio 1
	s_barrier
	v_mfma_f32_16x16x32_bf16 v[124:127], v[136:139], v[168:171], v[124:127]
	v_mfma_f32_16x16x32_bf16 v[124:127], v[140:143], v[172:175], v[124:127]
	v_mfma_f32_16x16x32_bf16 v[120:123], v[144:147], v[168:171], v[120:123]
	v_mfma_f32_16x16x32_bf16 v[120:123], v[148:151], v[172:175], v[120:123]
	v_mfma_f32_16x16x32_bf16 v[116:119], v[136:139], v[176:179], v[116:119]
	v_mfma_f32_16x16x32_bf16 v[116:119], v[140:143], v[180:183], v[116:119]
	v_mfma_f32_16x16x32_bf16 v[108:111], v[144:147], v[176:179], v[108:111]
	v_mfma_f32_16x16x32_bf16 v[108:111], v[148:151], v[180:183], v[108:111]
	v_mfma_f32_16x16x32_bf16 v[100:103], v[136:139], v[184:187], v[100:103]
	v_mfma_f32_16x16x32_bf16 v[100:103], v[140:143], v[188:191], v[100:103]
	v_mfma_f32_16x16x32_bf16 v[92:95], v[144:147], v[184:187], v[92:95]
	v_mfma_f32_16x16x32_bf16 v[92:95], v[148:151], v[188:191], v[92:95]
	v_mfma_f32_16x16x32_bf16 v[84:87], v[136:139], v[192:195], v[84:87]
	v_mfma_f32_16x16x32_bf16 v[84:87], v[140:143], v[200:203], v[84:87]
	v_mfma_f32_16x16x32_bf16 v[76:79], v[144:147], v[192:195], v[76:79]
	v_mfma_f32_16x16x32_bf16 v[76:79], v[148:151], v[200:203], v[76:79]
	v_mfma_f32_16x16x32_bf16 v[112:115], v[152:155], v[168:171], v[112:115]
	v_mfma_f32_16x16x32_bf16 v[112:115], v[156:159], v[172:175], v[112:115]
	v_mfma_f32_16x16x32_bf16 v[104:107], v[160:163], v[168:171], v[104:107]
	v_mfma_f32_16x16x32_bf16 v[104:107], v[164:167], v[172:175], v[104:107]
	v_mfma_f32_16x16x32_bf16 v[96:99], v[152:155], v[176:179], v[96:99]
	v_mfma_f32_16x16x32_bf16 v[96:99], v[156:159], v[180:183], v[96:99]
	v_mfma_f32_16x16x32_bf16 v[88:91], v[160:163], v[176:179], v[88:91]
	v_mfma_f32_16x16x32_bf16 v[88:91], v[164:167], v[180:183], v[88:91]
	v_mfma_f32_16x16x32_bf16 v[80:83], v[152:155], v[184:187], v[80:83]
	v_mfma_f32_16x16x32_bf16 v[80:83], v[156:159], v[188:191], v[80:83]
	v_mfma_f32_16x16x32_bf16 v[72:75], v[160:163], v[184:187], v[72:75]
	v_mfma_f32_16x16x32_bf16 v[72:75], v[164:167], v[188:191], v[72:75]
	v_mfma_f32_16x16x32_bf16 v[68:71], v[152:155], v[192:195], v[68:71]
	v_mfma_f32_16x16x32_bf16 v[68:71], v[156:159], v[200:203], v[68:71]
	v_mfma_f32_16x16x32_bf16 v[64:67], v[160:163], v[192:195], v[64:67]
	v_mfma_f32_16x16x32_bf16 v[64:67], v[164:167], v[200:203], v[64:67]
	s_barrier
	s_setprio 0
	s_add_u32 s34, s30, 0x80
	s_addc_u32 s35, s31, 0
	s_add_i32 s70, s70, s97
	s_mov_b32 m0, s70
	ds_read_b128 v[168:171], v135 offset:49152
	ds_read_b128 v[172:175], v135 offset:50176
	ds_read_b128 v[176:179], v135 offset:51200
	ds_read_b128 v[180:183], v135 offset:52224
	ds_read_b128 v[184:187], v135 offset:53248
	ds_read_b128 v[188:191], v135 offset:54272
	ds_read_b128 v[192:195], v135 offset:55296
	ds_read_b128 v[200:203], v135 offset:56320
	s_nop 0
	global_load_lds_dwordx4 v132, s[34:35]
	s_add_i32 m0, s70, 0x2000
	s_add_u32 s30, s30, 0x20080
	s_addc_u32 s31, s31, 0
	global_load_lds_dwordx4 v130, s[34:35]
	s_add_i32 s34, s71, s97
	s_mov_b32 m0, s34
	s_nop 0
	global_load_lds_dwordx4 v132, s[30:31]
	s_add_i32 m0, s34, 0x2000
	s_nop 0
	global_load_lds_dwordx4 v130, s[30:31]
	s_mov_b32 m0, s44
	s_nop 0
	global_load_lds_dwordx4 v133, s[28:29]
	s_mov_b32 m0, s46
	s_nop 0
	global_load_lds_dwordx4 v131, s[28:29]
	s_waitcnt vmcnt(8)
	s_waitcnt lgkmcnt(0)
	s_setprio 1
	s_barrier
	v_mfma_f32_16x16x32_bf16 v[60:63], v[136:139], v[168:171], v[60:63]
	v_mfma_f32_16x16x32_bf16 v[60:63], v[140:143], v[172:175], v[60:63]
	v_mfma_f32_16x16x32_bf16 v[56:59], v[144:147], v[168:171], v[56:59]
	v_mfma_f32_16x16x32_bf16 v[56:59], v[148:151], v[172:175], v[56:59]
	v_mfma_f32_16x16x32_bf16 v[52:55], v[136:139], v[176:179], v[52:55]
	v_mfma_f32_16x16x32_bf16 v[52:55], v[140:143], v[180:183], v[52:55]
	v_mfma_f32_16x16x32_bf16 v[44:47], v[144:147], v[176:179], v[44:47]
	v_mfma_f32_16x16x32_bf16 v[44:47], v[148:151], v[180:183], v[44:47]
	v_mfma_f32_16x16x32_bf16 v[36:39], v[136:139], v[184:187], v[36:39]
	v_mfma_f32_16x16x32_bf16 v[36:39], v[140:143], v[188:191], v[36:39]
	v_mfma_f32_16x16x32_bf16 v[28:31], v[144:147], v[184:187], v[28:31]
	v_mfma_f32_16x16x32_bf16 v[28:31], v[148:151], v[188:191], v[28:31]
	v_mfma_f32_16x16x32_bf16 v[20:23], v[136:139], v[192:195], v[20:23]
	v_mfma_f32_16x16x32_bf16 v[20:23], v[140:143], v[200:203], v[20:23]
	v_mfma_f32_16x16x32_bf16 v[12:15], v[144:147], v[192:195], v[12:15]
	v_mfma_f32_16x16x32_bf16 v[12:15], v[148:151], v[200:203], v[12:15]
	v_mfma_f32_16x16x32_bf16 v[48:51], v[152:155], v[168:171], v[48:51]
	v_mfma_f32_16x16x32_bf16 v[48:51], v[156:159], v[172:175], v[48:51]
	v_mfma_f32_16x16x32_bf16 v[40:43], v[160:163], v[168:171], v[40:43]
	v_mfma_f32_16x16x32_bf16 v[40:43], v[164:167], v[172:175], v[40:43]
	v_mfma_f32_16x16x32_bf16 v[32:35], v[152:155], v[176:179], v[32:35]
	v_mfma_f32_16x16x32_bf16 v[32:35], v[156:159], v[180:183], v[32:35]
	v_mfma_f32_16x16x32_bf16 v[24:27], v[160:163], v[176:179], v[24:27]
	v_mfma_f32_16x16x32_bf16 v[24:27], v[164:167], v[180:183], v[24:27]
	v_mfma_f32_16x16x32_bf16 v[16:19], v[152:155], v[184:187], v[16:19]
	v_mfma_f32_16x16x32_bf16 v[16:19], v[156:159], v[188:191], v[16:19]
	v_mfma_f32_16x16x32_bf16 v[8:11], v[160:163], v[184:187], v[8:11]
	v_mfma_f32_16x16x32_bf16 v[8:11], v[164:167], v[188:191], v[8:11]
	v_mfma_f32_16x16x32_bf16 v[4:7], v[152:155], v[192:195], v[4:7]
	v_mfma_f32_16x16x32_bf16 v[4:7], v[156:159], v[200:203], v[4:7]
	v_mfma_f32_16x16x32_bf16 v[0:3], v[160:163], v[192:195], v[0:3]
	v_mfma_f32_16x16x32_bf16 v[0:3], v[164:167], v[200:203], v[0:3]
	s_barrier
	s_setprio 0
	s_add_i32 s69, s69, 2
	s_add_u32 s49, s49, 0x100
	s_addc_u32 s56, s56, 0
	s_add_u32 s57, s57, 0x100
	s_addc_u32 s65, s65, 0
	s_add_u32 s26, s26, 0x100
	s_addc_u32 s27, s27, 0
	s_cmp_gt_u32 s69, 5
	s_cbranch_scc0 .LBB0_397
	s_and_b64 vcc, exec, s[60:61]
	s_cbranch_vccz .LBB0_400
	s_barrier

.LBB0_527:
	s_cmp_eq_u32 s85, 28
	s_cselect_b32 s56, s5, s39
	s_cselect_b32 s57, s4, s69
	s_cselect_b32 s86, s37, s72
	s_cselect_b32 s87, s11, s74
	s_add_u32 s12, s56, 0x80
	s_addc_u32 s13, s57, 0
	s_add_i32 vcc_lo, 0, 0x10000
	s_add_i32 vcc_hi, 0, 0x14000
	v_add_u32_e32 v136, vcc_lo, v184
	v_add_u32_e32 v156, vcc_hi, v184
	ds_read_b128 v[104:107], v136
	ds_read_b128 v[108:111], v136 offset:1024
	ds_read_b128 v[132:135], v136 offset:2048
	ds_read_b128 v[136:139], v136 offset:3072
	ds_read_b128 v[144:147], v156
	ds_read_b128 v[148:151], v156 offset:1024
	ds_read_b128 v[152:155], v156 offset:2048
	ds_read_b128 v[156:159], v156 offset:3072
	s_mov_b64 s[8:9], s[16:17]
	s_add_i32 m0, s89, 0xc000
	ds_read_b128 v[160:163], v185
	ds_read_b128 v[164:167], v185 offset:1024
	ds_read_b128 v[168:171], v185 offset:2048
	ds_read_b128 v[172:175], v185 offset:3072
	ds_read_b128 v[186:189], v185 offset:4096
	ds_read_b128 v[190:193], v185 offset:5120
	ds_read_b128 v[200:203], v185 offset:6144
	ds_read_b128 v[204:207], v185 offset:7168
	s_nop 0
	global_load_lds_dwordx4 v179, s[8:9]
	s_add_i32 m0, s89, 0xe000
	s_nop 0
	global_load_lds_dwordx4 v182, s[8:9]
	s_waitcnt vmcnt(8)
	s_waitcnt lgkmcnt(0)
	s_setprio 1
	s_barrier
	v_mfma_f32_16x16x32_bf16 v[140:143], v[104:107], v[160:163], v[140:143]
	v_mfma_f32_16x16x32_bf16 v[140:143], v[108:111], v[164:167], v[140:143]
	v_mfma_f32_16x16x32_bf16 v[128:131], v[132:135], v[160:163], v[128:131]
	v_mfma_f32_16x16x32_bf16 v[128:131], v[136:139], v[164:167], v[128:131]
	v_mfma_f32_16x16x32_bf16 v[124:127], v[104:107], v[168:171], v[124:127]
	v_mfma_f32_16x16x32_bf16 v[124:127], v[108:111], v[172:175], v[124:127]
	v_mfma_f32_16x16x32_bf16 v[112:115], v[132:135], v[168:171], v[112:115]
	v_mfma_f32_16x16x32_bf16 v[112:115], v[136:139], v[172:175], v[112:115]
	v_mfma_f32_16x16x32_bf16 v[96:99], v[104:107], v[186:189], v[96:99]
	v_mfma_f32_16x16x32_bf16 v[96:99], v[108:111], v[190:193], v[96:99]
	v_mfma_f32_16x16x32_bf16 v[88:91], v[132:135], v[186:189], v[88:91]
	v_mfma_f32_16x16x32_bf16 v[88:91], v[136:139], v[190:193], v[88:91]
	v_mfma_f32_16x16x32_bf16 v[84:87], v[104:107], v[200:203], v[84:87]
	v_mfma_f32_16x16x32_bf16 v[84:87], v[108:111], v[204:207], v[84:87]
	v_mfma_f32_16x16x32_bf16 v[72:75], v[132:135], v[200:203], v[72:75]
	v_mfma_f32_16x16x32_bf16 v[72:75], v[136:139], v[204:207], v[72:75]
	v_mfma_f32_16x16x32_bf16 v[120:123], v[144:147], v[160:163], v[120:123]
	v_mfma_f32_16x16x32_bf16 v[120:123], v[148:151], v[164:167], v[120:123]
	v_mfma_f32_16x16x32_bf16 v[116:119], v[152:155], v[160:163], v[116:119]
	v_mfma_f32_16x16x32_bf16 v[116:119], v[156:159], v[164:167], v[116:119]
	v_mfma_f32_16x16x32_bf16 v[100:103], v[144:147], v[168:171], v[100:103]
	v_mfma_f32_16x16x32_bf16 v[100:103], v[148:151], v[172:175], v[100:103]
	v_mfma_f32_16x16x32_bf16 v[92:95], v[152:155], v[168:171], v[92:95]
	v_mfma_f32_16x16x32_bf16 v[92:95], v[156:159], v[172:175], v[92:95]
	v_mfma_f32_16x16x32_bf16 v[80:83], v[144:147], v[186:189], v[80:83]
	v_mfma_f32_16x16x32_bf16 v[80:83], v[148:151], v[190:193], v[80:83]
	v_mfma_f32_16x16x32_bf16 v[76:79], v[152:155], v[186:189], v[76:79]
	v_mfma_f32_16x16x32_bf16 v[76:79], v[156:159], v[190:193], v[76:79]
	v_mfma_f32_16x16x32_bf16 v[68:71], v[144:147], v[200:203], v[68:71]
	v_mfma_f32_16x16x32_bf16 v[68:71], v[148:151], v[204:207], v[68:71]
	v_mfma_f32_16x16x32_bf16 v[64:67], v[152:155], v[200:203], v[64:67]
	v_mfma_f32_16x16x32_bf16 v[64:67], v[156:159], v[204:207], v[64:67]
	s_barrier
	s_setprio 0
	s_add_i32 vcc_lo, vcc_lo, s97
	s_mov_b64 s[8:9], s[86:87]
	s_mov_b32 m0, vcc_lo
	ds_read_b128 v[160:163], v185 offset:16384
	ds_read_b128 v[164:167], v185 offset:17408
	ds_read_b128 v[168:171], v185 offset:18432
	ds_read_b128 v[172:175], v185 offset:19456
	ds_read_b128 v[186:189], v185 offset:20480
	ds_read_b128 v[190:193], v185 offset:21504
	ds_read_b128 v[200:203], v185 offset:22528
	ds_read_b128 v[204:207], v185 offset:23552
	s_nop 0
	global_load_lds_dwordx4 v181, s[8:9]
	s_add_i32 m0, vcc_lo, 0x2000
	s_nop 0
	global_load_lds_dwordx4 v183, s[8:9]
	s_add_u32 s8, s86, 0x80000
	s_addc_u32 s9, s87, 0
	s_add_i32 vcc_lo, vcc_hi, s97
	s_mov_b32 m0, vcc_lo
	s_nop 0
	global_load_lds_dwordx4 v181, s[8:9]
	s_add_i32 m0, vcc_lo, 0x2000
	s_nop 0
	global_load_lds_dwordx4 v183, s[8:9]
	s_mov_b64 s[8:9], s[56:57]
	s_mov_b32 m0, s89
	s_nop 0
	global_load_lds_dwordx4 v179, s[8:9]
	s_mov_b32 m0, s92
	s_nop 0
	global_load_lds_dwordx4 v182, s[8:9]
	s_waitcnt vmcnt(8)
	s_waitcnt lgkmcnt(0)
	s_setprio 1
	s_barrier
	v_mfma_f32_16x16x32_bf16 v[60:63], v[104:107], v[160:163], v[60:63]
	v_mfma_f32_16x16x32_bf16 v[60:63], v[108:111], v[164:167], v[60:63]
	v_mfma_f32_16x16x32_bf16 v[56:59], v[132:135], v[160:163], v[56:59]
	v_mfma_f32_16x16x32_bf16 v[56:59], v[136:139], v[164:167], v[56:59]
	v_mfma_f32_16x16x32_bf16 v[48:51], v[104:107], v[168:171], v[48:51]
	v_mfma_f32_16x16x32_bf16 v[48:51], v[108:111], v[172:175], v[48:51]
	v_mfma_f32_16x16x32_bf16 v[40:43], v[132:135], v[168:171], v[40:43]
	v_mfma_f32_16x16x32_bf16 v[40:43], v[136:139], v[172:175], v[40:43]
	v_mfma_f32_16x16x32_bf16 v[32:35], v[104:107], v[186:189], v[32:35]
	v_mfma_f32_16x16x32_bf16 v[32:35], v[108:111], v[190:193], v[32:35]
	v_mfma_f32_16x16x32_bf16 v[24:27], v[132:135], v[186:189], v[24:27]
	v_mfma_f32_16x16x32_bf16 v[24:27], v[136:139], v[190:193], v[24:27]
	v_mfma_f32_16x16x32_bf16 v[16:19], v[104:107], v[200:203], v[16:19]
	v_mfma_f32_16x16x32_bf16 v[16:19], v[108:111], v[204:207], v[16:19]
	v_mfma_f32_16x16x32_bf16 v[8:11], v[132:135], v[200:203], v[8:11]
	v_mfma_f32_16x16x32_bf16 v[8:11], v[136:139], v[204:207], v[8:11]
	v_mfma_f32_16x16x32_bf16 v[52:55], v[144:147], v[160:163], v[52:55]
	v_mfma_f32_16x16x32_bf16 v[52:55], v[148:151], v[164:167], v[52:55]
	v_mfma_f32_16x16x32_bf16 v[44:47], v[152:155], v[160:163], v[44:47]
	v_mfma_f32_16x16x32_bf16 v[44:47], v[156:159], v[164:167], v[44:47]
	v_mfma_f32_16x16x32_bf16 v[36:39], v[144:147], v[168:171], v[36:39]
	v_mfma_f32_16x16x32_bf16 v[36:39], v[148:151], v[172:175], v[36:39]
	v_mfma_f32_16x16x32_bf16 v[28:31], v[152:155], v[168:171], v[28:31]
	v_mfma_f32_16x16x32_bf16 v[28:31], v[156:159], v[172:175], v[28:31]
	v_mfma_f32_16x16x32_bf16 v[20:23], v[144:147], v[186:189], v[20:23]
	v_mfma_f32_16x16x32_bf16 v[20:23], v[148:151], v[190:193], v[20:23]
	v_mfma_f32_16x16x32_bf16 v[12:15], v[152:155], v[186:189], v[12:15]
	v_mfma_f32_16x16x32_bf16 v[12:15], v[156:159], v[190:193], v[12:15]
	v_mfma_f32_16x16x32_bf16 v[4:7], v[144:147], v[200:203], v[4:7]
	v_mfma_f32_16x16x32_bf16 v[4:7], v[148:151], v[204:207], v[4:7]
	v_mfma_f32_16x16x32_bf16 v[0:3], v[152:155], v[200:203], v[0:3]
	v_mfma_f32_16x16x32_bf16 v[0:3], v[156:159], v[204:207], v[0:3]
	s_barrier
	s_setprio 0
	s_add_i32 vcc_lo, 0, 0x18000
	s_add_i32 vcc_hi, 0, 0x1c000
	v_add_u32_e32 v136, vcc_lo, v184
	v_add_u32_e32 v156, vcc_hi, v184
	ds_read_b128 v[104:107], v136
	ds_read_b128 v[108:111], v136 offset:1024
	ds_read_b128 v[132:135], v136 offset:2048
	ds_read_b128 v[136:139], v136 offset:3072
	ds_read_b128 v[144:147], v156
	ds_read_b128 v[148:151], v156 offset:1024
	ds_read_b128 v[152:155], v156 offset:2048
	ds_read_b128 v[156:159], v156 offset:3072
	s_add_u32 s8, s56, 0x80000
	s_addc_u32 s9, s57, 0
	s_mov_b32 m0, s93
	ds_read_b128 v[160:163], v185 offset:32768
	ds_read_b128 v[164:167], v185 offset:33792
	ds_read_b128 v[168:171], v185 offset:34816
	ds_read_b128 v[172:175], v185 offset:35840
	ds_read_b128 v[186:189], v185 offset:36864
	ds_read_b128 v[190:193], v185 offset:37888
	ds_read_b128 v[200:203], v185 offset:38912
	ds_read_b128 v[204:207], v185 offset:39936
	s_nop 0
	global_load_lds_dwordx4 v179, s[8:9]
	s_mov_b32 m0, s48
	s_nop 0
	global_load_lds_dwordx4 v182, s[8:9]
	s_waitcnt vmcnt(8)
	s_waitcnt lgkmcnt(0)
	s_setprio 1
	s_barrier
	v_mfma_f32_16x16x32_bf16 v[140:143], v[104:107], v[160:163], v[140:143]
	v_mfma_f32_16x16x32_bf16 v[140:143], v[108:111], v[164:167], v[140:143]
	v_mfma_f32_16x16x32_bf16 v[128:131], v[132:135], v[160:163], v[128:131]
	v_mfma_f32_16x16x32_bf16 v[128:131], v[136:139], v[164:167], v[128:131]
	v_mfma_f32_16x16x32_bf16 v[124:127], v[104:107], v[168:171], v[124:127]
	v_mfma_f32_16x16x32_bf16 v[124:127], v[108:111], v[172:175], v[124:127]
	v_mfma_f32_16x16x32_bf16 v[112:115], v[132:135], v[168:171], v[112:115]
	v_mfma_f32_16x16x32_bf16 v[112:115], v[136:139], v[172:175], v[112:115]
	v_mfma_f32_16x16x32_bf16 v[96:99], v[104:107], v[186:189], v[96:99]
	v_mfma_f32_16x16x32_bf16 v[96:99], v[108:111], v[190:193], v[96:99]
	v_mfma_f32_16x16x32_bf16 v[88:91], v[132:135], v[186:189], v[88:91]
	v_mfma_f32_16x16x32_bf16 v[88:91], v[136:139], v[190:193], v[88:91]
	v_mfma_f32_16x16x32_bf16 v[84:87], v[104:107], v[200:203], v[84:87]
	v_mfma_f32_16x16x32_bf16 v[84:87], v[108:111], v[204:207], v[84:87]
	v_mfma_f32_16x16x32_bf16 v[72:75], v[132:135], v[200:203], v[72:75]
	v_mfma_f32_16x16x32_bf16 v[72:75], v[136:139], v[204:207], v[72:75]
	v_mfma_f32_16x16x32_bf16 v[120:123], v[144:147], v[160:163], v[120:123]
	v_mfma_f32_16x16x32_bf16 v[120:123], v[148:151], v[164:167], v[120:123]
	v_mfma_f32_16x16x32_bf16 v[116:119], v[152:155], v[160:163], v[116:119]
	v_mfma_f32_16x16x32_bf16 v[116:119], v[156:159], v[164:167], v[116:119]
	v_mfma_f32_16x16x32_bf16 v[100:103], v[144:147], v[168:171], v[100:103]
	v_mfma_f32_16x16x32_bf16 v[100:103], v[148:151], v[172:175], v[100:103]
	v_mfma_f32_16x16x32_bf16 v[92:95], v[152:155], v[168:171], v[92:95]
	v_mfma_f32_16x16x32_bf16 v[92:95], v[156:159], v[172:175], v[92:95]
	v_mfma_f32_16x16x32_bf16 v[80:83], v[144:147], v[186:189], v[80:83]
	v_mfma_f32_16x16x32_bf16 v[80:83], v[148:151], v[190:193], v[80:83]
	v_mfma_f32_16x16x32_bf16 v[76:79], v[152:155], v[186:189], v[76:79]
	v_mfma_f32_16x16x32_bf16 v[76:79], v[156:159], v[190:193], v[76:79]
	v_mfma_f32_16x16x32_bf16 v[68:71], v[144:147], v[200:203], v[68:71]
	v_mfma_f32_16x16x32_bf16 v[68:71], v[148:151], v[204:207], v[68:71]
	v_mfma_f32_16x16x32_bf16 v[64:67], v[152:155], v[200:203], v[64:67]
	v_mfma_f32_16x16x32_bf16 v[64:67], v[156:159], v[204:207], v[64:67]
	s_barrier
	s_setprio 0
	s_add_u32 s8, s86, 0x80
	s_addc_u32 s9, s87, 0
	s_add_i32 s56, vcc_lo, s97
	s_mov_b32 m0, s56
	ds_read_b128 v[160:163], v185 offset:49152
	ds_read_b128 v[164:167], v185 offset:50176
	ds_read_b128 v[168:171], v185 offset:51200
	ds_read_b128 v[172:175], v185 offset:52224
	ds_read_b128 v[186:189], v185 offset:53248
	ds_read_b128 v[190:193], v185 offset:54272
	ds_read_b128 v[200:203], v185 offset:55296
	ds_read_b128 v[204:207], v185 offset:56320
	s_nop 0
	global_load_lds_dwordx4 v181, s[8:9]
	s_add_i32 m0, s56, 0x2000
	s_nop 0
	global_load_lds_dwordx4 v183, s[8:9]
	s_add_u32 s8, s86, 0x80080
	s_addc_u32 s9, s87, 0
	s_add_i32 s56, vcc_hi, s97
	s_mov_b32 m0, s56
	s_nop 0
	global_load_lds_dwordx4 v181, s[8:9]
	s_add_i32 m0, s56, 0x2000
	s_nop 0
	global_load_lds_dwordx4 v183, s[8:9]
	s_mov_b32 m0, s46
	s_nop 0
	global_load_lds_dwordx4 v179, s[12:13]
	s_mov_b32 m0, s70
	s_nop 0
	global_load_lds_dwordx4 v182, s[12:13]
	s_waitcnt vmcnt(8)
	s_waitcnt lgkmcnt(0)
	s_setprio 1
	s_barrier
	v_mfma_f32_16x16x32_bf16 v[60:63], v[104:107], v[160:163], v[60:63]
	v_mfma_f32_16x16x32_bf16 v[60:63], v[108:111], v[164:167], v[60:63]
	v_mfma_f32_16x16x32_bf16 v[56:59], v[132:135], v[160:163], v[56:59]
	v_mfma_f32_16x16x32_bf16 v[56:59], v[136:139], v[164:167], v[56:59]
	v_mfma_f32_16x16x32_bf16 v[48:51], v[104:107], v[168:171], v[48:51]
	v_mfma_f32_16x16x32_bf16 v[48:51], v[108:111], v[172:175], v[48:51]
	v_mfma_f32_16x16x32_bf16 v[40:43], v[132:135], v[168:171], v[40:43]
	v_mfma_f32_16x16x32_bf16 v[40:43], v[136:139], v[172:175], v[40:43]
	v_mfma_f32_16x16x32_bf16 v[32:35], v[104:107], v[186:189], v[32:35]
	v_mfma_f32_16x16x32_bf16 v[32:35], v[108:111], v[190:193], v[32:35]
	v_mfma_f32_16x16x32_bf16 v[24:27], v[132:135], v[186:189], v[24:27]
	v_mfma_f32_16x16x32_bf16 v[24:27], v[136:139], v[190:193], v[24:27]
	v_mfma_f32_16x16x32_bf16 v[16:19], v[104:107], v[200:203], v[16:19]
	v_mfma_f32_16x16x32_bf16 v[16:19], v[108:111], v[204:207], v[16:19]
	v_mfma_f32_16x16x32_bf16 v[8:11], v[132:135], v[200:203], v[8:11]
	v_mfma_f32_16x16x32_bf16 v[8:11], v[136:139], v[204:207], v[8:11]
	v_mfma_f32_16x16x32_bf16 v[52:55], v[144:147], v[160:163], v[52:55]
	v_mfma_f32_16x16x32_bf16 v[52:55], v[148:151], v[164:167], v[52:55]
	v_mfma_f32_16x16x32_bf16 v[44:47], v[152:155], v[160:163], v[44:47]
	v_mfma_f32_16x16x32_bf16 v[44:47], v[156:159], v[164:167], v[44:47]
	v_mfma_f32_16x16x32_bf16 v[36:39], v[144:147], v[168:171], v[36:39]
	v_mfma_f32_16x16x32_bf16 v[36:39], v[148:151], v[172:175], v[36:39]
	v_mfma_f32_16x16x32_bf16 v[28:31], v[152:155], v[168:171], v[28:31]
	v_mfma_f32_16x16x32_bf16 v[28:31], v[156:159], v[172:175], v[28:31]
	v_mfma_f32_16x16x32_bf16 v[20:23], v[144:147], v[186:189], v[20:23]
	v_mfma_f32_16x16x32_bf16 v[20:23], v[148:151], v[190:193], v[20:23]
	v_mfma_f32_16x16x32_bf16 v[12:15], v[152:155], v[186:189], v[12:15]
	v_mfma_f32_16x16x32_bf16 v[12:15], v[156:159], v[190:193], v[12:15]
	v_mfma_f32_16x16x32_bf16 v[4:7], v[144:147], v[200:203], v[4:7]
	v_mfma_f32_16x16x32_bf16 v[4:7], v[148:151], v[204:207], v[4:7]
	v_mfma_f32_16x16x32_bf16 v[0:3], v[152:155], v[200:203], v[0:3]
	v_mfma_f32_16x16x32_bf16 v[0:3], v[156:159], v[204:207], v[0:3]
	s_barrier
	s_setprio 0
	s_add_i32 s85, s85, 2
	s_add_u32 s39, s39, 0x100
	s_addc_u32 s69, s69, 0
	s_add_u32 s72, s72, 0x100
	s_addc_u32 s74, s74, 0
	s_add_u32 s16, s16, 0x100
	s_addc_u32 s17, s17, 0
	s_cmp_gt_u32 s85, 29
	s_cbranch_scc0 .LBB0_527
	s_and_b64 vcc, exec, s[60:61]
	s_cbranch_vccz .LBB0_530
	s_barrier

.LBB0_604:
	s_cmp_eq_u32 s21, 4
	s_cselect_b32 s38, s22, s4
	s_cselect_b32 s39, s23, s5
	s_cselect_b32 s36, s24, s15
	s_cselect_b32 s37, s25, s17
	s_add_u32 s34, s38, 0x80
	s_addc_u32 s35, s39, 0
	s_add_i32 s65, 0, 0x10000
	s_add_i32 s69, 0, 0x14000
	v_add_u32_e32 v132, s65, v154
	v_add_u32_e32 v148, s69, v154
	ds_read_b128 v[112:115], v132
	ds_read_b128 v[120:123], v132 offset:1024
	ds_read_b128 v[128:131], v132 offset:2048
	ds_read_b128 v[132:135], v132 offset:3072
	ds_read_b128 v[144:147], v148
	ds_read_b128 v[156:159], v148 offset:1024
	ds_read_b128 v[160:163], v148 offset:2048
	ds_read_b128 v[164:167], v148 offset:3072
	s_add_u32 s70, s4, 0x7ff80
	s_addc_u32 s71, s5, 0
	s_add_i32 m0, s27, 0xc000
	ds_read_b128 v[168:171], v155
	ds_read_b128 v[172:175], v155 offset:1024
	ds_read_b128 v[176:179], v155 offset:2048
	ds_read_b128 v[180:183], v155 offset:3072
	ds_read_b128 v[184:187], v155 offset:4096
	ds_read_b128 v[188:191], v155 offset:5120
	ds_read_b128 v[192:195], v155 offset:6144
	ds_read_b128 v[200:203], v155 offset:7168
	s_nop 0
	global_load_lds_dwordx4 v151, s[70:71]
	s_add_i32 m0, s27, 0xe000
	s_nop 0
	global_load_lds_dwordx4 v150, s[70:71]
	s_waitcnt vmcnt(8)
	s_waitcnt lgkmcnt(0)
	s_setprio 1
	s_barrier
	v_mfma_f32_16x16x32_bf16 v[140:143], v[112:115], v[168:171], v[140:143]
	v_mfma_f32_16x16x32_bf16 v[140:143], v[120:123], v[172:175], v[140:143]
	v_mfma_f32_16x16x32_bf16 v[136:139], v[128:131], v[168:171], v[136:139]
	v_mfma_f32_16x16x32_bf16 v[136:139], v[132:135], v[172:175], v[136:139]
	v_mfma_f32_16x16x32_bf16 v[108:111], v[112:115], v[176:179], v[108:111]
	v_mfma_f32_16x16x32_bf16 v[108:111], v[120:123], v[180:183], v[108:111]
	v_mfma_f32_16x16x32_bf16 v[104:107], v[128:131], v[176:179], v[104:107]
	v_mfma_f32_16x16x32_bf16 v[104:107], v[132:135], v[180:183], v[104:107]
	v_mfma_f32_16x16x32_bf16 v[92:95], v[112:115], v[184:187], v[92:95]
	v_mfma_f32_16x16x32_bf16 v[92:95], v[120:123], v[188:191], v[92:95]
	v_mfma_f32_16x16x32_bf16 v[88:91], v[128:131], v[184:187], v[88:91]
	v_mfma_f32_16x16x32_bf16 v[88:91], v[132:135], v[188:191], v[88:91]
	v_mfma_f32_16x16x32_bf16 v[76:79], v[112:115], v[192:195], v[76:79]
	v_mfma_f32_16x16x32_bf16 v[76:79], v[120:123], v[200:203], v[76:79]
	v_mfma_f32_16x16x32_bf16 v[72:75], v[128:131], v[192:195], v[72:75]
	v_mfma_f32_16x16x32_bf16 v[72:75], v[132:135], v[200:203], v[72:75]
	v_mfma_f32_16x16x32_bf16 v[124:127], v[144:147], v[168:171], v[124:127]
	v_mfma_f32_16x16x32_bf16 v[124:127], v[156:159], v[172:175], v[124:127]
	v_mfma_f32_16x16x32_bf16 v[116:119], v[160:163], v[168:171], v[116:119]
	v_mfma_f32_16x16x32_bf16 v[116:119], v[164:167], v[172:175], v[116:119]
	v_mfma_f32_16x16x32_bf16 v[100:103], v[144:147], v[176:179], v[100:103]
	v_mfma_f32_16x16x32_bf16 v[100:103], v[156:159], v[180:183], v[100:103]
	v_mfma_f32_16x16x32_bf16 v[96:99], v[160:163], v[176:179], v[96:99]
	v_mfma_f32_16x16x32_bf16 v[96:99], v[164:167], v[180:183], v[96:99]
	v_mfma_f32_16x16x32_bf16 v[84:87], v[144:147], v[184:187], v[84:87]
	v_mfma_f32_16x16x32_bf16 v[84:87], v[156:159], v[188:191], v[84:87]
	v_mfma_f32_16x16x32_bf16 v[80:83], v[160:163], v[184:187], v[80:83]
	v_mfma_f32_16x16x32_bf16 v[80:83], v[164:167], v[188:191], v[80:83]
	v_mfma_f32_16x16x32_bf16 v[68:71], v[144:147], v[192:195], v[68:71]
	v_mfma_f32_16x16x32_bf16 v[68:71], v[156:159], v[200:203], v[68:71]
	v_mfma_f32_16x16x32_bf16 v[64:67], v[160:163], v[192:195], v[64:67]
	v_mfma_f32_16x16x32_bf16 v[64:67], v[164:167], v[200:203], v[64:67]
	s_barrier
	s_setprio 0
	s_add_i32 s65, s65, s97
	s_mov_b64 s[70:71], s[36:37]
	s_mov_b32 m0, s65
	ds_read_b128 v[168:171], v155 offset:16384
	ds_read_b128 v[172:175], v155 offset:17408
	ds_read_b128 v[176:179], v155 offset:18432
	ds_read_b128 v[180:183], v155 offset:19456
	ds_read_b128 v[184:187], v155 offset:20480
	ds_read_b128 v[188:191], v155 offset:21504
	ds_read_b128 v[192:195], v155 offset:22528
	ds_read_b128 v[200:203], v155 offset:23552
	s_nop 0
	global_load_lds_dwordx4 v152, s[70:71]
	s_add_i32 m0, s65, 0x2000
	s_nop 0
	global_load_lds_dwordx4 v153, s[70:71]
	s_add_u32 s70, s36, 0x80000
	s_addc_u32 s71, s37, 0
	s_add_i32 s65, s69, s97
	s_mov_b32 m0, s65
	s_nop 0
	global_load_lds_dwordx4 v152, s[70:71]
	s_add_i32 m0, s65, 0x2000
	s_nop 0
	global_load_lds_dwordx4 v153, s[70:71]
	s_mov_b64 s[70:71], s[38:39]
	s_mov_b32 m0, s27
	s_nop 0
	global_load_lds_dwordx4 v151, s[70:71]
	s_mov_b32 m0, s29
	s_nop 0
	global_load_lds_dwordx4 v150, s[70:71]
	s_waitcnt vmcnt(8)
	s_waitcnt lgkmcnt(0)
	s_setprio 1
	s_barrier
	v_mfma_f32_16x16x32_bf16 v[60:63], v[112:115], v[168:171], v[60:63]
	v_mfma_f32_16x16x32_bf16 v[60:63], v[120:123], v[172:175], v[60:63]
	v_mfma_f32_16x16x32_bf16 v[56:59], v[128:131], v[168:171], v[56:59]
	v_mfma_f32_16x16x32_bf16 v[56:59], v[132:135], v[172:175], v[56:59]
	v_mfma_f32_16x16x32_bf16 v[52:55], v[112:115], v[176:179], v[52:55]
	v_mfma_f32_16x16x32_bf16 v[52:55], v[120:123], v[180:183], v[52:55]
	v_mfma_f32_16x16x32_bf16 v[44:47], v[128:131], v[176:179], v[44:47]
	v_mfma_f32_16x16x32_bf16 v[44:47], v[132:135], v[180:183], v[44:47]
	v_mfma_f32_16x16x32_bf16 v[36:39], v[112:115], v[184:187], v[36:39]
	v_mfma_f32_16x16x32_bf16 v[36:39], v[120:123], v[188:191], v[36:39]
	v_mfma_f32_16x16x32_bf16 v[28:31], v[128:131], v[184:187], v[28:31]
	v_mfma_f32_16x16x32_bf16 v[28:31], v[132:135], v[188:191], v[28:31]
	v_mfma_f32_16x16x32_bf16 v[20:23], v[112:115], v[192:195], v[20:23]
	v_mfma_f32_16x16x32_bf16 v[20:23], v[120:123], v[200:203], v[20:23]
	v_mfma_f32_16x16x32_bf16 v[8:11], v[128:131], v[192:195], v[8:11]
	v_mfma_f32_16x16x32_bf16 v[8:11], v[132:135], v[200:203], v[8:11]
	v_mfma_f32_16x16x32_bf16 v[48:51], v[144:147], v[168:171], v[48:51]
	v_mfma_f32_16x16x32_bf16 v[48:51], v[156:159], v[172:175], v[48:51]
	v_mfma_f32_16x16x32_bf16 v[40:43], v[160:163], v[168:171], v[40:43]
	v_mfma_f32_16x16x32_bf16 v[40:43], v[164:167], v[172:175], v[40:43]
	v_mfma_f32_16x16x32_bf16 v[32:35], v[144:147], v[176:179], v[32:35]
	v_mfma_f32_16x16x32_bf16 v[32:35], v[156:159], v[180:183], v[32:35]
	v_mfma_f32_16x16x32_bf16 v[24:27], v[160:163], v[176:179], v[24:27]
	v_mfma_f32_16x16x32_bf16 v[24:27], v[164:167], v[180:183], v[24:27]
	v_mfma_f32_16x16x32_bf16 v[16:19], v[144:147], v[184:187], v[16:19]
	v_mfma_f32_16x16x32_bf16 v[16:19], v[156:159], v[188:191], v[16:19]
	v_mfma_f32_16x16x32_bf16 v[12:15], v[160:163], v[184:187], v[12:15]
	v_mfma_f32_16x16x32_bf16 v[12:15], v[164:167], v[188:191], v[12:15]
	v_mfma_f32_16x16x32_bf16 v[4:7], v[144:147], v[192:195], v[4:7]
	v_mfma_f32_16x16x32_bf16 v[4:7], v[156:159], v[200:203], v[4:7]
	v_mfma_f32_16x16x32_bf16 v[0:3], v[160:163], v[192:195], v[0:3]
	v_mfma_f32_16x16x32_bf16 v[0:3], v[164:167], v[200:203], v[0:3]
	s_barrier
	s_setprio 0
	s_add_i32 s65, 0, 0x18000
	s_add_i32 s69, 0, 0x1c000
	v_add_u32_e32 v132, s65, v154
	v_add_u32_e32 v148, s69, v154
	ds_read_b128 v[112:115], v132
	ds_read_b128 v[120:123], v132 offset:1024
	ds_read_b128 v[128:131], v132 offset:2048
	ds_read_b128 v[132:135], v132 offset:3072
	ds_read_b128 v[144:147], v148
	ds_read_b128 v[156:159], v148 offset:1024
	ds_read_b128 v[160:163], v148 offset:2048
	ds_read_b128 v[164:167], v148 offset:3072
	s_add_u32 s38, s38, 0x80000
	s_addc_u32 s39, s39, 0
	s_mov_b32 m0, s31
	ds_read_b128 v[168:171], v155 offset:32768
	ds_read_b128 v[172:175], v155 offset:33792
	ds_read_b128 v[176:179], v155 offset:34816
	ds_read_b128 v[180:183], v155 offset:35840
	ds_read_b128 v[184:187], v155 offset:36864
	ds_read_b128 v[188:191], v155 offset:37888
	ds_read_b128 v[192:195], v155 offset:38912
	ds_read_b128 v[200:203], v155 offset:39936
	s_nop 0
	global_load_lds_dwordx4 v151, s[38:39]
	s_mov_b32 m0, s48
	s_nop 0
	global_load_lds_dwordx4 v150, s[38:39]
	s_waitcnt vmcnt(8)
	s_waitcnt lgkmcnt(0)
	s_setprio 1
	s_barrier
	v_mfma_f32_16x16x32_bf16 v[140:143], v[112:115], v[168:171], v[140:143]
	v_mfma_f32_16x16x32_bf16 v[140:143], v[120:123], v[172:175], v[140:143]
	v_mfma_f32_16x16x32_bf16 v[136:139], v[128:131], v[168:171], v[136:139]
	v_mfma_f32_16x16x32_bf16 v[136:139], v[132:135], v[172:175], v[136:139]
	v_mfma_f32_16x16x32_bf16 v[108:111], v[112:115], v[176:179], v[108:111]
	v_mfma_f32_16x16x32_bf16 v[108:111], v[120:123], v[180:183], v[108:111]
	v_mfma_f32_16x16x32_bf16 v[104:107], v[128:131], v[176:179], v[104:107]
	v_mfma_f32_16x16x32_bf16 v[104:107], v[132:135], v[180:183], v[104:107]
	v_mfma_f32_16x16x32_bf16 v[92:95], v[112:115], v[184:187], v[92:95]
	v_mfma_f32_16x16x32_bf16 v[92:95], v[120:123], v[188:191], v[92:95]
	v_mfma_f32_16x16x32_bf16 v[88:91], v[128:131], v[184:187], v[88:91]
	v_mfma_f32_16x16x32_bf16 v[88:91], v[132:135], v[188:191], v[88:91]
	v_mfma_f32_16x16x32_bf16 v[76:79], v[112:115], v[192:195], v[76:79]
	v_mfma_f32_16x16x32_bf16 v[76:79], v[120:123], v[200:203], v[76:79]
	v_mfma_f32_16x16x32_bf16 v[72:75], v[128:131], v[192:195], v[72:75]
	v_mfma_f32_16x16x32_bf16 v[72:75], v[132:135], v[200:203], v[72:75]
	v_mfma_f32_16x16x32_bf16 v[124:127], v[144:147], v[168:171], v[124:127]
	v_mfma_f32_16x16x32_bf16 v[124:127], v[156:159], v[172:175], v[124:127]
	v_mfma_f32_16x16x32_bf16 v[116:119], v[160:163], v[168:171], v[116:119]
	v_mfma_f32_16x16x32_bf16 v[116:119], v[164:167], v[172:175], v[116:119]
	v_mfma_f32_16x16x32_bf16 v[100:103], v[144:147], v[176:179], v[100:103]
	v_mfma_f32_16x16x32_bf16 v[100:103], v[156:159], v[180:183], v[100:103]
	v_mfma_f32_16x16x32_bf16 v[96:99], v[160:163], v[176:179], v[96:99]
	v_mfma_f32_16x16x32_bf16 v[96:99], v[164:167], v[180:183], v[96:99]
	v_mfma_f32_16x16x32_bf16 v[84:87], v[144:147], v[184:187], v[84:87]
	v_mfma_f32_16x16x32_bf16 v[84:87], v[156:159], v[188:191], v[84:87]
	v_mfma_f32_16x16x32_bf16 v[80:83], v[160:163], v[184:187], v[80:83]
	v_mfma_f32_16x16x32_bf16 v[80:83], v[164:167], v[188:191], v[80:83]
	v_mfma_f32_16x16x32_bf16 v[68:71], v[144:147], v[192:195], v[68:71]
	v_mfma_f32_16x16x32_bf16 v[68:71], v[156:159], v[200:203], v[68:71]
	v_mfma_f32_16x16x32_bf16 v[64:67], v[160:163], v[192:195], v[64:67]
	v_mfma_f32_16x16x32_bf16 v[64:67], v[164:167], v[200:203], v[64:67]
	s_barrier
	s_setprio 0
	s_add_u32 s38, s36, 0x80
	s_addc_u32 s39, s37, 0
	s_add_i32 s65, s65, s97
	s_mov_b32 m0, s65
	ds_read_b128 v[168:171], v155 offset:49152
	ds_read_b128 v[172:175], v155 offset:50176
	ds_read_b128 v[176:179], v155 offset:51200
	ds_read_b128 v[180:183], v155 offset:52224
	ds_read_b128 v[184:187], v155 offset:53248
	ds_read_b128 v[188:191], v155 offset:54272
	ds_read_b128 v[192:195], v155 offset:55296
	ds_read_b128 v[200:203], v155 offset:56320
	s_nop 0
	global_load_lds_dwordx4 v152, s[38:39]
	s_add_i32 m0, s65, 0x2000
	s_add_u32 s36, s36, 0x80080
	s_addc_u32 s37, s37, 0
	global_load_lds_dwordx4 v153, s[38:39]
	s_add_i32 s38, s69, s97
	s_mov_b32 m0, s38
	s_nop 0
	global_load_lds_dwordx4 v152, s[36:37]
	s_add_i32 m0, s38, 0x2000
	s_nop 0
	global_load_lds_dwordx4 v153, s[36:37]
	s_mov_b32 m0, s49
	s_nop 0
	global_load_lds_dwordx4 v151, s[34:35]
	s_mov_b32 m0, s56
	s_nop 0
	global_load_lds_dwordx4 v150, s[34:35]
	s_waitcnt vmcnt(8)
	s_waitcnt lgkmcnt(0)
	s_setprio 1
	s_barrier
	v_mfma_f32_16x16x32_bf16 v[60:63], v[112:115], v[168:171], v[60:63]
	v_mfma_f32_16x16x32_bf16 v[60:63], v[120:123], v[172:175], v[60:63]
	v_mfma_f32_16x16x32_bf16 v[56:59], v[128:131], v[168:171], v[56:59]
	v_mfma_f32_16x16x32_bf16 v[56:59], v[132:135], v[172:175], v[56:59]
	v_mfma_f32_16x16x32_bf16 v[52:55], v[112:115], v[176:179], v[52:55]
	v_mfma_f32_16x16x32_bf16 v[52:55], v[120:123], v[180:183], v[52:55]
	v_mfma_f32_16x16x32_bf16 v[44:47], v[128:131], v[176:179], v[44:47]
	v_mfma_f32_16x16x32_bf16 v[44:47], v[132:135], v[180:183], v[44:47]
	v_mfma_f32_16x16x32_bf16 v[36:39], v[112:115], v[184:187], v[36:39]
	v_mfma_f32_16x16x32_bf16 v[36:39], v[120:123], v[188:191], v[36:39]
	v_mfma_f32_16x16x32_bf16 v[28:31], v[128:131], v[184:187], v[28:31]
	v_mfma_f32_16x16x32_bf16 v[28:31], v[132:135], v[188:191], v[28:31]
	v_mfma_f32_16x16x32_bf16 v[20:23], v[112:115], v[192:195], v[20:23]
	v_mfma_f32_16x16x32_bf16 v[20:23], v[120:123], v[200:203], v[20:23]
	v_mfma_f32_16x16x32_bf16 v[8:11], v[128:131], v[192:195], v[8:11]
	v_mfma_f32_16x16x32_bf16 v[8:11], v[132:135], v[200:203], v[8:11]
	v_mfma_f32_16x16x32_bf16 v[48:51], v[144:147], v[168:171], v[48:51]
	v_mfma_f32_16x16x32_bf16 v[48:51], v[156:159], v[172:175], v[48:51]
	v_mfma_f32_16x16x32_bf16 v[40:43], v[160:163], v[168:171], v[40:43]
	v_mfma_f32_16x16x32_bf16 v[40:43], v[164:167], v[172:175], v[40:43]
	v_mfma_f32_16x16x32_bf16 v[32:35], v[144:147], v[176:179], v[32:35]
	v_mfma_f32_16x16x32_bf16 v[32:35], v[156:159], v[180:183], v[32:35]
	v_mfma_f32_16x16x32_bf16 v[24:27], v[160:163], v[176:179], v[24:27]
	v_mfma_f32_16x16x32_bf16 v[24:27], v[164:167], v[180:183], v[24:27]
	v_mfma_f32_16x16x32_bf16 v[16:19], v[144:147], v[184:187], v[16:19]
	v_mfma_f32_16x16x32_bf16 v[16:19], v[156:159], v[188:191], v[16:19]
	v_mfma_f32_16x16x32_bf16 v[12:15], v[160:163], v[184:187], v[12:15]
	v_mfma_f32_16x16x32_bf16 v[12:15], v[164:167], v[188:191], v[12:15]
	v_mfma_f32_16x16x32_bf16 v[4:7], v[144:147], v[192:195], v[4:7]
	v_mfma_f32_16x16x32_bf16 v[4:7], v[156:159], v[200:203], v[4:7]
	v_mfma_f32_16x16x32_bf16 v[0:3], v[160:163], v[192:195], v[0:3]
	v_mfma_f32_16x16x32_bf16 v[0:3], v[164:167], v[200:203], v[0:3]
	s_barrier
	s_setprio 0
	s_add_i32 s21, s21, 2
	s_add_u32 s4, s4, 0x100
	s_addc_u32 s5, s5, 0
	s_add_u32 s15, s15, 0x100
	s_addc_u32 s17, s17, 0
	s_cmp_gt_u32 s21, 5
	s_cbranch_scc0 .LBB0_604
	s_and_b64 vcc, exec, s[60:61]
	s_cbranch_vccz .LBB0_607
	s_barrier

.LBB0_676:
	s_add_u32 s30, s28, 0x100
	s_addc_u32 s31, s29, 0
	s_cmp_eq_u32 s69, 28
	s_cselect_b32 s38, s5, s30
	s_cselect_b32 s39, s4, s31
	s_cselect_b32 s36, s17, s21
	s_cselect_b32 s37, s13, s27
	s_add_u32 s34, s38, 0x80
	s_addc_u32 s35, s39, 0
	s_add_i32 s74, 0, 0x10000
	s_add_i32 s84, 0, 0x14000
	v_add_u32_e32 v140, s74, v150
	v_add_u32_e32 v144, s84, v150
	ds_read_b128 v[128:131], v140
	ds_read_b128 v[132:135], v140 offset:1024
	ds_read_b128 v[136:139], v140 offset:2048
	ds_read_b128 v[140:143], v140 offset:3072
	ds_read_b128 v[152:155], v144
	ds_read_b128 v[156:159], v144 offset:1024
	ds_read_b128 v[160:163], v144 offset:2048
	ds_read_b128 v[164:167], v144 offset:3072
	s_add_u32 s28, s28, 0x80080
	s_addc_u32 s29, s29, 0
	s_add_i32 m0, s48, 0xc000
	ds_read_b128 v[168:171], v151
	ds_read_b128 v[172:175], v151 offset:1024
	ds_read_b128 v[176:179], v151 offset:2048
	ds_read_b128 v[180:183], v151 offset:3072
	ds_read_b128 v[184:187], v151 offset:4096
	ds_read_b128 v[188:191], v151 offset:5120
	ds_read_b128 v[192:195], v151 offset:6144
	ds_read_b128 v[200:203], v151 offset:7168
	s_nop 0
	global_load_lds_dwordx4 v146, s[28:29]
	s_add_i32 m0, s48, 0xe000
	s_nop 0
	global_load_lds_dwordx4 v148, s[28:29]
	s_waitcnt vmcnt(8)
	s_waitcnt lgkmcnt(0)
	s_setprio 1
	s_barrier
	v_mfma_f32_16x16x32_bf16 v[124:127], v[128:131], v[168:171], v[124:127]
	v_mfma_f32_16x16x32_bf16 v[124:127], v[132:135], v[172:175], v[124:127]
	v_mfma_f32_16x16x32_bf16 v[120:123], v[136:139], v[168:171], v[120:123]
	v_mfma_f32_16x16x32_bf16 v[120:123], v[140:143], v[172:175], v[120:123]
	v_mfma_f32_16x16x32_bf16 v[108:111], v[128:131], v[176:179], v[108:111]
	v_mfma_f32_16x16x32_bf16 v[108:111], v[132:135], v[180:183], v[108:111]
	v_mfma_f32_16x16x32_bf16 v[104:107], v[136:139], v[176:179], v[104:107]
	v_mfma_f32_16x16x32_bf16 v[104:107], v[140:143], v[180:183], v[104:107]
	v_mfma_f32_16x16x32_bf16 v[96:99], v[128:131], v[184:187], v[96:99]
	v_mfma_f32_16x16x32_bf16 v[96:99], v[132:135], v[188:191], v[96:99]
	v_mfma_f32_16x16x32_bf16 v[88:91], v[136:139], v[184:187], v[88:91]
	v_mfma_f32_16x16x32_bf16 v[88:91], v[140:143], v[188:191], v[88:91]
	v_mfma_f32_16x16x32_bf16 v[80:83], v[128:131], v[192:195], v[80:83]
	v_mfma_f32_16x16x32_bf16 v[80:83], v[132:135], v[200:203], v[80:83]
	v_mfma_f32_16x16x32_bf16 v[72:75], v[136:139], v[192:195], v[72:75]
	v_mfma_f32_16x16x32_bf16 v[72:75], v[140:143], v[200:203], v[72:75]
	v_mfma_f32_16x16x32_bf16 v[116:119], v[152:155], v[168:171], v[116:119]
	v_mfma_f32_16x16x32_bf16 v[116:119], v[156:159], v[172:175], v[116:119]
	v_mfma_f32_16x16x32_bf16 v[112:115], v[160:163], v[168:171], v[112:115]
	v_mfma_f32_16x16x32_bf16 v[112:115], v[164:167], v[172:175], v[112:115]
	v_mfma_f32_16x16x32_bf16 v[100:103], v[152:155], v[176:179], v[100:103]
	v_mfma_f32_16x16x32_bf16 v[100:103], v[156:159], v[180:183], v[100:103]
	v_mfma_f32_16x16x32_bf16 v[92:95], v[160:163], v[176:179], v[92:95]
	v_mfma_f32_16x16x32_bf16 v[92:95], v[164:167], v[180:183], v[92:95]
	v_mfma_f32_16x16x32_bf16 v[84:87], v[152:155], v[184:187], v[84:87]
	v_mfma_f32_16x16x32_bf16 v[84:87], v[156:159], v[188:191], v[84:87]
	v_mfma_f32_16x16x32_bf16 v[76:79], v[160:163], v[184:187], v[76:79]
	v_mfma_f32_16x16x32_bf16 v[76:79], v[164:167], v[188:191], v[76:79]
	v_mfma_f32_16x16x32_bf16 v[68:71], v[152:155], v[192:195], v[68:71]
	v_mfma_f32_16x16x32_bf16 v[68:71], v[156:159], v[200:203], v[68:71]
	v_mfma_f32_16x16x32_bf16 v[64:67], v[160:163], v[192:195], v[64:67]
	v_mfma_f32_16x16x32_bf16 v[64:67], v[164:167], v[200:203], v[64:67]
	s_barrier
	s_setprio 0
	s_add_i32 s74, s74, s97
	s_mov_b64 s[28:29], s[36:37]
	s_mov_b32 m0, s74
	ds_read_b128 v[168:171], v151 offset:16384
	ds_read_b128 v[172:175], v151 offset:17408
	ds_read_b128 v[176:179], v151 offset:18432
	ds_read_b128 v[180:183], v151 offset:19456
	ds_read_b128 v[184:187], v151 offset:20480
	ds_read_b128 v[188:191], v151 offset:21504
	ds_read_b128 v[192:195], v151 offset:22528
	ds_read_b128 v[200:203], v151 offset:23552
	s_nop 0
	global_load_lds_dwordx4 v147, s[28:29]
	s_add_i32 m0, s74, 0x2000
	s_nop 0
	global_load_lds_dwordx4 v149, s[28:29]
	s_add_u32 s28, s36, 0x80000
	s_addc_u32 s29, s37, 0
	s_add_i32 s74, s84, s97
	s_mov_b32 m0, s74
	s_nop 0
	global_load_lds_dwordx4 v147, s[28:29]
	s_add_i32 m0, s74, 0x2000
	s_nop 0
	global_load_lds_dwordx4 v149, s[28:29]
	s_mov_b64 s[28:29], s[38:39]
	s_mov_b32 m0, s48
	s_nop 0
	global_load_lds_dwordx4 v146, s[28:29]
	s_mov_b32 m0, s49
	s_nop 0
	global_load_lds_dwordx4 v148, s[28:29]
	s_waitcnt vmcnt(8)
	s_waitcnt lgkmcnt(0)
	s_setprio 1
	s_barrier
	v_mfma_f32_16x16x32_bf16 v[60:63], v[128:131], v[168:171], v[60:63]
	v_mfma_f32_16x16x32_bf16 v[60:63], v[132:135], v[172:175], v[60:63]
	v_mfma_f32_16x16x32_bf16 v[56:59], v[136:139], v[168:171], v[56:59]
	v_mfma_f32_16x16x32_bf16 v[56:59], v[140:143], v[172:175], v[56:59]
	v_mfma_f32_16x16x32_bf16 v[48:51], v[128:131], v[176:179], v[48:51]
	v_mfma_f32_16x16x32_bf16 v[48:51], v[132:135], v[180:183], v[48:51]
	v_mfma_f32_16x16x32_bf16 v[40:43], v[136:139], v[176:179], v[40:43]
	v_mfma_f32_16x16x32_bf16 v[40:43], v[140:143], v[180:183], v[40:43]
	v_mfma_f32_16x16x32_bf16 v[32:35], v[128:131], v[184:187], v[32:35]
	v_mfma_f32_16x16x32_bf16 v[32:35], v[132:135], v[188:191], v[32:35]
	v_mfma_f32_16x16x32_bf16 v[24:27], v[136:139], v[184:187], v[24:27]
	v_mfma_f32_16x16x32_bf16 v[24:27], v[140:143], v[188:191], v[24:27]
	v_mfma_f32_16x16x32_bf16 v[16:19], v[128:131], v[192:195], v[16:19]
	v_mfma_f32_16x16x32_bf16 v[16:19], v[132:135], v[200:203], v[16:19]
	v_mfma_f32_16x16x32_bf16 v[8:11], v[136:139], v[192:195], v[8:11]
	v_mfma_f32_16x16x32_bf16 v[8:11], v[140:143], v[200:203], v[8:11]
	v_mfma_f32_16x16x32_bf16 v[52:55], v[152:155], v[168:171], v[52:55]
	v_mfma_f32_16x16x32_bf16 v[52:55], v[156:159], v[172:175], v[52:55]
	v_mfma_f32_16x16x32_bf16 v[44:47], v[160:163], v[168:171], v[44:47]
	v_mfma_f32_16x16x32_bf16 v[44:47], v[164:167], v[172:175], v[44:47]
	v_mfma_f32_16x16x32_bf16 v[36:39], v[152:155], v[176:179], v[36:39]
	v_mfma_f32_16x16x32_bf16 v[36:39], v[156:159], v[180:183], v[36:39]
	v_mfma_f32_16x16x32_bf16 v[28:31], v[160:163], v[176:179], v[28:31]
	v_mfma_f32_16x16x32_bf16 v[28:31], v[164:167], v[180:183], v[28:31]
	v_mfma_f32_16x16x32_bf16 v[20:23], v[152:155], v[184:187], v[20:23]
	v_mfma_f32_16x16x32_bf16 v[20:23], v[156:159], v[188:191], v[20:23]
	v_mfma_f32_16x16x32_bf16 v[12:15], v[160:163], v[184:187], v[12:15]
	v_mfma_f32_16x16x32_bf16 v[12:15], v[164:167], v[188:191], v[12:15]
	v_mfma_f32_16x16x32_bf16 v[4:7], v[152:155], v[192:195], v[4:7]
	v_mfma_f32_16x16x32_bf16 v[4:7], v[156:159], v[200:203], v[4:7]
	v_mfma_f32_16x16x32_bf16 v[0:3], v[160:163], v[192:195], v[0:3]
	v_mfma_f32_16x16x32_bf16 v[0:3], v[164:167], v[200:203], v[0:3]
	s_barrier
	s_setprio 0
	s_add_i32 s74, 0, 0x18000
	s_add_i32 s84, 0, 0x1c000
	v_add_u32_e32 v140, s74, v150
	v_add_u32_e32 v144, s84, v150
	ds_read_b128 v[128:131], v140
	ds_read_b128 v[132:135], v140 offset:1024
	ds_read_b128 v[136:139], v140 offset:2048
	ds_read_b128 v[140:143], v140 offset:3072
	ds_read_b128 v[152:155], v144
	ds_read_b128 v[156:159], v144 offset:1024
	ds_read_b128 v[160:163], v144 offset:2048
	ds_read_b128 v[164:167], v144 offset:3072
	s_add_u32 s28, s38, 0x80000
	s_addc_u32 s29, s39, 0
	s_mov_b32 m0, s56
	ds_read_b128 v[168:171], v151 offset:32768
	ds_read_b128 v[172:175], v151 offset:33792
	ds_read_b128 v[176:179], v151 offset:34816
	ds_read_b128 v[180:183], v151 offset:35840
	ds_read_b128 v[184:187], v151 offset:36864
	ds_read_b128 v[188:191], v151 offset:37888
	ds_read_b128 v[192:195], v151 offset:38912
	ds_read_b128 v[200:203], v151 offset:39936
	s_nop 0
	global_load_lds_dwordx4 v146, s[28:29]
	s_mov_b32 m0, s57
	s_nop 0
	global_load_lds_dwordx4 v148, s[28:29]
	s_waitcnt vmcnt(8)
	s_waitcnt lgkmcnt(0)
	s_setprio 1
	s_barrier
	v_mfma_f32_16x16x32_bf16 v[124:127], v[128:131], v[168:171], v[124:127]
	v_mfma_f32_16x16x32_bf16 v[124:127], v[132:135], v[172:175], v[124:127]
	v_mfma_f32_16x16x32_bf16 v[120:123], v[136:139], v[168:171], v[120:123]
	v_mfma_f32_16x16x32_bf16 v[120:123], v[140:143], v[172:175], v[120:123]
	v_mfma_f32_16x16x32_bf16 v[108:111], v[128:131], v[176:179], v[108:111]
	v_mfma_f32_16x16x32_bf16 v[108:111], v[132:135], v[180:183], v[108:111]
	v_mfma_f32_16x16x32_bf16 v[104:107], v[136:139], v[176:179], v[104:107]
	v_mfma_f32_16x16x32_bf16 v[104:107], v[140:143], v[180:183], v[104:107]
	v_mfma_f32_16x16x32_bf16 v[96:99], v[128:131], v[184:187], v[96:99]
	v_mfma_f32_16x16x32_bf16 v[96:99], v[132:135], v[188:191], v[96:99]
	v_mfma_f32_16x16x32_bf16 v[88:91], v[136:139], v[184:187], v[88:91]
	v_mfma_f32_16x16x32_bf16 v[88:91], v[140:143], v[188:191], v[88:91]
	v_mfma_f32_16x16x32_bf16 v[80:83], v[128:131], v[192:195], v[80:83]
	v_mfma_f32_16x16x32_bf16 v[80:83], v[132:135], v[200:203], v[80:83]
	v_mfma_f32_16x16x32_bf16 v[72:75], v[136:139], v[192:195], v[72:75]
	v_mfma_f32_16x16x32_bf16 v[72:75], v[140:143], v[200:203], v[72:75]
	v_mfma_f32_16x16x32_bf16 v[116:119], v[152:155], v[168:171], v[116:119]
	v_mfma_f32_16x16x32_bf16 v[116:119], v[156:159], v[172:175], v[116:119]
	v_mfma_f32_16x16x32_bf16 v[112:115], v[160:163], v[168:171], v[112:115]
	v_mfma_f32_16x16x32_bf16 v[112:115], v[164:167], v[172:175], v[112:115]
	v_mfma_f32_16x16x32_bf16 v[100:103], v[152:155], v[176:179], v[100:103]
	v_mfma_f32_16x16x32_bf16 v[100:103], v[156:159], v[180:183], v[100:103]
	v_mfma_f32_16x16x32_bf16 v[92:95], v[160:163], v[176:179], v[92:95]
	v_mfma_f32_16x16x32_bf16 v[92:95], v[164:167], v[180:183], v[92:95]
	v_mfma_f32_16x16x32_bf16 v[84:87], v[152:155], v[184:187], v[84:87]
	v_mfma_f32_16x16x32_bf16 v[84:87], v[156:159], v[188:191], v[84:87]
	v_mfma_f32_16x16x32_bf16 v[76:79], v[160:163], v[184:187], v[76:79]
	v_mfma_f32_16x16x32_bf16 v[76:79], v[164:167], v[188:191], v[76:79]
	v_mfma_f32_16x16x32_bf16 v[68:71], v[152:155], v[192:195], v[68:71]
	v_mfma_f32_16x16x32_bf16 v[68:71], v[156:159], v[200:203], v[68:71]
	v_mfma_f32_16x16x32_bf16 v[64:67], v[160:163], v[192:195], v[64:67]
	v_mfma_f32_16x16x32_bf16 v[64:67], v[164:167], v[200:203], v[64:67]
	s_barrier
	s_setprio 0
	s_add_u32 s28, s36, 0x80
	s_addc_u32 s29, s37, 0
	s_add_i32 s38, s74, s97
	s_mov_b32 m0, s38
	ds_read_b128 v[168:171], v151 offset:49152
	ds_read_b128 v[172:175], v151 offset:50176
	ds_read_b128 v[176:179], v151 offset:51200
	ds_read_b128 v[180:183], v151 offset:52224
	ds_read_b128 v[184:187], v151 offset:53248
	ds_read_b128 v[188:191], v151 offset:54272
	ds_read_b128 v[192:195], v151 offset:55296
	ds_read_b128 v[200:203], v151 offset:56320
	s_nop 0
	global_load_lds_dwordx4 v147, s[28:29]
	s_add_i32 m0, s38, 0x2000
	s_nop 0
	global_load_lds_dwordx4 v149, s[28:29]
	s_add_u32 s28, s36, 0x80080
	s_addc_u32 s29, s37, 0
	s_add_i32 s36, s84, s97
	s_mov_b32 m0, s36
	s_nop 0
	global_load_lds_dwordx4 v147, s[28:29]
	s_add_i32 m0, s36, 0x2000
	s_nop 0
	global_load_lds_dwordx4 v149, s[28:29]
	s_mov_b32 m0, s82
	s_nop 0
	global_load_lds_dwordx4 v146, s[34:35]
	s_mov_b32 m0, s83
	s_nop 0
	global_load_lds_dwordx4 v148, s[34:35]
	s_waitcnt vmcnt(8)
	s_waitcnt lgkmcnt(0)
	s_setprio 1
	s_barrier
	v_mfma_f32_16x16x32_bf16 v[60:63], v[128:131], v[168:171], v[60:63]
	v_mfma_f32_16x16x32_bf16 v[60:63], v[132:135], v[172:175], v[60:63]
	v_mfma_f32_16x16x32_bf16 v[56:59], v[136:139], v[168:171], v[56:59]
	v_mfma_f32_16x16x32_bf16 v[56:59], v[140:143], v[172:175], v[56:59]
	v_mfma_f32_16x16x32_bf16 v[48:51], v[128:131], v[176:179], v[48:51]
	v_mfma_f32_16x16x32_bf16 v[48:51], v[132:135], v[180:183], v[48:51]
	v_mfma_f32_16x16x32_bf16 v[40:43], v[136:139], v[176:179], v[40:43]
	v_mfma_f32_16x16x32_bf16 v[40:43], v[140:143], v[180:183], v[40:43]
	v_mfma_f32_16x16x32_bf16 v[32:35], v[128:131], v[184:187], v[32:35]
	v_mfma_f32_16x16x32_bf16 v[32:35], v[132:135], v[188:191], v[32:35]
	v_mfma_f32_16x16x32_bf16 v[24:27], v[136:139], v[184:187], v[24:27]
	v_mfma_f32_16x16x32_bf16 v[24:27], v[140:143], v[188:191], v[24:27]
	v_mfma_f32_16x16x32_bf16 v[16:19], v[128:131], v[192:195], v[16:19]
	v_mfma_f32_16x16x32_bf16 v[16:19], v[132:135], v[200:203], v[16:19]
	v_mfma_f32_16x16x32_bf16 v[8:11], v[136:139], v[192:195], v[8:11]
	v_mfma_f32_16x16x32_bf16 v[8:11], v[140:143], v[200:203], v[8:11]
	v_mfma_f32_16x16x32_bf16 v[52:55], v[152:155], v[168:171], v[52:55]
	v_mfma_f32_16x16x32_bf16 v[52:55], v[156:159], v[172:175], v[52:55]
	v_mfma_f32_16x16x32_bf16 v[44:47], v[160:163], v[168:171], v[44:47]
	v_mfma_f32_16x16x32_bf16 v[44:47], v[164:167], v[172:175], v[44:47]
	v_mfma_f32_16x16x32_bf16 v[36:39], v[152:155], v[176:179], v[36:39]
	v_mfma_f32_16x16x32_bf16 v[36:39], v[156:159], v[180:183], v[36:39]
	v_mfma_f32_16x16x32_bf16 v[28:31], v[160:163], v[176:179], v[28:31]
	v_mfma_f32_16x16x32_bf16 v[28:31], v[164:167], v[180:183], v[28:31]
	v_mfma_f32_16x16x32_bf16 v[20:23], v[152:155], v[184:187], v[20:23]
	v_mfma_f32_16x16x32_bf16 v[20:23], v[156:159], v[188:191], v[20:23]
	v_mfma_f32_16x16x32_bf16 v[12:15], v[160:163], v[184:187], v[12:15]
	v_mfma_f32_16x16x32_bf16 v[12:15], v[164:167], v[188:191], v[12:15]
	v_mfma_f32_16x16x32_bf16 v[4:7], v[152:155], v[192:195], v[4:7]
	v_mfma_f32_16x16x32_bf16 v[4:7], v[156:159], v[200:203], v[4:7]
	v_mfma_f32_16x16x32_bf16 v[0:3], v[160:163], v[192:195], v[0:3]
	v_mfma_f32_16x16x32_bf16 v[0:3], v[164:167], v[200:203], v[0:3]
	s_barrier
	s_setprio 0
	s_add_i32 s69, s69, 2
	s_add_u32 s21, s21, 0x100
	s_addc_u32 s27, s27, 0
	s_cmp_gt_u32 s69, 29
	s_mov_b64 s[28:29], s[30:31]
	s_cbranch_scc0 .LBB0_676
	s_and_b64 vcc, exec, s[60:61]
	s_cbranch_vccz .LBB0_679
	s_barrier

.LBB0_788:
	s_add_u32 s30, s28, 0x100
	s_addc_u32 s31, s29, 0
	s_cmp_eq_u32 s17, 4
	s_cselect_b32 s38, s20, s30
	s_cselect_b32 s39, s21, s31
	s_cselect_b32 s36, s22, s5
	s_cselect_b32 s37, s23, s15
	s_add_u32 s34, s38, 0x80
	s_addc_u32 s35, s39, 0
	s_add_i32 s83, 0, 0x10000
	s_add_i32 s84, 0, 0x14000
	v_add_u32_e32 v146, s83, v136
	v_add_u32_e32 v162, s84, v136
	ds_read_b128 v[128:131], v146
	ds_read_b128 v[138:141], v146 offset:1024
	ds_read_b128 v[142:145], v146 offset:2048
	ds_read_b128 v[146:149], v146 offset:3072
	ds_read_b128 v[150:153], v162
	ds_read_b128 v[154:157], v162 offset:1024
	ds_read_b128 v[158:161], v162 offset:2048
	ds_read_b128 v[162:165], v162 offset:3072
	s_add_u32 s28, s28, 0x20080
	s_addc_u32 s29, s29, 0
	s_add_i32 m0, s27, 0xc000
	ds_read_b128 v[166:169], v137
	ds_read_b128 v[170:173], v137 offset:1024
	ds_read_b128 v[174:177], v137 offset:2048
	ds_read_b128 v[178:181], v137 offset:3072
	ds_read_b128 v[182:185], v137 offset:4096
	ds_read_b128 v[186:189], v137 offset:5120
	ds_read_b128 v[190:193], v137 offset:6144
	ds_read_b128 v[200:203], v137 offset:7168
	s_nop 0
	global_load_lds_dwordx4 v132, s[28:29]
	s_add_i32 m0, s27, 0xe000
	s_nop 0
	global_load_lds_dwordx4 v134, s[28:29]
	s_waitcnt vmcnt(8)
	s_waitcnt lgkmcnt(0)
	s_setprio 1
	s_barrier
	v_mfma_f32_16x16x32_bf16 v[124:127], v[128:131], v[166:169], v[124:127]
	v_mfma_f32_16x16x32_bf16 v[124:127], v[138:141], v[170:173], v[124:127]
	v_mfma_f32_16x16x32_bf16 v[120:123], v[142:145], v[166:169], v[120:123]
	v_mfma_f32_16x16x32_bf16 v[120:123], v[146:149], v[170:173], v[120:123]
	v_mfma_f32_16x16x32_bf16 v[108:111], v[128:131], v[174:177], v[108:111]
	v_mfma_f32_16x16x32_bf16 v[108:111], v[138:141], v[178:181], v[108:111]
	v_mfma_f32_16x16x32_bf16 v[104:107], v[142:145], v[174:177], v[104:107]
	v_mfma_f32_16x16x32_bf16 v[104:107], v[146:149], v[178:181], v[104:107]
	v_mfma_f32_16x16x32_bf16 v[92:95], v[128:131], v[182:185], v[92:95]
	v_mfma_f32_16x16x32_bf16 v[92:95], v[138:141], v[186:189], v[92:95]
	v_mfma_f32_16x16x32_bf16 v[88:91], v[142:145], v[182:185], v[88:91]
	v_mfma_f32_16x16x32_bf16 v[88:91], v[146:149], v[186:189], v[88:91]
	v_mfma_f32_16x16x32_bf16 v[76:79], v[128:131], v[190:193], v[76:79]
	v_mfma_f32_16x16x32_bf16 v[76:79], v[138:141], v[200:203], v[76:79]
	v_mfma_f32_16x16x32_bf16 v[72:75], v[142:145], v[190:193], v[72:75]
	v_mfma_f32_16x16x32_bf16 v[72:75], v[146:149], v[200:203], v[72:75]
	v_mfma_f32_16x16x32_bf16 v[116:119], v[150:153], v[166:169], v[116:119]
	v_mfma_f32_16x16x32_bf16 v[116:119], v[154:157], v[170:173], v[116:119]
	v_mfma_f32_16x16x32_bf16 v[112:115], v[158:161], v[166:169], v[112:115]
	v_mfma_f32_16x16x32_bf16 v[112:115], v[162:165], v[170:173], v[112:115]
	v_mfma_f32_16x16x32_bf16 v[100:103], v[150:153], v[174:177], v[100:103]
	v_mfma_f32_16x16x32_bf16 v[100:103], v[154:157], v[178:181], v[100:103]
	v_mfma_f32_16x16x32_bf16 v[96:99], v[158:161], v[174:177], v[96:99]
	v_mfma_f32_16x16x32_bf16 v[96:99], v[162:165], v[178:181], v[96:99]
	v_mfma_f32_16x16x32_bf16 v[84:87], v[150:153], v[182:185], v[84:87]
	v_mfma_f32_16x16x32_bf16 v[84:87], v[154:157], v[186:189], v[84:87]
	v_mfma_f32_16x16x32_bf16 v[80:83], v[158:161], v[182:185], v[80:83]
	v_mfma_f32_16x16x32_bf16 v[80:83], v[162:165], v[186:189], v[80:83]
	v_mfma_f32_16x16x32_bf16 v[68:71], v[150:153], v[190:193], v[68:71]
	v_mfma_f32_16x16x32_bf16 v[68:71], v[154:157], v[200:203], v[68:71]
	v_mfma_f32_16x16x32_bf16 v[64:67], v[158:161], v[190:193], v[64:67]
	v_mfma_f32_16x16x32_bf16 v[64:67], v[162:165], v[200:203], v[64:67]
	s_barrier
	s_setprio 0
	s_add_i32 s83, s83, s97
	s_mov_b64 s[28:29], s[36:37]
	s_mov_b32 m0, s83
	ds_read_b128 v[166:169], v137 offset:16384
	ds_read_b128 v[170:173], v137 offset:17408
	ds_read_b128 v[174:177], v137 offset:18432
	ds_read_b128 v[178:181], v137 offset:19456
	ds_read_b128 v[182:185], v137 offset:20480
	ds_read_b128 v[186:189], v137 offset:21504
	ds_read_b128 v[190:193], v137 offset:22528
	ds_read_b128 v[200:203], v137 offset:23552
	s_nop 0
	global_load_lds_dwordx4 v133, s[28:29]
	s_add_i32 m0, s83, 0x2000
	s_nop 0
	global_load_lds_dwordx4 v135, s[28:29]
	s_add_u32 s28, s36, 0x20000
	s_addc_u32 s29, s37, 0
	s_add_i32 s83, s84, s97
	s_mov_b32 m0, s83
	s_nop 0
	global_load_lds_dwordx4 v133, s[28:29]
	s_add_i32 m0, s83, 0x2000
	s_nop 0
	global_load_lds_dwordx4 v135, s[28:29]
	s_mov_b64 s[28:29], s[38:39]
	s_mov_b32 m0, s27
	s_nop 0
	global_load_lds_dwordx4 v132, s[28:29]
	s_mov_b32 m0, s69
	s_nop 0
	global_load_lds_dwordx4 v134, s[28:29]
	s_waitcnt vmcnt(8)
	s_waitcnt lgkmcnt(0)
	s_setprio 1
	s_barrier
	v_mfma_f32_16x16x32_bf16 v[60:63], v[128:131], v[166:169], v[60:63]
	v_mfma_f32_16x16x32_bf16 v[60:63], v[138:141], v[170:173], v[60:63]
	v_mfma_f32_16x16x32_bf16 v[56:59], v[142:145], v[166:169], v[56:59]
	v_mfma_f32_16x16x32_bf16 v[56:59], v[146:149], v[170:173], v[56:59]
	v_mfma_f32_16x16x32_bf16 v[44:47], v[128:131], v[174:177], v[44:47]
	v_mfma_f32_16x16x32_bf16 v[44:47], v[138:141], v[178:181], v[44:47]
	v_mfma_f32_16x16x32_bf16 v[40:43], v[142:145], v[174:177], v[40:43]
	v_mfma_f32_16x16x32_bf16 v[40:43], v[146:149], v[178:181], v[40:43]
	v_mfma_f32_16x16x32_bf16 v[28:31], v[128:131], v[182:185], v[28:31]
	v_mfma_f32_16x16x32_bf16 v[28:31], v[138:141], v[186:189], v[28:31]
	v_mfma_f32_16x16x32_bf16 v[24:27], v[142:145], v[182:185], v[24:27]
	v_mfma_f32_16x16x32_bf16 v[24:27], v[146:149], v[186:189], v[24:27]
	v_mfma_f32_16x16x32_bf16 v[12:15], v[128:131], v[190:193], v[12:15]
	v_mfma_f32_16x16x32_bf16 v[12:15], v[138:141], v[200:203], v[12:15]
	v_mfma_f32_16x16x32_bf16 v[8:11], v[142:145], v[190:193], v[8:11]
	v_mfma_f32_16x16x32_bf16 v[8:11], v[146:149], v[200:203], v[8:11]
	v_mfma_f32_16x16x32_bf16 v[52:55], v[150:153], v[166:169], v[52:55]
	v_mfma_f32_16x16x32_bf16 v[52:55], v[154:157], v[170:173], v[52:55]
	v_mfma_f32_16x16x32_bf16 v[48:51], v[158:161], v[166:169], v[48:51]
	v_mfma_f32_16x16x32_bf16 v[48:51], v[162:165], v[170:173], v[48:51]
	v_mfma_f32_16x16x32_bf16 v[36:39], v[150:153], v[174:177], v[36:39]
	v_mfma_f32_16x16x32_bf16 v[36:39], v[154:157], v[178:181], v[36:39]
	v_mfma_f32_16x16x32_bf16 v[32:35], v[158:161], v[174:177], v[32:35]
	v_mfma_f32_16x16x32_bf16 v[32:35], v[162:165], v[178:181], v[32:35]
	v_mfma_f32_16x16x32_bf16 v[20:23], v[150:153], v[182:185], v[20:23]
	v_mfma_f32_16x16x32_bf16 v[20:23], v[154:157], v[186:189], v[20:23]
	v_mfma_f32_16x16x32_bf16 v[16:19], v[158:161], v[182:185], v[16:19]
	v_mfma_f32_16x16x32_bf16 v[16:19], v[162:165], v[186:189], v[16:19]
	v_mfma_f32_16x16x32_bf16 v[4:7], v[150:153], v[190:193], v[4:7]
	v_mfma_f32_16x16x32_bf16 v[4:7], v[154:157], v[200:203], v[4:7]
	v_mfma_f32_16x16x32_bf16 v[0:3], v[158:161], v[190:193], v[0:3]
	v_mfma_f32_16x16x32_bf16 v[0:3], v[162:165], v[200:203], v[0:3]
	s_barrier
	s_setprio 0
	s_add_i32 s83, 0, 0x18000
	s_add_i32 s84, 0, 0x1c000
	v_add_u32_e32 v146, s83, v136
	v_add_u32_e32 v162, s84, v136
	ds_read_b128 v[128:131], v146
	ds_read_b128 v[138:141], v146 offset:1024
	ds_read_b128 v[142:145], v146 offset:2048
	ds_read_b128 v[146:149], v146 offset:3072
	ds_read_b128 v[150:153], v162
	ds_read_b128 v[154:157], v162 offset:1024
	ds_read_b128 v[158:161], v162 offset:2048
	ds_read_b128 v[162:165], v162 offset:3072
	s_add_u32 s28, s38, 0x20000
	s_addc_u32 s29, s39, 0
	s_mov_b32 m0, s71
	ds_read_b128 v[166:169], v137 offset:32768
	ds_read_b128 v[170:173], v137 offset:33792
	ds_read_b128 v[174:177], v137 offset:34816
	ds_read_b128 v[178:181], v137 offset:35840
	ds_read_b128 v[182:185], v137 offset:36864
	ds_read_b128 v[186:189], v137 offset:37888
	ds_read_b128 v[190:193], v137 offset:38912
	ds_read_b128 v[200:203], v137 offset:39936
	s_nop 0
	global_load_lds_dwordx4 v132, s[28:29]
	s_mov_b32 m0, s72
	s_nop 0
	global_load_lds_dwordx4 v134, s[28:29]
	s_waitcnt vmcnt(8)
	s_waitcnt lgkmcnt(0)
	s_setprio 1
	s_barrier
	v_mfma_f32_16x16x32_bf16 v[124:127], v[128:131], v[166:169], v[124:127]
	v_mfma_f32_16x16x32_bf16 v[124:127], v[138:141], v[170:173], v[124:127]
	v_mfma_f32_16x16x32_bf16 v[120:123], v[142:145], v[166:169], v[120:123]
	v_mfma_f32_16x16x32_bf16 v[120:123], v[146:149], v[170:173], v[120:123]
	v_mfma_f32_16x16x32_bf16 v[108:111], v[128:131], v[174:177], v[108:111]
	v_mfma_f32_16x16x32_bf16 v[108:111], v[138:141], v[178:181], v[108:111]
	v_mfma_f32_16x16x32_bf16 v[104:107], v[142:145], v[174:177], v[104:107]
	v_mfma_f32_16x16x32_bf16 v[104:107], v[146:149], v[178:181], v[104:107]
	v_mfma_f32_16x16x32_bf16 v[92:95], v[128:131], v[182:185], v[92:95]
	v_mfma_f32_16x16x32_bf16 v[92:95], v[138:141], v[186:189], v[92:95]
	v_mfma_f32_16x16x32_bf16 v[88:91], v[142:145], v[182:185], v[88:91]
	v_mfma_f32_16x16x32_bf16 v[88:91], v[146:149], v[186:189], v[88:91]
	v_mfma_f32_16x16x32_bf16 v[76:79], v[128:131], v[190:193], v[76:79]
	v_mfma_f32_16x16x32_bf16 v[76:79], v[138:141], v[200:203], v[76:79]
	v_mfma_f32_16x16x32_bf16 v[72:75], v[142:145], v[190:193], v[72:75]
	v_mfma_f32_16x16x32_bf16 v[72:75], v[146:149], v[200:203], v[72:75]
	v_mfma_f32_16x16x32_bf16 v[116:119], v[150:153], v[166:169], v[116:119]
	v_mfma_f32_16x16x32_bf16 v[116:119], v[154:157], v[170:173], v[116:119]
	v_mfma_f32_16x16x32_bf16 v[112:115], v[158:161], v[166:169], v[112:115]
	v_mfma_f32_16x16x32_bf16 v[112:115], v[162:165], v[170:173], v[112:115]
	v_mfma_f32_16x16x32_bf16 v[100:103], v[150:153], v[174:177], v[100:103]
	v_mfma_f32_16x16x32_bf16 v[100:103], v[154:157], v[178:181], v[100:103]
	v_mfma_f32_16x16x32_bf16 v[96:99], v[158:161], v[174:177], v[96:99]
	v_mfma_f32_16x16x32_bf16 v[96:99], v[162:165], v[178:181], v[96:99]
	v_mfma_f32_16x16x32_bf16 v[84:87], v[150:153], v[182:185], v[84:87]
	v_mfma_f32_16x16x32_bf16 v[84:87], v[154:157], v[186:189], v[84:87]
	v_mfma_f32_16x16x32_bf16 v[80:83], v[158:161], v[182:185], v[80:83]
	v_mfma_f32_16x16x32_bf16 v[80:83], v[162:165], v[186:189], v[80:83]
	v_mfma_f32_16x16x32_bf16 v[68:71], v[150:153], v[190:193], v[68:71]
	v_mfma_f32_16x16x32_bf16 v[68:71], v[154:157], v[200:203], v[68:71]
	v_mfma_f32_16x16x32_bf16 v[64:67], v[158:161], v[190:193], v[64:67]
	v_mfma_f32_16x16x32_bf16 v[64:67], v[162:165], v[200:203], v[64:67]
	s_barrier
	s_setprio 0
	s_add_u32 s28, s36, 0x80
	s_addc_u32 s29, s37, 0
	s_add_i32 s38, s83, s97
	s_mov_b32 m0, s38
	ds_read_b128 v[166:169], v137 offset:49152
	ds_read_b128 v[170:173], v137 offset:50176
	ds_read_b128 v[174:177], v137 offset:51200
	ds_read_b128 v[178:181], v137 offset:52224
	ds_read_b128 v[182:185], v137 offset:53248
	ds_read_b128 v[186:189], v137 offset:54272
	ds_read_b128 v[190:193], v137 offset:55296
	ds_read_b128 v[200:203], v137 offset:56320
	s_nop 0
	global_load_lds_dwordx4 v133, s[28:29]
	s_add_i32 m0, s38, 0x2000
	s_nop 0
	global_load_lds_dwordx4 v135, s[28:29]
	s_add_u32 s28, s36, 0x20080
	s_addc_u32 s29, s37, 0
	s_add_i32 s36, s84, s97
	s_mov_b32 m0, s36
	s_nop 0
	global_load_lds_dwordx4 v133, s[28:29]
	s_add_i32 m0, s36, 0x2000
	s_nop 0
	global_load_lds_dwordx4 v135, s[28:29]
	s_mov_b32 m0, s80
	s_nop 0
	global_load_lds_dwordx4 v132, s[34:35]
	s_mov_b32 m0, s81
	s_nop 0
	global_load_lds_dwordx4 v134, s[34:35]
	s_waitcnt vmcnt(8)
	s_waitcnt lgkmcnt(0)
	s_setprio 1
	s_barrier
	v_mfma_f32_16x16x32_bf16 v[60:63], v[128:131], v[166:169], v[60:63]
	v_mfma_f32_16x16x32_bf16 v[60:63], v[138:141], v[170:173], v[60:63]
	v_mfma_f32_16x16x32_bf16 v[56:59], v[142:145], v[166:169], v[56:59]
	v_mfma_f32_16x16x32_bf16 v[56:59], v[146:149], v[170:173], v[56:59]
	v_mfma_f32_16x16x32_bf16 v[44:47], v[128:131], v[174:177], v[44:47]
	v_mfma_f32_16x16x32_bf16 v[44:47], v[138:141], v[178:181], v[44:47]
	v_mfma_f32_16x16x32_bf16 v[40:43], v[142:145], v[174:177], v[40:43]
	v_mfma_f32_16x16x32_bf16 v[40:43], v[146:149], v[178:181], v[40:43]
	v_mfma_f32_16x16x32_bf16 v[28:31], v[128:131], v[182:185], v[28:31]
	v_mfma_f32_16x16x32_bf16 v[28:31], v[138:141], v[186:189], v[28:31]
	v_mfma_f32_16x16x32_bf16 v[24:27], v[142:145], v[182:185], v[24:27]
	v_mfma_f32_16x16x32_bf16 v[24:27], v[146:149], v[186:189], v[24:27]
	v_mfma_f32_16x16x32_bf16 v[12:15], v[128:131], v[190:193], v[12:15]
	v_mfma_f32_16x16x32_bf16 v[12:15], v[138:141], v[200:203], v[12:15]
	v_mfma_f32_16x16x32_bf16 v[8:11], v[142:145], v[190:193], v[8:11]
	v_mfma_f32_16x16x32_bf16 v[8:11], v[146:149], v[200:203], v[8:11]
	v_mfma_f32_16x16x32_bf16 v[52:55], v[150:153], v[166:169], v[52:55]
	v_mfma_f32_16x16x32_bf16 v[52:55], v[154:157], v[170:173], v[52:55]
	v_mfma_f32_16x16x32_bf16 v[48:51], v[158:161], v[166:169], v[48:51]
	v_mfma_f32_16x16x32_bf16 v[48:51], v[162:165], v[170:173], v[48:51]
	v_mfma_f32_16x16x32_bf16 v[36:39], v[150:153], v[174:177], v[36:39]
	v_mfma_f32_16x16x32_bf16 v[36:39], v[154:157], v[178:181], v[36:39]
	v_mfma_f32_16x16x32_bf16 v[32:35], v[158:161], v[174:177], v[32:35]
	v_mfma_f32_16x16x32_bf16 v[32:35], v[162:165], v[178:181], v[32:35]
	v_mfma_f32_16x16x32_bf16 v[20:23], v[150:153], v[182:185], v[20:23]
	v_mfma_f32_16x16x32_bf16 v[20:23], v[154:157], v[186:189], v[20:23]
	v_mfma_f32_16x16x32_bf16 v[16:19], v[158:161], v[182:185], v[16:19]
	v_mfma_f32_16x16x32_bf16 v[16:19], v[162:165], v[186:189], v[16:19]
	v_mfma_f32_16x16x32_bf16 v[4:7], v[150:153], v[190:193], v[4:7]
	v_mfma_f32_16x16x32_bf16 v[4:7], v[154:157], v[200:203], v[4:7]
	v_mfma_f32_16x16x32_bf16 v[0:3], v[158:161], v[190:193], v[0:3]
	v_mfma_f32_16x16x32_bf16 v[0:3], v[162:165], v[200:203], v[0:3]
	s_barrier
	s_setprio 0
	s_add_i32 s17, s17, 2
	s_add_u32 s5, s5, 0x100
	s_addc_u32 s15, s15, 0
	s_cmp_gt_u32 s17, 5
	s_mov_b64 s[28:29], s[30:31]
	s_cbranch_scc0 .LBB0_788
	s_and_b64 vcc, exec, s[60:61]
	s_cbranch_vccz .LBB0_791
	s_barrier

.LBB0_1050:
	s_cmp_eq_u32 s83, 28
	s_cselect_b32 s56, s5, s39
	s_cselect_b32 s57, s4, s69
	s_cselect_b32 s84, s37, s72
	s_cselect_b32 s85, s11, s74
	s_add_u32 s12, s56, 0x80
	s_addc_u32 s13, s57, 0
	s_add_i32 vcc_lo, 0, 0x10000
	s_add_i32 vcc_hi, 0, 0x14000
	v_add_u32_e32 v136, vcc_lo, v184
	v_add_u32_e32 v156, vcc_hi, v184
	ds_read_b128 v[104:107], v136
	ds_read_b128 v[108:111], v136 offset:1024
	ds_read_b128 v[132:135], v136 offset:2048
	ds_read_b128 v[136:139], v136 offset:3072
	ds_read_b128 v[144:147], v156
	ds_read_b128 v[148:151], v156 offset:1024
	ds_read_b128 v[152:155], v156 offset:2048
	ds_read_b128 v[156:159], v156 offset:3072
	s_mov_b64 s[86:87], s[8:9]
	s_add_i32 m0, s92, 0xc000
	ds_read_b128 v[160:163], v185
	ds_read_b128 v[164:167], v185 offset:1024
	ds_read_b128 v[168:171], v185 offset:2048
	ds_read_b128 v[172:175], v185 offset:3072
	ds_read_b128 v[186:189], v185 offset:4096
	ds_read_b128 v[190:193], v185 offset:5120
	ds_read_b128 v[200:203], v185 offset:6144
	ds_read_b128 v[204:207], v185 offset:7168
	s_nop 0
	global_load_lds_dwordx4 v179, s[86:87]
	s_add_i32 m0, s92, 0xe000
	s_nop 0
	global_load_lds_dwordx4 v182, s[86:87]
	s_waitcnt vmcnt(8)
	s_waitcnt lgkmcnt(0)
	s_setprio 1
	s_barrier
	v_mfma_f32_16x16x32_bf16 v[140:143], v[104:107], v[160:163], v[140:143]
	v_mfma_f32_16x16x32_bf16 v[140:143], v[108:111], v[164:167], v[140:143]
	v_mfma_f32_16x16x32_bf16 v[128:131], v[132:135], v[160:163], v[128:131]
	v_mfma_f32_16x16x32_bf16 v[128:131], v[136:139], v[164:167], v[128:131]
	v_mfma_f32_16x16x32_bf16 v[124:127], v[104:107], v[168:171], v[124:127]
	v_mfma_f32_16x16x32_bf16 v[124:127], v[108:111], v[172:175], v[124:127]
	v_mfma_f32_16x16x32_bf16 v[112:115], v[132:135], v[168:171], v[112:115]
	v_mfma_f32_16x16x32_bf16 v[112:115], v[136:139], v[172:175], v[112:115]
	v_mfma_f32_16x16x32_bf16 v[96:99], v[104:107], v[186:189], v[96:99]
	v_mfma_f32_16x16x32_bf16 v[96:99], v[108:111], v[190:193], v[96:99]
	v_mfma_f32_16x16x32_bf16 v[88:91], v[132:135], v[186:189], v[88:91]
	v_mfma_f32_16x16x32_bf16 v[88:91], v[136:139], v[190:193], v[88:91]
	v_mfma_f32_16x16x32_bf16 v[84:87], v[104:107], v[200:203], v[84:87]
	v_mfma_f32_16x16x32_bf16 v[84:87], v[108:111], v[204:207], v[84:87]
	v_mfma_f32_16x16x32_bf16 v[72:75], v[132:135], v[200:203], v[72:75]
	v_mfma_f32_16x16x32_bf16 v[72:75], v[136:139], v[204:207], v[72:75]
	v_mfma_f32_16x16x32_bf16 v[120:123], v[144:147], v[160:163], v[120:123]
	v_mfma_f32_16x16x32_bf16 v[120:123], v[148:151], v[164:167], v[120:123]
	v_mfma_f32_16x16x32_bf16 v[116:119], v[152:155], v[160:163], v[116:119]
	v_mfma_f32_16x16x32_bf16 v[116:119], v[156:159], v[164:167], v[116:119]
	v_mfma_f32_16x16x32_bf16 v[100:103], v[144:147], v[168:171], v[100:103]
	v_mfma_f32_16x16x32_bf16 v[100:103], v[148:151], v[172:175], v[100:103]
	v_mfma_f32_16x16x32_bf16 v[92:95], v[152:155], v[168:171], v[92:95]
	v_mfma_f32_16x16x32_bf16 v[92:95], v[156:159], v[172:175], v[92:95]
	v_mfma_f32_16x16x32_bf16 v[80:83], v[144:147], v[186:189], v[80:83]
	v_mfma_f32_16x16x32_bf16 v[80:83], v[148:151], v[190:193], v[80:83]
	v_mfma_f32_16x16x32_bf16 v[76:79], v[152:155], v[186:189], v[76:79]
	v_mfma_f32_16x16x32_bf16 v[76:79], v[156:159], v[190:193], v[76:79]
	v_mfma_f32_16x16x32_bf16 v[68:71], v[144:147], v[200:203], v[68:71]
	v_mfma_f32_16x16x32_bf16 v[68:71], v[148:151], v[204:207], v[68:71]
	v_mfma_f32_16x16x32_bf16 v[64:67], v[152:155], v[200:203], v[64:67]
	v_mfma_f32_16x16x32_bf16 v[64:67], v[156:159], v[204:207], v[64:67]
	s_barrier
	s_setprio 0
	s_add_i32 vcc_lo, vcc_lo, s97
	s_mov_b64 s[86:87], s[84:85]
	s_mov_b32 m0, vcc_lo
	ds_read_b128 v[160:163], v185 offset:16384
	ds_read_b128 v[164:167], v185 offset:17408
	ds_read_b128 v[168:171], v185 offset:18432
	ds_read_b128 v[172:175], v185 offset:19456
	ds_read_b128 v[186:189], v185 offset:20480
	ds_read_b128 v[190:193], v185 offset:21504
	ds_read_b128 v[200:203], v185 offset:22528
	ds_read_b128 v[204:207], v185 offset:23552
	s_nop 0
	global_load_lds_dwordx4 v181, s[86:87]
	s_add_i32 m0, vcc_lo, 0x2000
	s_nop 0
	global_load_lds_dwordx4 v183, s[86:87]
	s_add_u32 s86, s84, 0x80000
	s_addc_u32 s87, s85, 0
	s_add_i32 vcc_lo, vcc_hi, s97
	s_mov_b32 m0, vcc_lo
	s_nop 0
	global_load_lds_dwordx4 v181, s[86:87]
	s_add_i32 m0, vcc_lo, 0x2000
	s_nop 0
	global_load_lds_dwordx4 v183, s[86:87]
	s_mov_b64 s[86:87], s[56:57]
	s_mov_b32 m0, s92
	s_nop 0
	global_load_lds_dwordx4 v179, s[86:87]
	s_mov_b32 m0, s93
	s_nop 0
	global_load_lds_dwordx4 v182, s[86:87]
	s_waitcnt vmcnt(8)
	s_waitcnt lgkmcnt(0)
	s_setprio 1
	s_barrier
	v_mfma_f32_16x16x32_bf16 v[60:63], v[104:107], v[160:163], v[60:63]
	v_mfma_f32_16x16x32_bf16 v[60:63], v[108:111], v[164:167], v[60:63]
	v_mfma_f32_16x16x32_bf16 v[56:59], v[132:135], v[160:163], v[56:59]
	v_mfma_f32_16x16x32_bf16 v[56:59], v[136:139], v[164:167], v[56:59]
	v_mfma_f32_16x16x32_bf16 v[48:51], v[104:107], v[168:171], v[48:51]
	v_mfma_f32_16x16x32_bf16 v[48:51], v[108:111], v[172:175], v[48:51]
	v_mfma_f32_16x16x32_bf16 v[40:43], v[132:135], v[168:171], v[40:43]
	v_mfma_f32_16x16x32_bf16 v[40:43], v[136:139], v[172:175], v[40:43]
	v_mfma_f32_16x16x32_bf16 v[32:35], v[104:107], v[186:189], v[32:35]
	v_mfma_f32_16x16x32_bf16 v[32:35], v[108:111], v[190:193], v[32:35]
	v_mfma_f32_16x16x32_bf16 v[24:27], v[132:135], v[186:189], v[24:27]
	v_mfma_f32_16x16x32_bf16 v[24:27], v[136:139], v[190:193], v[24:27]
	v_mfma_f32_16x16x32_bf16 v[16:19], v[104:107], v[200:203], v[16:19]
	v_mfma_f32_16x16x32_bf16 v[16:19], v[108:111], v[204:207], v[16:19]
	v_mfma_f32_16x16x32_bf16 v[8:11], v[132:135], v[200:203], v[8:11]
	v_mfma_f32_16x16x32_bf16 v[8:11], v[136:139], v[204:207], v[8:11]
	v_mfma_f32_16x16x32_bf16 v[52:55], v[144:147], v[160:163], v[52:55]
	v_mfma_f32_16x16x32_bf16 v[52:55], v[148:151], v[164:167], v[52:55]
	v_mfma_f32_16x16x32_bf16 v[44:47], v[152:155], v[160:163], v[44:47]
	v_mfma_f32_16x16x32_bf16 v[44:47], v[156:159], v[164:167], v[44:47]
	v_mfma_f32_16x16x32_bf16 v[36:39], v[144:147], v[168:171], v[36:39]
	v_mfma_f32_16x16x32_bf16 v[36:39], v[148:151], v[172:175], v[36:39]
	v_mfma_f32_16x16x32_bf16 v[28:31], v[152:155], v[168:171], v[28:31]
	v_mfma_f32_16x16x32_bf16 v[28:31], v[156:159], v[172:175], v[28:31]
	v_mfma_f32_16x16x32_bf16 v[20:23], v[144:147], v[186:189], v[20:23]
	v_mfma_f32_16x16x32_bf16 v[20:23], v[148:151], v[190:193], v[20:23]
	v_mfma_f32_16x16x32_bf16 v[12:15], v[152:155], v[186:189], v[12:15]
	v_mfma_f32_16x16x32_bf16 v[12:15], v[156:159], v[190:193], v[12:15]
	v_mfma_f32_16x16x32_bf16 v[4:7], v[144:147], v[200:203], v[4:7]
	v_mfma_f32_16x16x32_bf16 v[4:7], v[148:151], v[204:207], v[4:7]
	v_mfma_f32_16x16x32_bf16 v[0:3], v[152:155], v[200:203], v[0:3]
	v_mfma_f32_16x16x32_bf16 v[0:3], v[156:159], v[204:207], v[0:3]
	s_barrier
	s_setprio 0
	s_add_i32 s86, 0, 0x18000
	s_add_i32 s87, 0, 0x1c000
	v_add_u32_e32 v136, s86, v184
	v_add_u32_e32 v156, s87, v184
	ds_read_b128 v[104:107], v136
	ds_read_b128 v[108:111], v136 offset:1024
	ds_read_b128 v[132:135], v136 offset:2048
	ds_read_b128 v[136:139], v136 offset:3072
	ds_read_b128 v[144:147], v156
	ds_read_b128 v[148:151], v156 offset:1024
	ds_read_b128 v[152:155], v156 offset:2048
	ds_read_b128 v[156:159], v156 offset:3072
	s_add_u32 s56, s56, 0x80000
	s_addc_u32 s57, s57, 0
	s_mov_b32 m0, s80
	ds_read_b128 v[160:163], v185 offset:32768
	ds_read_b128 v[164:167], v185 offset:33792
	ds_read_b128 v[168:171], v185 offset:34816
	ds_read_b128 v[172:175], v185 offset:35840
	ds_read_b128 v[186:189], v185 offset:36864
	ds_read_b128 v[190:193], v185 offset:37888
	ds_read_b128 v[200:203], v185 offset:38912
	ds_read_b128 v[204:207], v185 offset:39936
	s_nop 0
	global_load_lds_dwordx4 v179, s[56:57]
	s_mov_b32 m0, s48
	s_nop 0
	global_load_lds_dwordx4 v182, s[56:57]
	s_waitcnt vmcnt(8)
	s_waitcnt lgkmcnt(0)
	s_setprio 1
	s_barrier
	v_mfma_f32_16x16x32_bf16 v[140:143], v[104:107], v[160:163], v[140:143]
	v_mfma_f32_16x16x32_bf16 v[140:143], v[108:111], v[164:167], v[140:143]
	v_mfma_f32_16x16x32_bf16 v[128:131], v[132:135], v[160:163], v[128:131]
	v_mfma_f32_16x16x32_bf16 v[128:131], v[136:139], v[164:167], v[128:131]
	v_mfma_f32_16x16x32_bf16 v[124:127], v[104:107], v[168:171], v[124:127]
	v_mfma_f32_16x16x32_bf16 v[124:127], v[108:111], v[172:175], v[124:127]
	v_mfma_f32_16x16x32_bf16 v[112:115], v[132:135], v[168:171], v[112:115]
	v_mfma_f32_16x16x32_bf16 v[112:115], v[136:139], v[172:175], v[112:115]
	v_mfma_f32_16x16x32_bf16 v[96:99], v[104:107], v[186:189], v[96:99]
	v_mfma_f32_16x16x32_bf16 v[96:99], v[108:111], v[190:193], v[96:99]
	v_mfma_f32_16x16x32_bf16 v[88:91], v[132:135], v[186:189], v[88:91]
	v_mfma_f32_16x16x32_bf16 v[88:91], v[136:139], v[190:193], v[88:91]
	v_mfma_f32_16x16x32_bf16 v[84:87], v[104:107], v[200:203], v[84:87]
	v_mfma_f32_16x16x32_bf16 v[84:87], v[108:111], v[204:207], v[84:87]
	v_mfma_f32_16x16x32_bf16 v[72:75], v[132:135], v[200:203], v[72:75]
	v_mfma_f32_16x16x32_bf16 v[72:75], v[136:139], v[204:207], v[72:75]
	v_mfma_f32_16x16x32_bf16 v[120:123], v[144:147], v[160:163], v[120:123]
	v_mfma_f32_16x16x32_bf16 v[120:123], v[148:151], v[164:167], v[120:123]
	v_mfma_f32_16x16x32_bf16 v[116:119], v[152:155], v[160:163], v[116:119]
	v_mfma_f32_16x16x32_bf16 v[116:119], v[156:159], v[164:167], v[116:119]
	v_mfma_f32_16x16x32_bf16 v[100:103], v[144:147], v[168:171], v[100:103]
	v_mfma_f32_16x16x32_bf16 v[100:103], v[148:151], v[172:175], v[100:103]
	v_mfma_f32_16x16x32_bf16 v[92:95], v[152:155], v[168:171], v[92:95]
	v_mfma_f32_16x16x32_bf16 v[92:95], v[156:159], v[172:175], v[92:95]
	v_mfma_f32_16x16x32_bf16 v[80:83], v[144:147], v[186:189], v[80:83]
	v_mfma_f32_16x16x32_bf16 v[80:83], v[148:151], v[190:193], v[80:83]
	v_mfma_f32_16x16x32_bf16 v[76:79], v[152:155], v[186:189], v[76:79]
	v_mfma_f32_16x16x32_bf16 v[76:79], v[156:159], v[190:193], v[76:79]
	v_mfma_f32_16x16x32_bf16 v[68:71], v[144:147], v[200:203], v[68:71]
	v_mfma_f32_16x16x32_bf16 v[68:71], v[148:151], v[204:207], v[68:71]
	v_mfma_f32_16x16x32_bf16 v[64:67], v[152:155], v[200:203], v[64:67]
	v_mfma_f32_16x16x32_bf16 v[64:67], v[156:159], v[204:207], v[64:67]
	s_barrier
	s_setprio 0
	s_add_u32 s56, s84, 0x80
	s_addc_u32 s57, s85, 0
	s_add_i32 s86, s86, s97
	s_mov_b32 m0, s86
	ds_read_b128 v[160:163], v185 offset:49152
	ds_read_b128 v[164:167], v185 offset:50176
	ds_read_b128 v[168:171], v185 offset:51200
	ds_read_b128 v[172:175], v185 offset:52224
	ds_read_b128 v[186:189], v185 offset:53248
	ds_read_b128 v[190:193], v185 offset:54272
	ds_read_b128 v[200:203], v185 offset:55296
	ds_read_b128 v[204:207], v185 offset:56320
	s_nop 0
	global_load_lds_dwordx4 v181, s[56:57]
	s_add_i32 m0, s86, 0x2000
	s_nop 0
	global_load_lds_dwordx4 v183, s[56:57]
	s_add_u32 s56, s84, 0x80080
	s_addc_u32 s57, s85, 0
	s_add_i32 s84, s87, s97
	s_mov_b32 m0, s84
	s_nop 0
	global_load_lds_dwordx4 v181, s[56:57]
	s_add_i32 m0, s84, 0x2000
	s_nop 0
	global_load_lds_dwordx4 v183, s[56:57]
	s_mov_b32 m0, s81
	s_nop 0
	global_load_lds_dwordx4 v179, s[12:13]
	s_mov_b32 m0, s70
	s_nop 0
	global_load_lds_dwordx4 v182, s[12:13]
	s_waitcnt vmcnt(8)
	s_waitcnt lgkmcnt(0)
	s_setprio 1
	s_barrier
	v_mfma_f32_16x16x32_bf16 v[60:63], v[104:107], v[160:163], v[60:63]
	v_mfma_f32_16x16x32_bf16 v[60:63], v[108:111], v[164:167], v[60:63]
	v_mfma_f32_16x16x32_bf16 v[56:59], v[132:135], v[160:163], v[56:59]
	v_mfma_f32_16x16x32_bf16 v[56:59], v[136:139], v[164:167], v[56:59]
	v_mfma_f32_16x16x32_bf16 v[48:51], v[104:107], v[168:171], v[48:51]
	v_mfma_f32_16x16x32_bf16 v[48:51], v[108:111], v[172:175], v[48:51]
	v_mfma_f32_16x16x32_bf16 v[40:43], v[132:135], v[168:171], v[40:43]
	v_mfma_f32_16x16x32_bf16 v[40:43], v[136:139], v[172:175], v[40:43]
	v_mfma_f32_16x16x32_bf16 v[32:35], v[104:107], v[186:189], v[32:35]
	v_mfma_f32_16x16x32_bf16 v[32:35], v[108:111], v[190:193], v[32:35]
	v_mfma_f32_16x16x32_bf16 v[24:27], v[132:135], v[186:189], v[24:27]
	v_mfma_f32_16x16x32_bf16 v[24:27], v[136:139], v[190:193], v[24:27]
	v_mfma_f32_16x16x32_bf16 v[16:19], v[104:107], v[200:203], v[16:19]
	v_mfma_f32_16x16x32_bf16 v[16:19], v[108:111], v[204:207], v[16:19]
	v_mfma_f32_16x16x32_bf16 v[8:11], v[132:135], v[200:203], v[8:11]
	v_mfma_f32_16x16x32_bf16 v[8:11], v[136:139], v[204:207], v[8:11]
	v_mfma_f32_16x16x32_bf16 v[52:55], v[144:147], v[160:163], v[52:55]
	v_mfma_f32_16x16x32_bf16 v[52:55], v[148:151], v[164:167], v[52:55]
	v_mfma_f32_16x16x32_bf16 v[44:47], v[152:155], v[160:163], v[44:47]
	v_mfma_f32_16x16x32_bf16 v[44:47], v[156:159], v[164:167], v[44:47]
	v_mfma_f32_16x16x32_bf16 v[36:39], v[144:147], v[168:171], v[36:39]
	v_mfma_f32_16x16x32_bf16 v[36:39], v[148:151], v[172:175], v[36:39]
	v_mfma_f32_16x16x32_bf16 v[28:31], v[152:155], v[168:171], v[28:31]
	v_mfma_f32_16x16x32_bf16 v[28:31], v[156:159], v[172:175], v[28:31]
	v_mfma_f32_16x16x32_bf16 v[20:23], v[144:147], v[186:189], v[20:23]
	v_mfma_f32_16x16x32_bf16 v[20:23], v[148:151], v[190:193], v[20:23]
	v_mfma_f32_16x16x32_bf16 v[12:15], v[152:155], v[186:189], v[12:15]
	v_mfma_f32_16x16x32_bf16 v[12:15], v[156:159], v[190:193], v[12:15]
	v_mfma_f32_16x16x32_bf16 v[4:7], v[144:147], v[200:203], v[4:7]
	v_mfma_f32_16x16x32_bf16 v[4:7], v[148:151], v[204:207], v[4:7]
	v_mfma_f32_16x16x32_bf16 v[0:3], v[152:155], v[200:203], v[0:3]
	v_mfma_f32_16x16x32_bf16 v[0:3], v[156:159], v[204:207], v[0:3]
	s_barrier
	s_setprio 0
	s_add_i32 s83, s83, 2
	s_add_u32 s39, s39, 0x100
	s_addc_u32 s69, s69, 0
	s_add_u32 s72, s72, 0x100
	s_addc_u32 s74, s74, 0
	s_add_u32 s8, s8, 0x100
	s_addc_u32 s9, s9, 0
	s_cmp_gt_u32 s83, 29
	s_cbranch_scc0 .LBB0_1050
	s_and_b64 vcc, exec, s[60:61]
	s_cbranch_vccz .LBB0_1053
	s_barrier

.LBB0_1127:
	s_cmp_eq_u32 s21, 4
	s_cselect_b32 s38, s22, s4
	s_cselect_b32 s39, s23, s5
	s_cselect_b32 s36, s24, s15
	s_cselect_b32 s37, s25, s17
	s_add_u32 s34, s38, 0x80
	s_addc_u32 s35, s39, 0
	s_add_i32 s65, 0, 0x10000
	s_add_i32 s69, 0, 0x14000
	v_add_u32_e32 v132, s65, v154
	v_add_u32_e32 v148, s69, v154
	ds_read_b128 v[112:115], v132
	ds_read_b128 v[120:123], v132 offset:1024
	ds_read_b128 v[128:131], v132 offset:2048
	ds_read_b128 v[132:135], v132 offset:3072
	ds_read_b128 v[144:147], v148
	ds_read_b128 v[156:159], v148 offset:1024
	ds_read_b128 v[160:163], v148 offset:2048
	ds_read_b128 v[164:167], v148 offset:3072
	s_add_u32 s56, s4, 0x7ff80
	s_addc_u32 s57, s5, 0
	s_add_i32 m0, s27, 0xc000
	ds_read_b128 v[168:171], v155
	ds_read_b128 v[172:175], v155 offset:1024
	ds_read_b128 v[176:179], v155 offset:2048
	ds_read_b128 v[180:183], v155 offset:3072
	ds_read_b128 v[184:187], v155 offset:4096
	ds_read_b128 v[188:191], v155 offset:5120
	ds_read_b128 v[192:195], v155 offset:6144
	ds_read_b128 v[200:203], v155 offset:7168
	s_nop 0
	global_load_lds_dwordx4 v151, s[56:57]
	s_add_i32 m0, s27, 0xe000
	s_nop 0
	global_load_lds_dwordx4 v150, s[56:57]
	s_waitcnt vmcnt(8)
	s_waitcnt lgkmcnt(0)
	s_setprio 1
	s_barrier
	v_mfma_f32_16x16x32_bf16 v[140:143], v[112:115], v[168:171], v[140:143]
	v_mfma_f32_16x16x32_bf16 v[140:143], v[120:123], v[172:175], v[140:143]
	v_mfma_f32_16x16x32_bf16 v[136:139], v[128:131], v[168:171], v[136:139]
	v_mfma_f32_16x16x32_bf16 v[136:139], v[132:135], v[172:175], v[136:139]
	v_mfma_f32_16x16x32_bf16 v[108:111], v[112:115], v[176:179], v[108:111]
	v_mfma_f32_16x16x32_bf16 v[108:111], v[120:123], v[180:183], v[108:111]
	v_mfma_f32_16x16x32_bf16 v[104:107], v[128:131], v[176:179], v[104:107]
	v_mfma_f32_16x16x32_bf16 v[104:107], v[132:135], v[180:183], v[104:107]
	v_mfma_f32_16x16x32_bf16 v[92:95], v[112:115], v[184:187], v[92:95]
	v_mfma_f32_16x16x32_bf16 v[92:95], v[120:123], v[188:191], v[92:95]
	v_mfma_f32_16x16x32_bf16 v[88:91], v[128:131], v[184:187], v[88:91]
	v_mfma_f32_16x16x32_bf16 v[88:91], v[132:135], v[188:191], v[88:91]
	v_mfma_f32_16x16x32_bf16 v[76:79], v[112:115], v[192:195], v[76:79]
	v_mfma_f32_16x16x32_bf16 v[76:79], v[120:123], v[200:203], v[76:79]
	v_mfma_f32_16x16x32_bf16 v[72:75], v[128:131], v[192:195], v[72:75]
	v_mfma_f32_16x16x32_bf16 v[72:75], v[132:135], v[200:203], v[72:75]
	v_mfma_f32_16x16x32_bf16 v[124:127], v[144:147], v[168:171], v[124:127]
	v_mfma_f32_16x16x32_bf16 v[124:127], v[156:159], v[172:175], v[124:127]
	v_mfma_f32_16x16x32_bf16 v[116:119], v[160:163], v[168:171], v[116:119]
	v_mfma_f32_16x16x32_bf16 v[116:119], v[164:167], v[172:175], v[116:119]
	v_mfma_f32_16x16x32_bf16 v[100:103], v[144:147], v[176:179], v[100:103]
	v_mfma_f32_16x16x32_bf16 v[100:103], v[156:159], v[180:183], v[100:103]
	v_mfma_f32_16x16x32_bf16 v[96:99], v[160:163], v[176:179], v[96:99]
	v_mfma_f32_16x16x32_bf16 v[96:99], v[164:167], v[180:183], v[96:99]
	v_mfma_f32_16x16x32_bf16 v[84:87], v[144:147], v[184:187], v[84:87]
	v_mfma_f32_16x16x32_bf16 v[84:87], v[156:159], v[188:191], v[84:87]
	v_mfma_f32_16x16x32_bf16 v[80:83], v[160:163], v[184:187], v[80:83]
	v_mfma_f32_16x16x32_bf16 v[80:83], v[164:167], v[188:191], v[80:83]
	v_mfma_f32_16x16x32_bf16 v[68:71], v[144:147], v[192:195], v[68:71]
	v_mfma_f32_16x16x32_bf16 v[68:71], v[156:159], v[200:203], v[68:71]
	v_mfma_f32_16x16x32_bf16 v[64:67], v[160:163], v[192:195], v[64:67]
	v_mfma_f32_16x16x32_bf16 v[64:67], v[164:167], v[200:203], v[64:67]
	s_barrier
	s_setprio 0
	s_add_i32 s65, s65, s97
	s_mov_b64 s[56:57], s[36:37]
	s_mov_b32 m0, s65
	ds_read_b128 v[168:171], v155 offset:16384
	ds_read_b128 v[172:175], v155 offset:17408
	ds_read_b128 v[176:179], v155 offset:18432
	ds_read_b128 v[180:183], v155 offset:19456
	ds_read_b128 v[184:187], v155 offset:20480
	ds_read_b128 v[188:191], v155 offset:21504
	ds_read_b128 v[192:195], v155 offset:22528
	ds_read_b128 v[200:203], v155 offset:23552
	s_nop 0
	global_load_lds_dwordx4 v152, s[56:57]
	s_add_i32 m0, s65, 0x2000
	s_nop 0
	global_load_lds_dwordx4 v153, s[56:57]
	s_add_u32 s56, s36, 0x80000
	s_addc_u32 s57, s37, 0
	s_add_i32 s65, s69, s97
	s_mov_b32 m0, s65
	s_nop 0
	global_load_lds_dwordx4 v152, s[56:57]
	s_add_i32 m0, s65, 0x2000
	s_nop 0
	global_load_lds_dwordx4 v153, s[56:57]
	s_mov_b64 s[56:57], s[38:39]
	s_mov_b32 m0, s27
	s_nop 0
	global_load_lds_dwordx4 v151, s[56:57]
	s_mov_b32 m0, s29
	s_nop 0
	global_load_lds_dwordx4 v150, s[56:57]
	s_waitcnt vmcnt(8)
	s_waitcnt lgkmcnt(0)
	s_setprio 1
	s_barrier
	v_mfma_f32_16x16x32_bf16 v[60:63], v[112:115], v[168:171], v[60:63]
	v_mfma_f32_16x16x32_bf16 v[60:63], v[120:123], v[172:175], v[60:63]
	v_mfma_f32_16x16x32_bf16 v[56:59], v[128:131], v[168:171], v[56:59]
	v_mfma_f32_16x16x32_bf16 v[56:59], v[132:135], v[172:175], v[56:59]
	v_mfma_f32_16x16x32_bf16 v[52:55], v[112:115], v[176:179], v[52:55]
	v_mfma_f32_16x16x32_bf16 v[52:55], v[120:123], v[180:183], v[52:55]
	v_mfma_f32_16x16x32_bf16 v[44:47], v[128:131], v[176:179], v[44:47]
	v_mfma_f32_16x16x32_bf16 v[44:47], v[132:135], v[180:183], v[44:47]
	v_mfma_f32_16x16x32_bf16 v[36:39], v[112:115], v[184:187], v[36:39]
	v_mfma_f32_16x16x32_bf16 v[36:39], v[120:123], v[188:191], v[36:39]
	v_mfma_f32_16x16x32_bf16 v[28:31], v[128:131], v[184:187], v[28:31]
	v_mfma_f32_16x16x32_bf16 v[28:31], v[132:135], v[188:191], v[28:31]
	v_mfma_f32_16x16x32_bf16 v[20:23], v[112:115], v[192:195], v[20:23]
	v_mfma_f32_16x16x32_bf16 v[20:23], v[120:123], v[200:203], v[20:23]
	v_mfma_f32_16x16x32_bf16 v[8:11], v[128:131], v[192:195], v[8:11]
	v_mfma_f32_16x16x32_bf16 v[8:11], v[132:135], v[200:203], v[8:11]
	v_mfma_f32_16x16x32_bf16 v[48:51], v[144:147], v[168:171], v[48:51]
	v_mfma_f32_16x16x32_bf16 v[48:51], v[156:159], v[172:175], v[48:51]
	v_mfma_f32_16x16x32_bf16 v[40:43], v[160:163], v[168:171], v[40:43]
	v_mfma_f32_16x16x32_bf16 v[40:43], v[164:167], v[172:175], v[40:43]
	v_mfma_f32_16x16x32_bf16 v[32:35], v[144:147], v[176:179], v[32:35]
	v_mfma_f32_16x16x32_bf16 v[32:35], v[156:159], v[180:183], v[32:35]
	v_mfma_f32_16x16x32_bf16 v[24:27], v[160:163], v[176:179], v[24:27]
	v_mfma_f32_16x16x32_bf16 v[24:27], v[164:167], v[180:183], v[24:27]
	v_mfma_f32_16x16x32_bf16 v[16:19], v[144:147], v[184:187], v[16:19]
	v_mfma_f32_16x16x32_bf16 v[16:19], v[156:159], v[188:191], v[16:19]
	v_mfma_f32_16x16x32_bf16 v[12:15], v[160:163], v[184:187], v[12:15]
	v_mfma_f32_16x16x32_bf16 v[12:15], v[164:167], v[188:191], v[12:15]
	v_mfma_f32_16x16x32_bf16 v[4:7], v[144:147], v[192:195], v[4:7]
	v_mfma_f32_16x16x32_bf16 v[4:7], v[156:159], v[200:203], v[4:7]
	v_mfma_f32_16x16x32_bf16 v[0:3], v[160:163], v[192:195], v[0:3]
	v_mfma_f32_16x16x32_bf16 v[0:3], v[164:167], v[200:203], v[0:3]
	s_barrier
	s_setprio 0
	s_add_i32 s56, 0, 0x18000
	s_add_i32 s57, 0, 0x1c000
	v_add_u32_e32 v132, s56, v154
	v_add_u32_e32 v148, s57, v154
	ds_read_b128 v[112:115], v132
	ds_read_b128 v[120:123], v132 offset:1024
	ds_read_b128 v[128:131], v132 offset:2048
	ds_read_b128 v[132:135], v132 offset:3072
	ds_read_b128 v[144:147], v148
	ds_read_b128 v[156:159], v148 offset:1024
	ds_read_b128 v[160:163], v148 offset:2048
	ds_read_b128 v[164:167], v148 offset:3072
	s_add_u32 s38, s38, 0x80000
	s_addc_u32 s39, s39, 0
	s_mov_b32 m0, s31
	ds_read_b128 v[168:171], v155 offset:32768
	ds_read_b128 v[172:175], v155 offset:33792
	ds_read_b128 v[176:179], v155 offset:34816
	ds_read_b128 v[180:183], v155 offset:35840
	ds_read_b128 v[184:187], v155 offset:36864
	ds_read_b128 v[188:191], v155 offset:37888
	ds_read_b128 v[192:195], v155 offset:38912
	ds_read_b128 v[200:203], v155 offset:39936
	s_nop 0
	global_load_lds_dwordx4 v151, s[38:39]
	s_mov_b32 m0, s46
	s_nop 0
	global_load_lds_dwordx4 v150, s[38:39]
	s_waitcnt vmcnt(8)
	s_waitcnt lgkmcnt(0)
	s_setprio 1
	s_barrier
	v_mfma_f32_16x16x32_bf16 v[140:143], v[112:115], v[168:171], v[140:143]
	v_mfma_f32_16x16x32_bf16 v[140:143], v[120:123], v[172:175], v[140:143]
	v_mfma_f32_16x16x32_bf16 v[136:139], v[128:131], v[168:171], v[136:139]
	v_mfma_f32_16x16x32_bf16 v[136:139], v[132:135], v[172:175], v[136:139]
	v_mfma_f32_16x16x32_bf16 v[108:111], v[112:115], v[176:179], v[108:111]
	v_mfma_f32_16x16x32_bf16 v[108:111], v[120:123], v[180:183], v[108:111]
	v_mfma_f32_16x16x32_bf16 v[104:107], v[128:131], v[176:179], v[104:107]
	v_mfma_f32_16x16x32_bf16 v[104:107], v[132:135], v[180:183], v[104:107]
	v_mfma_f32_16x16x32_bf16 v[92:95], v[112:115], v[184:187], v[92:95]
	v_mfma_f32_16x16x32_bf16 v[92:95], v[120:123], v[188:191], v[92:95]
	v_mfma_f32_16x16x32_bf16 v[88:91], v[128:131], v[184:187], v[88:91]
	v_mfma_f32_16x16x32_bf16 v[88:91], v[132:135], v[188:191], v[88:91]
	v_mfma_f32_16x16x32_bf16 v[76:79], v[112:115], v[192:195], v[76:79]
	v_mfma_f32_16x16x32_bf16 v[76:79], v[120:123], v[200:203], v[76:79]
	v_mfma_f32_16x16x32_bf16 v[72:75], v[128:131], v[192:195], v[72:75]
	v_mfma_f32_16x16x32_bf16 v[72:75], v[132:135], v[200:203], v[72:75]
	v_mfma_f32_16x16x32_bf16 v[124:127], v[144:147], v[168:171], v[124:127]
	v_mfma_f32_16x16x32_bf16 v[124:127], v[156:159], v[172:175], v[124:127]
	v_mfma_f32_16x16x32_bf16 v[116:119], v[160:163], v[168:171], v[116:119]
	v_mfma_f32_16x16x32_bf16 v[116:119], v[164:167], v[172:175], v[116:119]
	v_mfma_f32_16x16x32_bf16 v[100:103], v[144:147], v[176:179], v[100:103]
	v_mfma_f32_16x16x32_bf16 v[100:103], v[156:159], v[180:183], v[100:103]
	v_mfma_f32_16x16x32_bf16 v[96:99], v[160:163], v[176:179], v[96:99]
	v_mfma_f32_16x16x32_bf16 v[96:99], v[164:167], v[180:183], v[96:99]
	v_mfma_f32_16x16x32_bf16 v[84:87], v[144:147], v[184:187], v[84:87]
	v_mfma_f32_16x16x32_bf16 v[84:87], v[156:159], v[188:191], v[84:87]
	v_mfma_f32_16x16x32_bf16 v[80:83], v[160:163], v[184:187], v[80:83]
	v_mfma_f32_16x16x32_bf16 v[80:83], v[164:167], v[188:191], v[80:83]
	v_mfma_f32_16x16x32_bf16 v[68:71], v[144:147], v[192:195], v[68:71]
	v_mfma_f32_16x16x32_bf16 v[68:71], v[156:159], v[200:203], v[68:71]
	v_mfma_f32_16x16x32_bf16 v[64:67], v[160:163], v[192:195], v[64:67]
	v_mfma_f32_16x16x32_bf16 v[64:67], v[164:167], v[200:203], v[64:67]
	s_barrier
	s_setprio 0
	s_add_u32 s38, s36, 0x80
	s_addc_u32 s39, s37, 0
	s_add_i32 s56, s56, s97
	s_mov_b32 m0, s56
	ds_read_b128 v[168:171], v155 offset:49152
	ds_read_b128 v[172:175], v155 offset:50176
	ds_read_b128 v[176:179], v155 offset:51200
	ds_read_b128 v[180:183], v155 offset:52224
	ds_read_b128 v[184:187], v155 offset:53248
	ds_read_b128 v[188:191], v155 offset:54272
	ds_read_b128 v[192:195], v155 offset:55296
	ds_read_b128 v[200:203], v155 offset:56320
	s_nop 0
	global_load_lds_dwordx4 v152, s[38:39]
	s_add_i32 m0, s56, 0x2000
	s_add_u32 s36, s36, 0x80080
	s_addc_u32 s37, s37, 0
	global_load_lds_dwordx4 v153, s[38:39]
	s_add_i32 s38, s57, s97
	s_mov_b32 m0, s38
	s_nop 0
	global_load_lds_dwordx4 v152, s[36:37]
	s_add_i32 m0, s38, 0x2000
	s_nop 0
	global_load_lds_dwordx4 v153, s[36:37]
	s_mov_b32 m0, s47
	s_nop 0
	global_load_lds_dwordx4 v151, s[34:35]
	s_mov_b32 m0, s48
	s_nop 0
	global_load_lds_dwordx4 v150, s[34:35]
	s_waitcnt vmcnt(8)
	s_waitcnt lgkmcnt(0)
	s_setprio 1
	s_barrier
	v_mfma_f32_16x16x32_bf16 v[60:63], v[112:115], v[168:171], v[60:63]
	v_mfma_f32_16x16x32_bf16 v[60:63], v[120:123], v[172:175], v[60:63]
	v_mfma_f32_16x16x32_bf16 v[56:59], v[128:131], v[168:171], v[56:59]
	v_mfma_f32_16x16x32_bf16 v[56:59], v[132:135], v[172:175], v[56:59]
	v_mfma_f32_16x16x32_bf16 v[52:55], v[112:115], v[176:179], v[52:55]
	v_mfma_f32_16x16x32_bf16 v[52:55], v[120:123], v[180:183], v[52:55]
	v_mfma_f32_16x16x32_bf16 v[44:47], v[128:131], v[176:179], v[44:47]
	v_mfma_f32_16x16x32_bf16 v[44:47], v[132:135], v[180:183], v[44:47]
	v_mfma_f32_16x16x32_bf16 v[36:39], v[112:115], v[184:187], v[36:39]
	v_mfma_f32_16x16x32_bf16 v[36:39], v[120:123], v[188:191], v[36:39]
	v_mfma_f32_16x16x32_bf16 v[28:31], v[128:131], v[184:187], v[28:31]
	v_mfma_f32_16x16x32_bf16 v[28:31], v[132:135], v[188:191], v[28:31]
	v_mfma_f32_16x16x32_bf16 v[20:23], v[112:115], v[192:195], v[20:23]
	v_mfma_f32_16x16x32_bf16 v[20:23], v[120:123], v[200:203], v[20:23]
	v_mfma_f32_16x16x32_bf16 v[8:11], v[128:131], v[192:195], v[8:11]
	v_mfma_f32_16x16x32_bf16 v[8:11], v[132:135], v[200:203], v[8:11]
	v_mfma_f32_16x16x32_bf16 v[48:51], v[144:147], v[168:171], v[48:51]
	v_mfma_f32_16x16x32_bf16 v[48:51], v[156:159], v[172:175], v[48:51]
	v_mfma_f32_16x16x32_bf16 v[40:43], v[160:163], v[168:171], v[40:43]
	v_mfma_f32_16x16x32_bf16 v[40:43], v[164:167], v[172:175], v[40:43]
	v_mfma_f32_16x16x32_bf16 v[32:35], v[144:147], v[176:179], v[32:35]
	v_mfma_f32_16x16x32_bf16 v[32:35], v[156:159], v[180:183], v[32:35]
	v_mfma_f32_16x16x32_bf16 v[24:27], v[160:163], v[176:179], v[24:27]
	v_mfma_f32_16x16x32_bf16 v[24:27], v[164:167], v[180:183], v[24:27]
	v_mfma_f32_16x16x32_bf16 v[16:19], v[144:147], v[184:187], v[16:19]
	v_mfma_f32_16x16x32_bf16 v[16:19], v[156:159], v[188:191], v[16:19]
	v_mfma_f32_16x16x32_bf16 v[12:15], v[160:163], v[184:187], v[12:15]
	v_mfma_f32_16x16x32_bf16 v[12:15], v[164:167], v[188:191], v[12:15]
	v_mfma_f32_16x16x32_bf16 v[4:7], v[144:147], v[192:195], v[4:7]
	v_mfma_f32_16x16x32_bf16 v[4:7], v[156:159], v[200:203], v[4:7]
	v_mfma_f32_16x16x32_bf16 v[0:3], v[160:163], v[192:195], v[0:3]
	v_mfma_f32_16x16x32_bf16 v[0:3], v[164:167], v[200:203], v[0:3]
	s_barrier
	s_setprio 0
	s_add_i32 s21, s21, 2
	s_add_u32 s4, s4, 0x100
	s_addc_u32 s5, s5, 0
	s_add_u32 s15, s15, 0x100
	s_addc_u32 s17, s17, 0
	s_cmp_gt_u32 s21, 5
	s_cbranch_scc0 .LBB0_1127
	s_and_b64 vcc, exec, s[60:61]
	s_cbranch_vccz .LBB0_1130
	s_barrier

.LBB0_1253:
	s_add_u32 s34, s10, 0x100
	s_addc_u32 s35, s11, 0
	s_cmp_eq_u32 vcc_hi, 28
	s_cselect_b32 s40, s5, s34
	s_cselect_b32 s41, s4, s35
	s_cselect_b32 s38, s25, s27
	s_cselect_b32 s39, s9, vcc_lo
	s_add_u32 s36, s40, 0x80
	s_addc_u32 s37, s41, 0
	s_add_i32 s75, 0, 0x10000
	s_add_i32 s46, 0, 0x14000
	v_add_u32_e32 v140, s75, v196
	v_add_u32_e32 v156, s46, v196
	ds_read_b128 v[128:131], v140
	ds_read_b128 v[132:135], v140 offset:1024
	ds_read_b128 v[136:139], v140 offset:2048
	ds_read_b128 v[140:143], v140 offset:3072
	ds_read_b128 v[144:147], v156
	ds_read_b128 v[148:151], v156 offset:1024
	ds_read_b128 v[152:155], v156 offset:2048
	ds_read_b128 v[156:159], v156 offset:3072
	s_add_u32 s10, s10, 0x80080
	s_addc_u32 s11, s11, 0
	s_add_i32 m0, s15, 0xc000
	ds_read_b128 v[160:163], v200
	ds_read_b128 v[164:167], v200 offset:1024
	ds_read_b128 v[168:171], v200 offset:2048
	ds_read_b128 v[172:175], v200 offset:3072
	ds_read_b128 v[176:179], v200 offset:4096
	ds_read_b128 v[180:183], v200 offset:5120
	ds_read_b128 v[184:187], v200 offset:6144
	ds_read_b128 v[188:191], v200 offset:7168
	s_nop 0
	global_load_lds_dwordx4 v192, s[10:11]
	s_add_i32 m0, s15, 0xe000
	s_nop 0
	global_load_lds_dwordx4 v194, s[10:11]
	s_waitcnt vmcnt(8)
	s_waitcnt lgkmcnt(0)
	s_setprio 1
	s_barrier
	v_mfma_f32_16x16x32_bf16 v[124:127], v[128:131], v[160:163], v[124:127]
	v_mfma_f32_16x16x32_bf16 v[124:127], v[132:135], v[164:167], v[124:127]
	v_mfma_f32_16x16x32_bf16 v[60:63], v[136:139], v[160:163], v[60:63]
	v_mfma_f32_16x16x32_bf16 v[60:63], v[140:143], v[164:167], v[60:63]
	v_mfma_f32_16x16x32_bf16 v[120:123], v[128:131], v[168:171], v[120:123]
	v_mfma_f32_16x16x32_bf16 v[120:123], v[132:135], v[172:175], v[120:123]
	v_mfma_f32_16x16x32_bf16 v[56:59], v[136:139], v[168:171], v[56:59]
	v_mfma_f32_16x16x32_bf16 v[56:59], v[140:143], v[172:175], v[56:59]
	v_mfma_f32_16x16x32_bf16 v[116:119], v[128:131], v[176:179], v[116:119]
	v_mfma_f32_16x16x32_bf16 v[116:119], v[132:135], v[180:183], v[116:119]
	v_mfma_f32_16x16x32_bf16 v[52:55], v[136:139], v[176:179], v[52:55]
	v_mfma_f32_16x16x32_bf16 v[52:55], v[140:143], v[180:183], v[52:55]
	v_mfma_f32_16x16x32_bf16 v[112:115], v[128:131], v[184:187], v[112:115]
	v_mfma_f32_16x16x32_bf16 v[112:115], v[132:135], v[188:191], v[112:115]
	v_mfma_f32_16x16x32_bf16 v[48:51], v[136:139], v[184:187], v[48:51]
	v_mfma_f32_16x16x32_bf16 v[48:51], v[140:143], v[188:191], v[48:51]
	v_mfma_f32_16x16x32_bf16 v[108:111], v[144:147], v[160:163], v[108:111]
	v_mfma_f32_16x16x32_bf16 v[108:111], v[148:151], v[164:167], v[108:111]
	v_mfma_f32_16x16x32_bf16 v[44:47], v[152:155], v[160:163], v[44:47]
	v_mfma_f32_16x16x32_bf16 v[44:47], v[156:159], v[164:167], v[44:47]
	v_mfma_f32_16x16x32_bf16 v[104:107], v[144:147], v[168:171], v[104:107]
	v_mfma_f32_16x16x32_bf16 v[104:107], v[148:151], v[172:175], v[104:107]
	v_mfma_f32_16x16x32_bf16 v[40:43], v[152:155], v[168:171], v[40:43]
	v_mfma_f32_16x16x32_bf16 v[40:43], v[156:159], v[172:175], v[40:43]
	v_mfma_f32_16x16x32_bf16 v[100:103], v[144:147], v[176:179], v[100:103]
	v_mfma_f32_16x16x32_bf16 v[100:103], v[148:151], v[180:183], v[100:103]
	v_mfma_f32_16x16x32_bf16 v[36:39], v[152:155], v[176:179], v[36:39]
	v_mfma_f32_16x16x32_bf16 v[36:39], v[156:159], v[180:183], v[36:39]
	v_mfma_f32_16x16x32_bf16 v[96:99], v[144:147], v[184:187], v[96:99]
	v_mfma_f32_16x16x32_bf16 v[96:99], v[148:151], v[188:191], v[96:99]
	v_mfma_f32_16x16x32_bf16 v[32:35], v[152:155], v[184:187], v[32:35]
	v_mfma_f32_16x16x32_bf16 v[32:35], v[156:159], v[188:191], v[32:35]
	s_barrier
	s_setprio 0
	s_add_i32 s47, s75, s97
	s_mov_b64 s[10:11], s[38:39]
	s_mov_b32 m0, s47
	ds_read_b128 v[160:163], v200 offset:16384
	ds_read_b128 v[164:167], v200 offset:17408
	ds_read_b128 v[168:171], v200 offset:18432
	ds_read_b128 v[172:175], v200 offset:19456
	ds_read_b128 v[176:179], v200 offset:20480
	ds_read_b128 v[180:183], v200 offset:21504
	ds_read_b128 v[184:187], v200 offset:22528
	ds_read_b128 v[188:191], v200 offset:23552
	s_nop 0
	global_load_lds_dwordx4 v193, s[10:11]
	s_add_i32 m0, s47, 0x2000
	s_nop 0
	global_load_lds_dwordx4 v195, s[10:11]
	s_add_u32 s10, s38, 0x80000
	s_addc_u32 s11, s39, 0
	s_add_i32 s46, s46, s97
	s_mov_b32 m0, s46
	s_nop 0
	global_load_lds_dwordx4 v193, s[10:11]
	s_add_i32 m0, s46, 0x2000
	s_nop 0
	global_load_lds_dwordx4 v195, s[10:11]
	s_mov_b64 s[10:11], s[40:41]
	s_mov_b32 m0, s15
	s_nop 0
	global_load_lds_dwordx4 v192, s[10:11]
	s_mov_b32 m0, s69
	s_nop 0
	global_load_lds_dwordx4 v194, s[10:11]
	s_waitcnt vmcnt(8)
	s_waitcnt lgkmcnt(0)
	s_setprio 1
	s_barrier
	v_mfma_f32_16x16x32_bf16 v[92:95], v[128:131], v[160:163], v[92:95]
	v_mfma_f32_16x16x32_bf16 v[92:95], v[132:135], v[164:167], v[92:95]
	v_mfma_f32_16x16x32_bf16 v[28:31], v[136:139], v[160:163], v[28:31]
	v_mfma_f32_16x16x32_bf16 v[28:31], v[140:143], v[164:167], v[28:31]
	v_mfma_f32_16x16x32_bf16 v[88:91], v[128:131], v[168:171], v[88:91]
	v_mfma_f32_16x16x32_bf16 v[88:91], v[132:135], v[172:175], v[88:91]
	v_mfma_f32_16x16x32_bf16 v[16:19], v[136:139], v[168:171], v[16:19]
	v_mfma_f32_16x16x32_bf16 v[16:19], v[140:143], v[172:175], v[16:19]
	v_mfma_f32_16x16x32_bf16 v[84:87], v[128:131], v[176:179], v[84:87]
	v_mfma_f32_16x16x32_bf16 v[84:87], v[132:135], v[180:183], v[84:87]
	v_mfma_f32_16x16x32_bf16 v[20:23], v[136:139], v[176:179], v[20:23]
	v_mfma_f32_16x16x32_bf16 v[20:23], v[140:143], v[180:183], v[20:23]
	v_mfma_f32_16x16x32_bf16 v[80:83], v[128:131], v[184:187], v[80:83]
	v_mfma_f32_16x16x32_bf16 v[80:83], v[132:135], v[188:191], v[80:83]
	v_mfma_f32_16x16x32_bf16 v[8:11], v[136:139], v[184:187], v[8:11]
	v_mfma_f32_16x16x32_bf16 v[8:11], v[140:143], v[188:191], v[8:11]
	v_mfma_f32_16x16x32_bf16 v[76:79], v[144:147], v[160:163], v[76:79]
	v_mfma_f32_16x16x32_bf16 v[76:79], v[148:151], v[164:167], v[76:79]
	v_mfma_f32_16x16x32_bf16 v[24:27], v[152:155], v[160:163], v[24:27]
	v_mfma_f32_16x16x32_bf16 v[24:27], v[156:159], v[164:167], v[24:27]
	v_mfma_f32_16x16x32_bf16 v[72:75], v[144:147], v[168:171], v[72:75]
	v_mfma_f32_16x16x32_bf16 v[72:75], v[148:151], v[172:175], v[72:75]
	v_mfma_f32_16x16x32_bf16 v[12:15], v[152:155], v[168:171], v[12:15]
	v_mfma_f32_16x16x32_bf16 v[12:15], v[156:159], v[172:175], v[12:15]
	v_mfma_f32_16x16x32_bf16 v[68:71], v[144:147], v[176:179], v[68:71]
	v_mfma_f32_16x16x32_bf16 v[68:71], v[148:151], v[180:183], v[68:71]
	v_mfma_f32_16x16x32_bf16 v[4:7], v[152:155], v[176:179], v[4:7]
	v_mfma_f32_16x16x32_bf16 v[4:7], v[156:159], v[180:183], v[4:7]
	v_mfma_f32_16x16x32_bf16 v[64:67], v[144:147], v[184:187], v[64:67]
	v_mfma_f32_16x16x32_bf16 v[64:67], v[148:151], v[188:191], v[64:67]
	v_mfma_f32_16x16x32_bf16 v[0:3], v[152:155], v[184:187], v[0:3]
	v_mfma_f32_16x16x32_bf16 v[0:3], v[156:159], v[188:191], v[0:3]
	s_barrier
	s_setprio 0
	s_add_i32 s46, 0, 0x18000
	s_add_i32 s47, 0, 0x1c000
	v_add_u32_e32 v140, s46, v196
	v_add_u32_e32 v156, s47, v196
	ds_read_b128 v[128:131], v140
	ds_read_b128 v[132:135], v140 offset:1024
	ds_read_b128 v[136:139], v140 offset:2048
	ds_read_b128 v[140:143], v140 offset:3072
	ds_read_b128 v[144:147], v156
	ds_read_b128 v[148:151], v156 offset:1024
	ds_read_b128 v[152:155], v156 offset:2048
	ds_read_b128 v[156:159], v156 offset:3072
	s_add_u32 s10, s40, 0x80000
	s_addc_u32 s11, s41, 0
	s_mov_b32 m0, s78
	ds_read_b128 v[160:163], v200 offset:32768
	ds_read_b128 v[164:167], v200 offset:33792
	ds_read_b128 v[168:171], v200 offset:34816
	ds_read_b128 v[172:175], v200 offset:35840
	ds_read_b128 v[176:179], v200 offset:36864
	ds_read_b128 v[180:183], v200 offset:37888
	ds_read_b128 v[184:187], v200 offset:38912
	ds_read_b128 v[188:191], v200 offset:39936
	s_nop 0
	global_load_lds_dwordx4 v192, s[10:11]
	s_mov_b32 m0, s80
	s_nop 0
	global_load_lds_dwordx4 v194, s[10:11]
	s_waitcnt vmcnt(8)
	s_waitcnt lgkmcnt(0)
	s_setprio 1
	s_barrier
	v_mfma_f32_16x16x32_bf16 v[124:127], v[128:131], v[160:163], v[124:127]
	v_mfma_f32_16x16x32_bf16 v[124:127], v[132:135], v[164:167], v[124:127]
	v_mfma_f32_16x16x32_bf16 v[60:63], v[136:139], v[160:163], v[60:63]
	v_mfma_f32_16x16x32_bf16 v[60:63], v[140:143], v[164:167], v[60:63]
	v_mfma_f32_16x16x32_bf16 v[120:123], v[128:131], v[168:171], v[120:123]
	v_mfma_f32_16x16x32_bf16 v[120:123], v[132:135], v[172:175], v[120:123]
	v_mfma_f32_16x16x32_bf16 v[56:59], v[136:139], v[168:171], v[56:59]
	v_mfma_f32_16x16x32_bf16 v[56:59], v[140:143], v[172:175], v[56:59]
	v_mfma_f32_16x16x32_bf16 v[116:119], v[128:131], v[176:179], v[116:119]
	v_mfma_f32_16x16x32_bf16 v[116:119], v[132:135], v[180:183], v[116:119]
	v_mfma_f32_16x16x32_bf16 v[52:55], v[136:139], v[176:179], v[52:55]
	v_mfma_f32_16x16x32_bf16 v[52:55], v[140:143], v[180:183], v[52:55]
	v_mfma_f32_16x16x32_bf16 v[112:115], v[128:131], v[184:187], v[112:115]
	v_mfma_f32_16x16x32_bf16 v[112:115], v[132:135], v[188:191], v[112:115]
	v_mfma_f32_16x16x32_bf16 v[48:51], v[136:139], v[184:187], v[48:51]
	v_mfma_f32_16x16x32_bf16 v[48:51], v[140:143], v[188:191], v[48:51]
	v_mfma_f32_16x16x32_bf16 v[108:111], v[144:147], v[160:163], v[108:111]
	v_mfma_f32_16x16x32_bf16 v[108:111], v[148:151], v[164:167], v[108:111]
	v_mfma_f32_16x16x32_bf16 v[44:47], v[152:155], v[160:163], v[44:47]
	v_mfma_f32_16x16x32_bf16 v[44:47], v[156:159], v[164:167], v[44:47]
	v_mfma_f32_16x16x32_bf16 v[104:107], v[144:147], v[168:171], v[104:107]
	v_mfma_f32_16x16x32_bf16 v[104:107], v[148:151], v[172:175], v[104:107]
	v_mfma_f32_16x16x32_bf16 v[40:43], v[152:155], v[168:171], v[40:43]
	v_mfma_f32_16x16x32_bf16 v[40:43], v[156:159], v[172:175], v[40:43]
	v_mfma_f32_16x16x32_bf16 v[100:103], v[144:147], v[176:179], v[100:103]
	v_mfma_f32_16x16x32_bf16 v[100:103], v[148:151], v[180:183], v[100:103]
	v_mfma_f32_16x16x32_bf16 v[36:39], v[152:155], v[176:179], v[36:39]
	v_mfma_f32_16x16x32_bf16 v[36:39], v[156:159], v[180:183], v[36:39]
	v_mfma_f32_16x16x32_bf16 v[96:99], v[144:147], v[184:187], v[96:99]
	v_mfma_f32_16x16x32_bf16 v[96:99], v[148:151], v[188:191], v[96:99]
	v_mfma_f32_16x16x32_bf16 v[32:35], v[152:155], v[184:187], v[32:35]
	v_mfma_f32_16x16x32_bf16 v[32:35], v[156:159], v[188:191], v[32:35]
	s_barrier
	s_setprio 0
	s_add_u32 s10, s38, 0x80
	s_addc_u32 s11, s39, 0
	s_add_i32 s40, s46, s97
	s_mov_b32 m0, s40
	ds_read_b128 v[160:163], v200 offset:49152
	ds_read_b128 v[164:167], v200 offset:50176
	ds_read_b128 v[168:171], v200 offset:51200
	ds_read_b128 v[172:175], v200 offset:52224
	ds_read_b128 v[176:179], v200 offset:53248
	ds_read_b128 v[180:183], v200 offset:54272
	ds_read_b128 v[184:187], v200 offset:55296
	ds_read_b128 v[188:191], v200 offset:56320
	s_nop 0
	global_load_lds_dwordx4 v193, s[10:11]
	s_add_i32 m0, s40, 0x2000
	s_nop 0
	global_load_lds_dwordx4 v195, s[10:11]
	s_add_u32 s10, s38, 0x80080
	s_addc_u32 s11, s39, 0
	s_add_i32 s38, s47, s97
	s_mov_b32 m0, s38
	s_nop 0
	global_load_lds_dwordx4 v193, s[10:11]
	s_add_i32 m0, s38, 0x2000
	s_nop 0
	global_load_lds_dwordx4 v195, s[10:11]
	s_mov_b32 m0, s85
	s_nop 0
	global_load_lds_dwordx4 v192, s[36:37]
	s_mov_b32 m0, s86
	s_nop 0
	global_load_lds_dwordx4 v194, s[36:37]
	s_waitcnt vmcnt(8)
	s_waitcnt lgkmcnt(0)
	s_setprio 1
	s_barrier
	v_mfma_f32_16x16x32_bf16 v[92:95], v[128:131], v[160:163], v[92:95]
	v_mfma_f32_16x16x32_bf16 v[92:95], v[132:135], v[164:167], v[92:95]
	v_mfma_f32_16x16x32_bf16 v[28:31], v[136:139], v[160:163], v[28:31]
	v_mfma_f32_16x16x32_bf16 v[28:31], v[140:143], v[164:167], v[28:31]
	v_mfma_f32_16x16x32_bf16 v[88:91], v[128:131], v[168:171], v[88:91]
	v_mfma_f32_16x16x32_bf16 v[88:91], v[132:135], v[172:175], v[88:91]
	v_mfma_f32_16x16x32_bf16 v[16:19], v[136:139], v[168:171], v[16:19]
	v_mfma_f32_16x16x32_bf16 v[16:19], v[140:143], v[172:175], v[16:19]
	v_mfma_f32_16x16x32_bf16 v[84:87], v[128:131], v[176:179], v[84:87]
	v_mfma_f32_16x16x32_bf16 v[84:87], v[132:135], v[180:183], v[84:87]
	v_mfma_f32_16x16x32_bf16 v[20:23], v[136:139], v[176:179], v[20:23]
	v_mfma_f32_16x16x32_bf16 v[20:23], v[140:143], v[180:183], v[20:23]
	v_mfma_f32_16x16x32_bf16 v[80:83], v[128:131], v[184:187], v[80:83]
	v_mfma_f32_16x16x32_bf16 v[80:83], v[132:135], v[188:191], v[80:83]
	v_mfma_f32_16x16x32_bf16 v[8:11], v[136:139], v[184:187], v[8:11]
	v_mfma_f32_16x16x32_bf16 v[8:11], v[140:143], v[188:191], v[8:11]
	v_mfma_f32_16x16x32_bf16 v[76:79], v[144:147], v[160:163], v[76:79]
	v_mfma_f32_16x16x32_bf16 v[76:79], v[148:151], v[164:167], v[76:79]
	v_mfma_f32_16x16x32_bf16 v[24:27], v[152:155], v[160:163], v[24:27]
	v_mfma_f32_16x16x32_bf16 v[24:27], v[156:159], v[164:167], v[24:27]
	v_mfma_f32_16x16x32_bf16 v[72:75], v[144:147], v[168:171], v[72:75]
	v_mfma_f32_16x16x32_bf16 v[72:75], v[148:151], v[172:175], v[72:75]
	v_mfma_f32_16x16x32_bf16 v[12:15], v[152:155], v[168:171], v[12:15]
	v_mfma_f32_16x16x32_bf16 v[12:15], v[156:159], v[172:175], v[12:15]
	v_mfma_f32_16x16x32_bf16 v[68:71], v[144:147], v[176:179], v[68:71]
	v_mfma_f32_16x16x32_bf16 v[68:71], v[148:151], v[180:183], v[68:71]
	v_mfma_f32_16x16x32_bf16 v[4:7], v[152:155], v[176:179], v[4:7]
	v_mfma_f32_16x16x32_bf16 v[4:7], v[156:159], v[180:183], v[4:7]
	v_mfma_f32_16x16x32_bf16 v[64:67], v[144:147], v[184:187], v[64:67]
	v_mfma_f32_16x16x32_bf16 v[64:67], v[148:151], v[188:191], v[64:67]
	v_mfma_f32_16x16x32_bf16 v[0:3], v[152:155], v[184:187], v[0:3]
	v_mfma_f32_16x16x32_bf16 v[0:3], v[156:159], v[188:191], v[0:3]
	s_barrier
	s_setprio 0
	s_add_i32 vcc_hi, vcc_hi, 2
	s_add_u32 s27, s27, 0x100
	s_addc_u32 vcc_lo, vcc_lo, 0
	s_cmp_gt_u32 vcc_hi, 29
	s_mov_b64 s[10:11], s[34:35]
	s_cbranch_scc0 .LBB0_1253
	s_and_b64 vcc, exec, s[60:61]
	s_cbranch_vccz .LBB0_1256
	s_barrier

.LBB0_1290:
	s_cmp_eq_u32 s21, 12
	s_cselect_b32 s40, s24, s4
	s_cselect_b32 s41, s25, s5
	s_cselect_b32 s38, s30, s15
	s_cselect_b32 s39, s31, s17
	s_add_u32 s36, s40, 0x80
	s_addc_u32 s37, s41, 0
	s_add_i32 s23, 0, 0x10000
	v_add_u32_e32 v128, s23, v134
	s_add_i32 s46, 0, 0x14000
	ds_read_b128 v[136:139], v128
	ds_read_b128 v[140:143], v128 offset:1024
	ds_read_b128 v[144:147], v128 offset:2048
	ds_read_b128 v[148:151], v128 offset:3072
	v_add_u32_e32 v128, s46, v134
	ds_read_b128 v[152:155], v128
	ds_read_b128 v[156:159], v128 offset:1024
	ds_read_b128 v[160:163], v128 offset:2048
	ds_read_b128 v[164:167], v128 offset:3072
	s_mov_b64 s[74:75], s[34:35]
	s_add_i32 m0, s27, 0xc000
	ds_read_b128 v[168:171], v135
	ds_read_b128 v[172:175], v135 offset:1024
	ds_read_b128 v[176:179], v135 offset:2048
	ds_read_b128 v[180:183], v135 offset:3072
	ds_read_b128 v[184:187], v135 offset:4096
	ds_read_b128 v[188:191], v135 offset:5120
	ds_read_b128 v[192:195], v135 offset:6144
	ds_read_b128 v[200:203], v135 offset:7168
	s_nop 0
	global_load_lds_dwordx4 v133, s[74:75]
	s_add_i32 m0, s27, 0xe000
	s_nop 0
	global_load_lds_dwordx4 v131, s[74:75]
	s_waitcnt vmcnt(8)
	s_waitcnt lgkmcnt(0)
	s_setprio 1
	s_barrier
	v_mfma_f32_16x16x32_bf16 v[124:127], v[136:139], v[168:171], v[124:127]
	v_mfma_f32_16x16x32_bf16 v[124:127], v[140:143], v[172:175], v[124:127]
	v_mfma_f32_16x16x32_bf16 v[120:123], v[144:147], v[168:171], v[120:123]
	v_mfma_f32_16x16x32_bf16 v[120:123], v[148:151], v[172:175], v[120:123]
	v_mfma_f32_16x16x32_bf16 v[116:119], v[136:139], v[176:179], v[116:119]
	v_mfma_f32_16x16x32_bf16 v[116:119], v[140:143], v[180:183], v[116:119]
	v_mfma_f32_16x16x32_bf16 v[108:111], v[144:147], v[176:179], v[108:111]
	v_mfma_f32_16x16x32_bf16 v[108:111], v[148:151], v[180:183], v[108:111]
	v_mfma_f32_16x16x32_bf16 v[100:103], v[136:139], v[184:187], v[100:103]
	v_mfma_f32_16x16x32_bf16 v[100:103], v[140:143], v[188:191], v[100:103]
	v_mfma_f32_16x16x32_bf16 v[92:95], v[144:147], v[184:187], v[92:95]
	v_mfma_f32_16x16x32_bf16 v[92:95], v[148:151], v[188:191], v[92:95]
	v_mfma_f32_16x16x32_bf16 v[84:87], v[136:139], v[192:195], v[84:87]
	v_mfma_f32_16x16x32_bf16 v[84:87], v[140:143], v[200:203], v[84:87]
	v_mfma_f32_16x16x32_bf16 v[76:79], v[144:147], v[192:195], v[76:79]
	v_mfma_f32_16x16x32_bf16 v[76:79], v[148:151], v[200:203], v[76:79]
	v_mfma_f32_16x16x32_bf16 v[112:115], v[152:155], v[168:171], v[112:115]
	v_mfma_f32_16x16x32_bf16 v[112:115], v[156:159], v[172:175], v[112:115]
	v_mfma_f32_16x16x32_bf16 v[104:107], v[160:163], v[168:171], v[104:107]
	v_mfma_f32_16x16x32_bf16 v[104:107], v[164:167], v[172:175], v[104:107]
	v_mfma_f32_16x16x32_bf16 v[96:99], v[152:155], v[176:179], v[96:99]
	v_mfma_f32_16x16x32_bf16 v[96:99], v[156:159], v[180:183], v[96:99]
	v_mfma_f32_16x16x32_bf16 v[88:91], v[160:163], v[176:179], v[88:91]
	v_mfma_f32_16x16x32_bf16 v[88:91], v[164:167], v[180:183], v[88:91]
	v_mfma_f32_16x16x32_bf16 v[80:83], v[152:155], v[184:187], v[80:83]
	v_mfma_f32_16x16x32_bf16 v[80:83], v[156:159], v[188:191], v[80:83]
	v_mfma_f32_16x16x32_bf16 v[72:75], v[160:163], v[184:187], v[72:75]
	v_mfma_f32_16x16x32_bf16 v[72:75], v[164:167], v[188:191], v[72:75]
	v_mfma_f32_16x16x32_bf16 v[68:71], v[152:155], v[192:195], v[68:71]
	v_mfma_f32_16x16x32_bf16 v[68:71], v[156:159], v[200:203], v[68:71]
	v_mfma_f32_16x16x32_bf16 v[64:67], v[160:163], v[192:195], v[64:67]
	v_mfma_f32_16x16x32_bf16 v[64:67], v[164:167], v[200:203], v[64:67]
	s_barrier
	s_setprio 0
	s_add_i32 s23, s23, s97
	s_mov_b64 s[74:75], s[38:39]
	s_mov_b32 m0, s23
	ds_read_b128 v[168:171], v135 offset:16384
	ds_read_b128 v[172:175], v135 offset:17408
	ds_read_b128 v[176:179], v135 offset:18432
	ds_read_b128 v[180:183], v135 offset:19456
	ds_read_b128 v[184:187], v135 offset:20480
	ds_read_b128 v[188:191], v135 offset:21504
	ds_read_b128 v[192:195], v135 offset:22528
	ds_read_b128 v[200:203], v135 offset:23552
	s_nop 0
	global_load_lds_dwordx4 v132, s[74:75]
	s_add_i32 m0, s23, 0x2000
	s_nop 0
	global_load_lds_dwordx4 v130, s[74:75]
	s_add_u32 s74, s38, 0x80000
	s_addc_u32 s75, s39, 0
	s_add_i32 s23, s46, s97
	s_mov_b32 m0, s23
	s_nop 0
	global_load_lds_dwordx4 v132, s[74:75]
	s_add_i32 m0, s23, 0x2000
	s_nop 0
	global_load_lds_dwordx4 v130, s[74:75]
	s_mov_b64 s[74:75], s[40:41]
	s_mov_b32 m0, s27
	s_nop 0
	global_load_lds_dwordx4 v133, s[74:75]
	s_mov_b32 m0, s29
	s_nop 0
	global_load_lds_dwordx4 v131, s[74:75]
	s_waitcnt vmcnt(8)
	s_waitcnt lgkmcnt(0)
	s_setprio 1
	s_barrier
	v_mfma_f32_16x16x32_bf16 v[60:63], v[136:139], v[168:171], v[60:63]
	v_mfma_f32_16x16x32_bf16 v[60:63], v[140:143], v[172:175], v[60:63]
	v_mfma_f32_16x16x32_bf16 v[56:59], v[144:147], v[168:171], v[56:59]
	v_mfma_f32_16x16x32_bf16 v[56:59], v[148:151], v[172:175], v[56:59]
	v_mfma_f32_16x16x32_bf16 v[52:55], v[136:139], v[176:179], v[52:55]
	v_mfma_f32_16x16x32_bf16 v[52:55], v[140:143], v[180:183], v[52:55]
	v_mfma_f32_16x16x32_bf16 v[44:47], v[144:147], v[176:179], v[44:47]
	v_mfma_f32_16x16x32_bf16 v[44:47], v[148:151], v[180:183], v[44:47]
	v_mfma_f32_16x16x32_bf16 v[36:39], v[136:139], v[184:187], v[36:39]
	v_mfma_f32_16x16x32_bf16 v[36:39], v[140:143], v[188:191], v[36:39]
	v_mfma_f32_16x16x32_bf16 v[28:31], v[144:147], v[184:187], v[28:31]
	v_mfma_f32_16x16x32_bf16 v[28:31], v[148:151], v[188:191], v[28:31]
	v_mfma_f32_16x16x32_bf16 v[20:23], v[136:139], v[192:195], v[20:23]
	v_mfma_f32_16x16x32_bf16 v[20:23], v[140:143], v[200:203], v[20:23]
	v_mfma_f32_16x16x32_bf16 v[12:15], v[144:147], v[192:195], v[12:15]
	v_mfma_f32_16x16x32_bf16 v[12:15], v[148:151], v[200:203], v[12:15]
	v_mfma_f32_16x16x32_bf16 v[48:51], v[152:155], v[168:171], v[48:51]
	v_mfma_f32_16x16x32_bf16 v[48:51], v[156:159], v[172:175], v[48:51]
	v_mfma_f32_16x16x32_bf16 v[40:43], v[160:163], v[168:171], v[40:43]
	v_mfma_f32_16x16x32_bf16 v[40:43], v[164:167], v[172:175], v[40:43]
	v_mfma_f32_16x16x32_bf16 v[32:35], v[152:155], v[176:179], v[32:35]
	v_mfma_f32_16x16x32_bf16 v[32:35], v[156:159], v[180:183], v[32:35]
	v_mfma_f32_16x16x32_bf16 v[24:27], v[160:163], v[176:179], v[24:27]
	v_mfma_f32_16x16x32_bf16 v[24:27], v[164:167], v[180:183], v[24:27]
	v_mfma_f32_16x16x32_bf16 v[16:19], v[152:155], v[184:187], v[16:19]
	v_mfma_f32_16x16x32_bf16 v[16:19], v[156:159], v[188:191], v[16:19]
	v_mfma_f32_16x16x32_bf16 v[8:11], v[160:163], v[184:187], v[8:11]
	v_mfma_f32_16x16x32_bf16 v[8:11], v[164:167], v[188:191], v[8:11]
	v_mfma_f32_16x16x32_bf16 v[4:7], v[152:155], v[192:195], v[4:7]
	v_mfma_f32_16x16x32_bf16 v[4:7], v[156:159], v[200:203], v[4:7]
	v_mfma_f32_16x16x32_bf16 v[0:3], v[160:163], v[192:195], v[0:3]
	v_mfma_f32_16x16x32_bf16 v[0:3], v[164:167], v[200:203], v[0:3]
	s_barrier
	s_setprio 0
	s_add_i32 s23, 0, 0x18000
	v_add_u32_e32 v128, s23, v134
	s_add_i32 s46, 0, 0x1c000
	ds_read_b128 v[136:139], v128
	ds_read_b128 v[140:143], v128 offset:1024
	ds_read_b128 v[144:147], v128 offset:2048
	ds_read_b128 v[148:151], v128 offset:3072
	v_add_u32_e32 v128, s46, v134
	ds_read_b128 v[152:155], v128
	ds_read_b128 v[156:159], v128 offset:1024
	ds_read_b128 v[160:163], v128 offset:2048
	ds_read_b128 v[164:167], v128 offset:3072
	s_add_u32 s40, s40, 0x80000
	s_addc_u32 s41, s41, 0
	s_mov_b32 m0, s56
	ds_read_b128 v[168:171], v135 offset:32768
	ds_read_b128 v[172:175], v135 offset:33792
	ds_read_b128 v[176:179], v135 offset:34816
	ds_read_b128 v[180:183], v135 offset:35840
	ds_read_b128 v[184:187], v135 offset:36864
	ds_read_b128 v[188:191], v135 offset:37888
	ds_read_b128 v[192:195], v135 offset:38912
	ds_read_b128 v[200:203], v135 offset:39936
	s_nop 0
	global_load_lds_dwordx4 v133, s[40:41]
	s_mov_b32 m0, s57
	s_nop 0
	global_load_lds_dwordx4 v131, s[40:41]
	s_waitcnt vmcnt(8)
	s_waitcnt lgkmcnt(0)
	s_setprio 1
	s_barrier
	v_mfma_f32_16x16x32_bf16 v[124:127], v[136:139], v[168:171], v[124:127]
	v_mfma_f32_16x16x32_bf16 v[124:127], v[140:143], v[172:175], v[124:127]
	v_mfma_f32_16x16x32_bf16 v[120:123], v[144:147], v[168:171], v[120:123]
	v_mfma_f32_16x16x32_bf16 v[120:123], v[148:151], v[172:175], v[120:123]
	v_mfma_f32_16x16x32_bf16 v[116:119], v[136:139], v[176:179], v[116:119]
	v_mfma_f32_16x16x32_bf16 v[116:119], v[140:143], v[180:183], v[116:119]
	v_mfma_f32_16x16x32_bf16 v[108:111], v[144:147], v[176:179], v[108:111]
	v_mfma_f32_16x16x32_bf16 v[108:111], v[148:151], v[180:183], v[108:111]
	v_mfma_f32_16x16x32_bf16 v[100:103], v[136:139], v[184:187], v[100:103]
	v_mfma_f32_16x16x32_bf16 v[100:103], v[140:143], v[188:191], v[100:103]
	v_mfma_f32_16x16x32_bf16 v[92:95], v[144:147], v[184:187], v[92:95]
	v_mfma_f32_16x16x32_bf16 v[92:95], v[148:151], v[188:191], v[92:95]
	v_mfma_f32_16x16x32_bf16 v[84:87], v[136:139], v[192:195], v[84:87]
	v_mfma_f32_16x16x32_bf16 v[84:87], v[140:143], v[200:203], v[84:87]
	v_mfma_f32_16x16x32_bf16 v[76:79], v[144:147], v[192:195], v[76:79]
	v_mfma_f32_16x16x32_bf16 v[76:79], v[148:151], v[200:203], v[76:79]
	v_mfma_f32_16x16x32_bf16 v[112:115], v[152:155], v[168:171], v[112:115]
	v_mfma_f32_16x16x32_bf16 v[112:115], v[156:159], v[172:175], v[112:115]
	v_mfma_f32_16x16x32_bf16 v[104:107], v[160:163], v[168:171], v[104:107]
	v_mfma_f32_16x16x32_bf16 v[104:107], v[164:167], v[172:175], v[104:107]
	v_mfma_f32_16x16x32_bf16 v[96:99], v[152:155], v[176:179], v[96:99]
	v_mfma_f32_16x16x32_bf16 v[96:99], v[156:159], v[180:183], v[96:99]
	v_mfma_f32_16x16x32_bf16 v[88:91], v[160:163], v[176:179], v[88:91]
	v_mfma_f32_16x16x32_bf16 v[88:91], v[164:167], v[180:183], v[88:91]
	v_mfma_f32_16x16x32_bf16 v[80:83], v[152:155], v[184:187], v[80:83]
	v_mfma_f32_16x16x32_bf16 v[80:83], v[156:159], v[188:191], v[80:83]
	v_mfma_f32_16x16x32_bf16 v[72:75], v[160:163], v[184:187], v[72:75]
	v_mfma_f32_16x16x32_bf16 v[72:75], v[164:167], v[188:191], v[72:75]
	v_mfma_f32_16x16x32_bf16 v[68:71], v[152:155], v[192:195], v[68:71]
	v_mfma_f32_16x16x32_bf16 v[68:71], v[156:159], v[200:203], v[68:71]
	v_mfma_f32_16x16x32_bf16 v[64:67], v[160:163], v[192:195], v[64:67]
	v_mfma_f32_16x16x32_bf16 v[64:67], v[164:167], v[200:203], v[64:67]
	s_barrier
	s_setprio 0
	s_add_u32 s40, s38, 0x80
	s_addc_u32 s41, s39, 0
	s_add_i32 s23, s23, s97
	s_mov_b32 m0, s23
	ds_read_b128 v[168:171], v135 offset:49152
	ds_read_b128 v[172:175], v135 offset:50176
	ds_read_b128 v[176:179], v135 offset:51200
	ds_read_b128 v[180:183], v135 offset:52224
	ds_read_b128 v[184:187], v135 offset:53248
	ds_read_b128 v[188:191], v135 offset:54272
	ds_read_b128 v[192:195], v135 offset:55296
	ds_read_b128 v[200:203], v135 offset:56320
	s_nop 0
	global_load_lds_dwordx4 v132, s[40:41]
	s_add_i32 m0, s23, 0x2000
	s_add_u32 s38, s38, 0x80080
	s_addc_u32 s39, s39, 0
	s_add_i32 s23, s46, s97
	s_nop 0
	global_load_lds_dwordx4 v130, s[40:41]
	s_mov_b32 m0, s23
	s_nop 0
	global_load_lds_dwordx4 v132, s[38:39]
	s_add_i32 m0, s23, 0x2000
	s_nop 0
	global_load_lds_dwordx4 v130, s[38:39]
	s_mov_b32 m0, s70
	s_nop 0
	global_load_lds_dwordx4 v133, s[36:37]
	s_mov_b32 m0, s71
	s_nop 0
	global_load_lds_dwordx4 v131, s[36:37]
	s_waitcnt vmcnt(8)
	s_waitcnt lgkmcnt(0)
	s_setprio 1
	s_barrier
	v_mfma_f32_16x16x32_bf16 v[60:63], v[136:139], v[168:171], v[60:63]
	v_mfma_f32_16x16x32_bf16 v[60:63], v[140:143], v[172:175], v[60:63]
	v_mfma_f32_16x16x32_bf16 v[56:59], v[144:147], v[168:171], v[56:59]
	v_mfma_f32_16x16x32_bf16 v[56:59], v[148:151], v[172:175], v[56:59]
	v_mfma_f32_16x16x32_bf16 v[52:55], v[136:139], v[176:179], v[52:55]
	v_mfma_f32_16x16x32_bf16 v[52:55], v[140:143], v[180:183], v[52:55]
	v_mfma_f32_16x16x32_bf16 v[44:47], v[144:147], v[176:179], v[44:47]
	v_mfma_f32_16x16x32_bf16 v[44:47], v[148:151], v[180:183], v[44:47]
	v_mfma_f32_16x16x32_bf16 v[36:39], v[136:139], v[184:187], v[36:39]
	v_mfma_f32_16x16x32_bf16 v[36:39], v[140:143], v[188:191], v[36:39]
	v_mfma_f32_16x16x32_bf16 v[28:31], v[144:147], v[184:187], v[28:31]
	v_mfma_f32_16x16x32_bf16 v[28:31], v[148:151], v[188:191], v[28:31]
	v_mfma_f32_16x16x32_bf16 v[20:23], v[136:139], v[192:195], v[20:23]
	v_mfma_f32_16x16x32_bf16 v[20:23], v[140:143], v[200:203], v[20:23]
	v_mfma_f32_16x16x32_bf16 v[12:15], v[144:147], v[192:195], v[12:15]
	v_mfma_f32_16x16x32_bf16 v[12:15], v[148:151], v[200:203], v[12:15]
	v_mfma_f32_16x16x32_bf16 v[48:51], v[152:155], v[168:171], v[48:51]
	v_mfma_f32_16x16x32_bf16 v[48:51], v[156:159], v[172:175], v[48:51]
	v_mfma_f32_16x16x32_bf16 v[40:43], v[160:163], v[168:171], v[40:43]
	v_mfma_f32_16x16x32_bf16 v[40:43], v[164:167], v[172:175], v[40:43]
	v_mfma_f32_16x16x32_bf16 v[32:35], v[152:155], v[176:179], v[32:35]
	v_mfma_f32_16x16x32_bf16 v[32:35], v[156:159], v[180:183], v[32:35]
	v_mfma_f32_16x16x32_bf16 v[24:27], v[160:163], v[176:179], v[24:27]
	v_mfma_f32_16x16x32_bf16 v[24:27], v[164:167], v[180:183], v[24:27]
	v_mfma_f32_16x16x32_bf16 v[16:19], v[152:155], v[184:187], v[16:19]
	v_mfma_f32_16x16x32_bf16 v[16:19], v[156:159], v[188:191], v[16:19]
	v_mfma_f32_16x16x32_bf16 v[8:11], v[160:163], v[184:187], v[8:11]
	v_mfma_f32_16x16x32_bf16 v[8:11], v[164:167], v[188:191], v[8:11]
	v_mfma_f32_16x16x32_bf16 v[4:7], v[152:155], v[192:195], v[4:7]
	v_mfma_f32_16x16x32_bf16 v[4:7], v[156:159], v[200:203], v[4:7]
	v_mfma_f32_16x16x32_bf16 v[0:3], v[160:163], v[192:195], v[0:3]
	v_mfma_f32_16x16x32_bf16 v[0:3], v[164:167], v[200:203], v[0:3]
	s_barrier
	s_setprio 0
	s_add_i32 s21, s21, 2
	s_add_u32 s4, s4, 0x100
	s_addc_u32 s5, s5, 0
	s_add_u32 s15, s15, 0x100
	s_addc_u32 s17, s17, 0
	s_add_u32 s34, s34, 0x100
	s_addc_u32 s35, s35, 0
	s_cmp_gt_u32 s21, 13
	s_cbranch_scc0 .LBB0_1290
	s_and_b64 vcc, exec, s[60:61]
	s_cbranch_vccz .LBB0_1293
	s_barrier

.LBB0_1425:
	s_cmpk_eq_i32 s80, 0x54
	s_cselect_b32 s56, s48, s4
	s_cselect_b32 s57, s49, s5
	s_cselect_b32 s74, s70, s15
	s_cselect_b32 s75, s71, s72
	s_add_u32 s16, s56, 0x80
	s_addc_u32 s17, s57, 0
	s_add_i32 s81, 0, 0x10000
	s_add_i32 vcc_lo, 0, 0x14000
	v_add_u32_e32 v136, s81, v172
	v_add_u32_e32 v156, vcc_lo, v172
	ds_read_b128 v[120:123], v136
	ds_read_b128 v[124:127], v136 offset:1024
	ds_read_b128 v[132:135], v136 offset:2048
	ds_read_b128 v[136:139], v136 offset:3072
	ds_read_b128 v[144:147], v156
	ds_read_b128 v[148:151], v156 offset:1024
	ds_read_b128 v[152:155], v156 offset:2048
	ds_read_b128 v[156:159], v156 offset:3072
	s_mov_b64 s[12:13], s[28:29]
	s_add_i32 m0, s2, 0xc000
	ds_read_b128 v[160:163], v173
	ds_read_b128 v[164:167], v173 offset:1024
	ds_read_b128 v[174:177], v173 offset:2048
	ds_read_b128 v[178:181], v173 offset:3072
	ds_read_b128 v[182:185], v173 offset:4096
	ds_read_b128 v[186:189], v173 offset:5120
	ds_read_b128 v[190:193], v173 offset:6144
	ds_read_b128 v[200:203], v173 offset:7168
	s_nop 0
	global_load_lds_dwordx4 v168, s[12:13]
	s_add_i32 m0, s2, 0xe000
	s_nop 0
	global_load_lds_dwordx4 v170, s[12:13]
	s_waitcnt vmcnt(8)
	s_waitcnt lgkmcnt(0)
	s_setprio 1
	s_barrier
	v_mfma_f32_16x16x32_bf16 v[140:143], v[120:123], v[160:163], v[140:143]
	v_mfma_f32_16x16x32_bf16 v[140:143], v[124:127], v[164:167], v[140:143]
	v_mfma_f32_16x16x32_bf16 v[128:131], v[132:135], v[160:163], v[128:131]
	v_mfma_f32_16x16x32_bf16 v[128:131], v[136:139], v[164:167], v[128:131]
	v_mfma_f32_16x16x32_bf16 v[116:119], v[120:123], v[174:177], v[116:119]
	v_mfma_f32_16x16x32_bf16 v[116:119], v[124:127], v[178:181], v[116:119]
	v_mfma_f32_16x16x32_bf16 v[104:107], v[132:135], v[174:177], v[104:107]
	v_mfma_f32_16x16x32_bf16 v[104:107], v[136:139], v[178:181], v[104:107]
	v_mfma_f32_16x16x32_bf16 v[96:99], v[120:123], v[182:185], v[96:99]
	v_mfma_f32_16x16x32_bf16 v[96:99], v[124:127], v[186:189], v[96:99]
	v_mfma_f32_16x16x32_bf16 v[88:91], v[132:135], v[182:185], v[88:91]
	v_mfma_f32_16x16x32_bf16 v[88:91], v[136:139], v[186:189], v[88:91]
	v_mfma_f32_16x16x32_bf16 v[84:87], v[120:123], v[190:193], v[84:87]
	v_mfma_f32_16x16x32_bf16 v[84:87], v[124:127], v[200:203], v[84:87]
	v_mfma_f32_16x16x32_bf16 v[72:75], v[132:135], v[190:193], v[72:75]
	v_mfma_f32_16x16x32_bf16 v[72:75], v[136:139], v[200:203], v[72:75]
	v_mfma_f32_16x16x32_bf16 v[112:115], v[144:147], v[160:163], v[112:115]
	v_mfma_f32_16x16x32_bf16 v[112:115], v[148:151], v[164:167], v[112:115]
	v_mfma_f32_16x16x32_bf16 v[108:111], v[152:155], v[160:163], v[108:111]
	v_mfma_f32_16x16x32_bf16 v[108:111], v[156:159], v[164:167], v[108:111]
	v_mfma_f32_16x16x32_bf16 v[100:103], v[144:147], v[174:177], v[100:103]
	v_mfma_f32_16x16x32_bf16 v[100:103], v[148:151], v[178:181], v[100:103]
	v_mfma_f32_16x16x32_bf16 v[92:95], v[152:155], v[174:177], v[92:95]
	v_mfma_f32_16x16x32_bf16 v[92:95], v[156:159], v[178:181], v[92:95]
	v_mfma_f32_16x16x32_bf16 v[80:83], v[144:147], v[182:185], v[80:83]
	v_mfma_f32_16x16x32_bf16 v[80:83], v[148:151], v[186:189], v[80:83]
	v_mfma_f32_16x16x32_bf16 v[76:79], v[152:155], v[182:185], v[76:79]
	v_mfma_f32_16x16x32_bf16 v[76:79], v[156:159], v[186:189], v[76:79]
	v_mfma_f32_16x16x32_bf16 v[68:71], v[144:147], v[190:193], v[68:71]
	v_mfma_f32_16x16x32_bf16 v[68:71], v[148:151], v[200:203], v[68:71]
	v_mfma_f32_16x16x32_bf16 v[64:67], v[152:155], v[190:193], v[64:67]
	v_mfma_f32_16x16x32_bf16 v[64:67], v[156:159], v[200:203], v[64:67]
	s_barrier
	s_setprio 0
	s_add_i32 s81, s81, s97
	s_mov_b64 s[12:13], s[74:75]
	s_mov_b32 m0, s81
	ds_read_b128 v[160:163], v173 offset:16384
	ds_read_b128 v[164:167], v173 offset:17408
	ds_read_b128 v[174:177], v173 offset:18432
	ds_read_b128 v[178:181], v173 offset:19456
	ds_read_b128 v[182:185], v173 offset:20480
	ds_read_b128 v[186:189], v173 offset:21504
	ds_read_b128 v[190:193], v173 offset:22528
	ds_read_b128 v[200:203], v173 offset:23552
	s_nop 0
	global_load_lds_dwordx4 v169, s[12:13]
	s_add_i32 m0, s81, 0x2000
	s_nop 0
	global_load_lds_dwordx4 v171, s[12:13]
	s_add_u32 s12, s74, 0x160000
	s_addc_u32 s13, s75, 0
	s_add_i32 s81, vcc_lo, s97
	s_mov_b32 m0, s81
	s_nop 0
	global_load_lds_dwordx4 v169, s[12:13]
	s_add_i32 m0, s81, 0x2000
	s_nop 0
	global_load_lds_dwordx4 v171, s[12:13]
	s_mov_b64 s[12:13], s[56:57]
	s_mov_b32 m0, s2
	s_nop 0
	global_load_lds_dwordx4 v168, s[12:13]
	s_mov_b32 m0, s65
	s_nop 0
	global_load_lds_dwordx4 v170, s[12:13]
	s_waitcnt vmcnt(8)
	s_waitcnt lgkmcnt(0)
	s_setprio 1
	s_barrier
	v_mfma_f32_16x16x32_bf16 v[60:63], v[120:123], v[160:163], v[60:63]
	v_mfma_f32_16x16x32_bf16 v[60:63], v[124:127], v[164:167], v[60:63]
	v_mfma_f32_16x16x32_bf16 v[56:59], v[132:135], v[160:163], v[56:59]
	v_mfma_f32_16x16x32_bf16 v[56:59], v[136:139], v[164:167], v[56:59]
	v_mfma_f32_16x16x32_bf16 v[48:51], v[120:123], v[174:177], v[48:51]
	v_mfma_f32_16x16x32_bf16 v[48:51], v[124:127], v[178:181], v[48:51]
	v_mfma_f32_16x16x32_bf16 v[40:43], v[132:135], v[174:177], v[40:43]
	v_mfma_f32_16x16x32_bf16 v[40:43], v[136:139], v[178:181], v[40:43]
	v_mfma_f32_16x16x32_bf16 v[32:35], v[120:123], v[182:185], v[32:35]
	v_mfma_f32_16x16x32_bf16 v[32:35], v[124:127], v[186:189], v[32:35]
	v_mfma_f32_16x16x32_bf16 v[24:27], v[132:135], v[182:185], v[24:27]
	v_mfma_f32_16x16x32_bf16 v[24:27], v[136:139], v[186:189], v[24:27]
	v_mfma_f32_16x16x32_bf16 v[16:19], v[120:123], v[190:193], v[16:19]
	v_mfma_f32_16x16x32_bf16 v[16:19], v[124:127], v[200:203], v[16:19]
	v_mfma_f32_16x16x32_bf16 v[8:11], v[132:135], v[190:193], v[8:11]
	v_mfma_f32_16x16x32_bf16 v[8:11], v[136:139], v[200:203], v[8:11]
	v_mfma_f32_16x16x32_bf16 v[52:55], v[144:147], v[160:163], v[52:55]
	v_mfma_f32_16x16x32_bf16 v[52:55], v[148:151], v[164:167], v[52:55]
	v_mfma_f32_16x16x32_bf16 v[44:47], v[152:155], v[160:163], v[44:47]
	v_mfma_f32_16x16x32_bf16 v[44:47], v[156:159], v[164:167], v[44:47]
	v_mfma_f32_16x16x32_bf16 v[36:39], v[144:147], v[174:177], v[36:39]
	v_mfma_f32_16x16x32_bf16 v[36:39], v[148:151], v[178:181], v[36:39]
	v_mfma_f32_16x16x32_bf16 v[28:31], v[152:155], v[174:177], v[28:31]
	v_mfma_f32_16x16x32_bf16 v[28:31], v[156:159], v[178:181], v[28:31]
	v_mfma_f32_16x16x32_bf16 v[20:23], v[144:147], v[182:185], v[20:23]
	v_mfma_f32_16x16x32_bf16 v[20:23], v[148:151], v[186:189], v[20:23]
	v_mfma_f32_16x16x32_bf16 v[12:15], v[152:155], v[182:185], v[12:15]
	v_mfma_f32_16x16x32_bf16 v[12:15], v[156:159], v[186:189], v[12:15]
	v_mfma_f32_16x16x32_bf16 v[4:7], v[144:147], v[190:193], v[4:7]
	v_mfma_f32_16x16x32_bf16 v[4:7], v[148:151], v[200:203], v[4:7]
	v_mfma_f32_16x16x32_bf16 v[0:3], v[152:155], v[190:193], v[0:3]
	v_mfma_f32_16x16x32_bf16 v[0:3], v[156:159], v[200:203], v[0:3]
	s_barrier
	s_setprio 0
	s_add_i32 s81, 0, 0x18000
	s_add_i32 vcc_lo, 0, 0x1c000
	v_add_u32_e32 v136, s81, v172
	v_add_u32_e32 v156, vcc_lo, v172
	ds_read_b128 v[120:123], v136
	ds_read_b128 v[124:127], v136 offset:1024
	ds_read_b128 v[132:135], v136 offset:2048
	ds_read_b128 v[136:139], v136 offset:3072
	ds_read_b128 v[144:147], v156
	ds_read_b128 v[148:151], v156 offset:1024
	ds_read_b128 v[152:155], v156 offset:2048
	ds_read_b128 v[156:159], v156 offset:3072
	s_add_u32 s12, s56, 0x160000
	s_addc_u32 s13, s57, 0
	s_mov_b32 m0, s93
	ds_read_b128 v[160:163], v173 offset:32768
	ds_read_b128 v[164:167], v173 offset:33792
	ds_read_b128 v[174:177], v173 offset:34816
	ds_read_b128 v[178:181], v173 offset:35840
	ds_read_b128 v[182:185], v173 offset:36864
	ds_read_b128 v[186:189], v173 offset:37888
	ds_read_b128 v[190:193], v173 offset:38912
	ds_read_b128 v[200:203], v173 offset:39936
	s_nop 0
	global_load_lds_dwordx4 v168, s[12:13]
	s_mov_b32 m0, s92
	s_nop 0
	global_load_lds_dwordx4 v170, s[12:13]
	s_waitcnt vmcnt(8)
	s_waitcnt lgkmcnt(0)
	s_setprio 1
	s_barrier
	v_mfma_f32_16x16x32_bf16 v[140:143], v[120:123], v[160:163], v[140:143]
	v_mfma_f32_16x16x32_bf16 v[140:143], v[124:127], v[164:167], v[140:143]
	v_mfma_f32_16x16x32_bf16 v[128:131], v[132:135], v[160:163], v[128:131]
	v_mfma_f32_16x16x32_bf16 v[128:131], v[136:139], v[164:167], v[128:131]
	v_mfma_f32_16x16x32_bf16 v[116:119], v[120:123], v[174:177], v[116:119]
	v_mfma_f32_16x16x32_bf16 v[116:119], v[124:127], v[178:181], v[116:119]
	v_mfma_f32_16x16x32_bf16 v[104:107], v[132:135], v[174:177], v[104:107]
	v_mfma_f32_16x16x32_bf16 v[104:107], v[136:139], v[178:181], v[104:107]
	v_mfma_f32_16x16x32_bf16 v[96:99], v[120:123], v[182:185], v[96:99]
	v_mfma_f32_16x16x32_bf16 v[96:99], v[124:127], v[186:189], v[96:99]
	v_mfma_f32_16x16x32_bf16 v[88:91], v[132:135], v[182:185], v[88:91]
	v_mfma_f32_16x16x32_bf16 v[88:91], v[136:139], v[186:189], v[88:91]
	v_mfma_f32_16x16x32_bf16 v[84:87], v[120:123], v[190:193], v[84:87]
	v_mfma_f32_16x16x32_bf16 v[84:87], v[124:127], v[200:203], v[84:87]
	v_mfma_f32_16x16x32_bf16 v[72:75], v[132:135], v[190:193], v[72:75]
	v_mfma_f32_16x16x32_bf16 v[72:75], v[136:139], v[200:203], v[72:75]
	v_mfma_f32_16x16x32_bf16 v[112:115], v[144:147], v[160:163], v[112:115]
	v_mfma_f32_16x16x32_bf16 v[112:115], v[148:151], v[164:167], v[112:115]
	v_mfma_f32_16x16x32_bf16 v[108:111], v[152:155], v[160:163], v[108:111]
	v_mfma_f32_16x16x32_bf16 v[108:111], v[156:159], v[164:167], v[108:111]
	v_mfma_f32_16x16x32_bf16 v[100:103], v[144:147], v[174:177], v[100:103]
	v_mfma_f32_16x16x32_bf16 v[100:103], v[148:151], v[178:181], v[100:103]
	v_mfma_f32_16x16x32_bf16 v[92:95], v[152:155], v[174:177], v[92:95]
	v_mfma_f32_16x16x32_bf16 v[92:95], v[156:159], v[178:181], v[92:95]
	v_mfma_f32_16x16x32_bf16 v[80:83], v[144:147], v[182:185], v[80:83]
	v_mfma_f32_16x16x32_bf16 v[80:83], v[148:151], v[186:189], v[80:83]
	v_mfma_f32_16x16x32_bf16 v[76:79], v[152:155], v[182:185], v[76:79]
	v_mfma_f32_16x16x32_bf16 v[76:79], v[156:159], v[186:189], v[76:79]
	v_mfma_f32_16x16x32_bf16 v[68:71], v[144:147], v[190:193], v[68:71]
	v_mfma_f32_16x16x32_bf16 v[68:71], v[148:151], v[200:203], v[68:71]
	v_mfma_f32_16x16x32_bf16 v[64:67], v[152:155], v[190:193], v[64:67]
	v_mfma_f32_16x16x32_bf16 v[64:67], v[156:159], v[200:203], v[64:67]
	s_barrier
	s_setprio 0
	s_add_u32 s12, s74, 0x80
	s_addc_u32 s13, s75, 0
	s_add_i32 s56, s81, s97
	s_mov_b32 m0, s56
	ds_read_b128 v[160:163], v173 offset:49152
	ds_read_b128 v[164:167], v173 offset:50176
	ds_read_b128 v[174:177], v173 offset:51200
	ds_read_b128 v[178:181], v173 offset:52224
	ds_read_b128 v[182:185], v173 offset:53248
	ds_read_b128 v[186:189], v173 offset:54272
	ds_read_b128 v[190:193], v173 offset:55296
	ds_read_b128 v[200:203], v173 offset:56320
	s_nop 0
	global_load_lds_dwordx4 v169, s[12:13]
	s_add_i32 m0, s56, 0x2000
	s_nop 0
	global_load_lds_dwordx4 v171, s[12:13]
	s_add_u32 s12, s74, 0x160080
	s_addc_u32 s13, s75, 0
	s_add_i32 s56, vcc_lo, s97
	s_mov_b32 m0, s56
	s_nop 0
	global_load_lds_dwordx4 v169, s[12:13]
	s_add_i32 m0, s56, 0x2000
	s_nop 0
	global_load_lds_dwordx4 v171, s[12:13]
	s_mov_b32 m0, s19
	s_nop 0
	global_load_lds_dwordx4 v168, s[16:17]
	s_mov_b32 m0, s89
	s_nop 0
	global_load_lds_dwordx4 v170, s[16:17]
	s_waitcnt vmcnt(8)
	s_waitcnt lgkmcnt(0)
	s_setprio 1
	s_barrier
	v_mfma_f32_16x16x32_bf16 v[60:63], v[120:123], v[160:163], v[60:63]
	v_mfma_f32_16x16x32_bf16 v[60:63], v[124:127], v[164:167], v[60:63]
	v_mfma_f32_16x16x32_bf16 v[56:59], v[132:135], v[160:163], v[56:59]
	v_mfma_f32_16x16x32_bf16 v[56:59], v[136:139], v[164:167], v[56:59]
	v_mfma_f32_16x16x32_bf16 v[48:51], v[120:123], v[174:177], v[48:51]
	v_mfma_f32_16x16x32_bf16 v[48:51], v[124:127], v[178:181], v[48:51]
	v_mfma_f32_16x16x32_bf16 v[40:43], v[132:135], v[174:177], v[40:43]
	v_mfma_f32_16x16x32_bf16 v[40:43], v[136:139], v[178:181], v[40:43]
	v_mfma_f32_16x16x32_bf16 v[32:35], v[120:123], v[182:185], v[32:35]
	v_mfma_f32_16x16x32_bf16 v[32:35], v[124:127], v[186:189], v[32:35]
	v_mfma_f32_16x16x32_bf16 v[24:27], v[132:135], v[182:185], v[24:27]
	v_mfma_f32_16x16x32_bf16 v[24:27], v[136:139], v[186:189], v[24:27]
	v_mfma_f32_16x16x32_bf16 v[16:19], v[120:123], v[190:193], v[16:19]
	v_mfma_f32_16x16x32_bf16 v[16:19], v[124:127], v[200:203], v[16:19]
	v_mfma_f32_16x16x32_bf16 v[8:11], v[132:135], v[190:193], v[8:11]
	v_mfma_f32_16x16x32_bf16 v[8:11], v[136:139], v[200:203], v[8:11]
	v_mfma_f32_16x16x32_bf16 v[52:55], v[144:147], v[160:163], v[52:55]
	v_mfma_f32_16x16x32_bf16 v[52:55], v[148:151], v[164:167], v[52:55]
	v_mfma_f32_16x16x32_bf16 v[44:47], v[152:155], v[160:163], v[44:47]
	v_mfma_f32_16x16x32_bf16 v[44:47], v[156:159], v[164:167], v[44:47]
	v_mfma_f32_16x16x32_bf16 v[36:39], v[144:147], v[174:177], v[36:39]
	v_mfma_f32_16x16x32_bf16 v[36:39], v[148:151], v[178:181], v[36:39]
	v_mfma_f32_16x16x32_bf16 v[28:31], v[152:155], v[174:177], v[28:31]
	v_mfma_f32_16x16x32_bf16 v[28:31], v[156:159], v[178:181], v[28:31]
	v_mfma_f32_16x16x32_bf16 v[20:23], v[144:147], v[182:185], v[20:23]
	v_mfma_f32_16x16x32_bf16 v[20:23], v[148:151], v[186:189], v[20:23]
	v_mfma_f32_16x16x32_bf16 v[12:15], v[152:155], v[182:185], v[12:15]
	v_mfma_f32_16x16x32_bf16 v[12:15], v[156:159], v[186:189], v[12:15]
	v_mfma_f32_16x16x32_bf16 v[4:7], v[144:147], v[190:193], v[4:7]
	v_mfma_f32_16x16x32_bf16 v[4:7], v[148:151], v[200:203], v[4:7]
	v_mfma_f32_16x16x32_bf16 v[0:3], v[152:155], v[190:193], v[0:3]
	v_mfma_f32_16x16x32_bf16 v[0:3], v[156:159], v[200:203], v[0:3]
	s_barrier
	s_setprio 0
	s_add_i32 s80, s80, 2
	s_add_u32 s4, s4, 0x100
	s_addc_u32 s5, s5, 0
	s_add_u32 s15, s15, 0x100
	s_addc_u32 s72, s72, 0
	s_add_u32 s28, s28, 0x100
	s_addc_u32 s29, s29, 0
	s_cmpk_gt_u32 s80, 0x55
	s_cbranch_scc0 .LBB0_1425
	s_and_b64 vcc, exec, s[60:61]
	s_cbranch_vccz .LBB0_1428
	s_barrier

.LBB0_1579:
	s_cmp_eq_u32 s49, 4
	s_cselect_b32 s26, s14, s13
	s_cselect_b32 s27, s15, s21
	s_cselect_b32 s24, s16, s47
	s_cselect_b32 s25, s17, s48
	s_add_u32 s22, s26, 0x80
	s_addc_u32 s23, s27, 0
	s_add_i32 s65, 0, 0x10000
	s_add_i32 s69, 0, 0x14000
	v_add_u32_e32 v132, s65, v154
	v_add_u32_e32 v148, s69, v154
	ds_read_b128 v[112:115], v132
	ds_read_b128 v[120:123], v132 offset:1024
	ds_read_b128 v[128:131], v132 offset:2048
	ds_read_b128 v[132:135], v132 offset:3072
	ds_read_b128 v[144:147], v148
	ds_read_b128 v[156:159], v148 offset:1024
	ds_read_b128 v[160:163], v148 offset:2048
	ds_read_b128 v[164:167], v148 offset:3072
	s_add_u32 s56, s13, 0x15ff80
	s_addc_u32 s57, s21, 0
	s_add_i32 m0, s31, 0xc000
	ds_read_b128 v[168:171], v155
	ds_read_b128 v[172:175], v155 offset:1024
	ds_read_b128 v[176:179], v155 offset:2048
	ds_read_b128 v[180:183], v155 offset:3072
	ds_read_b128 v[184:187], v155 offset:4096
	ds_read_b128 v[188:191], v155 offset:5120
	ds_read_b128 v[192:195], v155 offset:6144
	ds_read_b128 v[200:203], v155 offset:7168
	s_nop 0
	global_load_lds_dwordx4 v151, s[56:57]
	s_add_i32 m0, s31, 0xe000
	s_nop 0
	global_load_lds_dwordx4 v150, s[56:57]
	s_waitcnt vmcnt(8)
	s_waitcnt lgkmcnt(0)
	s_setprio 1
	s_barrier
	v_mfma_f32_16x16x32_bf16 v[140:143], v[112:115], v[168:171], v[140:143]
	v_mfma_f32_16x16x32_bf16 v[140:143], v[120:123], v[172:175], v[140:143]
	v_mfma_f32_16x16x32_bf16 v[136:139], v[128:131], v[168:171], v[136:139]
	v_mfma_f32_16x16x32_bf16 v[136:139], v[132:135], v[172:175], v[136:139]
	v_mfma_f32_16x16x32_bf16 v[108:111], v[112:115], v[176:179], v[108:111]
	v_mfma_f32_16x16x32_bf16 v[108:111], v[120:123], v[180:183], v[108:111]
	v_mfma_f32_16x16x32_bf16 v[104:107], v[128:131], v[176:179], v[104:107]
	v_mfma_f32_16x16x32_bf16 v[104:107], v[132:135], v[180:183], v[104:107]
	v_mfma_f32_16x16x32_bf16 v[92:95], v[112:115], v[184:187], v[92:95]
	v_mfma_f32_16x16x32_bf16 v[92:95], v[120:123], v[188:191], v[92:95]
	v_mfma_f32_16x16x32_bf16 v[88:91], v[128:131], v[184:187], v[88:91]
	v_mfma_f32_16x16x32_bf16 v[88:91], v[132:135], v[188:191], v[88:91]
	v_mfma_f32_16x16x32_bf16 v[76:79], v[112:115], v[192:195], v[76:79]
	v_mfma_f32_16x16x32_bf16 v[76:79], v[120:123], v[200:203], v[76:79]
	v_mfma_f32_16x16x32_bf16 v[72:75], v[128:131], v[192:195], v[72:75]
	v_mfma_f32_16x16x32_bf16 v[72:75], v[132:135], v[200:203], v[72:75]
	v_mfma_f32_16x16x32_bf16 v[124:127], v[144:147], v[168:171], v[124:127]
	v_mfma_f32_16x16x32_bf16 v[124:127], v[156:159], v[172:175], v[124:127]
	v_mfma_f32_16x16x32_bf16 v[116:119], v[160:163], v[168:171], v[116:119]
	v_mfma_f32_16x16x32_bf16 v[116:119], v[164:167], v[172:175], v[116:119]
	v_mfma_f32_16x16x32_bf16 v[100:103], v[144:147], v[176:179], v[100:103]
	v_mfma_f32_16x16x32_bf16 v[100:103], v[156:159], v[180:183], v[100:103]
	v_mfma_f32_16x16x32_bf16 v[96:99], v[160:163], v[176:179], v[96:99]
	v_mfma_f32_16x16x32_bf16 v[96:99], v[164:167], v[180:183], v[96:99]
	v_mfma_f32_16x16x32_bf16 v[84:87], v[144:147], v[184:187], v[84:87]
	v_mfma_f32_16x16x32_bf16 v[84:87], v[156:159], v[188:191], v[84:87]
	v_mfma_f32_16x16x32_bf16 v[80:83], v[160:163], v[184:187], v[80:83]
	v_mfma_f32_16x16x32_bf16 v[80:83], v[164:167], v[188:191], v[80:83]
	v_mfma_f32_16x16x32_bf16 v[68:71], v[144:147], v[192:195], v[68:71]
	v_mfma_f32_16x16x32_bf16 v[68:71], v[156:159], v[200:203], v[68:71]
	v_mfma_f32_16x16x32_bf16 v[64:67], v[160:163], v[192:195], v[64:67]
	v_mfma_f32_16x16x32_bf16 v[64:67], v[164:167], v[200:203], v[64:67]
	s_barrier
	s_setprio 0
	s_add_i32 s65, s65, s97
	s_mov_b64 s[56:57], s[24:25]
	s_mov_b32 m0, s65
	ds_read_b128 v[168:171], v155 offset:16384
	ds_read_b128 v[172:175], v155 offset:17408
	ds_read_b128 v[176:179], v155 offset:18432
	ds_read_b128 v[180:183], v155 offset:19456
	ds_read_b128 v[184:187], v155 offset:20480
	ds_read_b128 v[188:191], v155 offset:21504
	ds_read_b128 v[192:195], v155 offset:22528
	ds_read_b128 v[200:203], v155 offset:23552
	s_nop 0
	global_load_lds_dwordx4 v152, s[56:57]
	s_add_i32 m0, s65, 0x2000
	s_nop 0
	global_load_lds_dwordx4 v153, s[56:57]
	s_add_u32 s56, s24, 0x160000
	s_addc_u32 s57, s25, 0
	s_add_i32 s65, s69, s97
	s_mov_b32 m0, s65
	s_nop 0
	global_load_lds_dwordx4 v152, s[56:57]
	s_add_i32 m0, s65, 0x2000
	s_nop 0
	global_load_lds_dwordx4 v153, s[56:57]
	s_mov_b64 s[56:57], s[26:27]
	s_mov_b32 m0, s31
	s_nop 0
	global_load_lds_dwordx4 v151, s[56:57]
	s_mov_b32 m0, s34
	s_nop 0
	global_load_lds_dwordx4 v150, s[56:57]
	s_waitcnt vmcnt(8)
	s_waitcnt lgkmcnt(0)
	s_setprio 1
	s_barrier
	v_mfma_f32_16x16x32_bf16 v[60:63], v[112:115], v[168:171], v[60:63]
	v_mfma_f32_16x16x32_bf16 v[60:63], v[120:123], v[172:175], v[60:63]
	v_mfma_f32_16x16x32_bf16 v[56:59], v[128:131], v[168:171], v[56:59]
	v_mfma_f32_16x16x32_bf16 v[56:59], v[132:135], v[172:175], v[56:59]
	v_mfma_f32_16x16x32_bf16 v[52:55], v[112:115], v[176:179], v[52:55]
	v_mfma_f32_16x16x32_bf16 v[52:55], v[120:123], v[180:183], v[52:55]
	v_mfma_f32_16x16x32_bf16 v[44:47], v[128:131], v[176:179], v[44:47]
	v_mfma_f32_16x16x32_bf16 v[44:47], v[132:135], v[180:183], v[44:47]
	v_mfma_f32_16x16x32_bf16 v[36:39], v[112:115], v[184:187], v[36:39]
	v_mfma_f32_16x16x32_bf16 v[36:39], v[120:123], v[188:191], v[36:39]
	v_mfma_f32_16x16x32_bf16 v[28:31], v[128:131], v[184:187], v[28:31]
	v_mfma_f32_16x16x32_bf16 v[28:31], v[132:135], v[188:191], v[28:31]
	v_mfma_f32_16x16x32_bf16 v[20:23], v[112:115], v[192:195], v[20:23]
	v_mfma_f32_16x16x32_bf16 v[20:23], v[120:123], v[200:203], v[20:23]
	v_mfma_f32_16x16x32_bf16 v[8:11], v[128:131], v[192:195], v[8:11]
	v_mfma_f32_16x16x32_bf16 v[8:11], v[132:135], v[200:203], v[8:11]
	v_mfma_f32_16x16x32_bf16 v[48:51], v[144:147], v[168:171], v[48:51]
	v_mfma_f32_16x16x32_bf16 v[48:51], v[156:159], v[172:175], v[48:51]
	v_mfma_f32_16x16x32_bf16 v[40:43], v[160:163], v[168:171], v[40:43]
	v_mfma_f32_16x16x32_bf16 v[40:43], v[164:167], v[172:175], v[40:43]
	v_mfma_f32_16x16x32_bf16 v[32:35], v[144:147], v[176:179], v[32:35]
	v_mfma_f32_16x16x32_bf16 v[32:35], v[156:159], v[180:183], v[32:35]
	v_mfma_f32_16x16x32_bf16 v[24:27], v[160:163], v[176:179], v[24:27]
	v_mfma_f32_16x16x32_bf16 v[24:27], v[164:167], v[180:183], v[24:27]
	v_mfma_f32_16x16x32_bf16 v[16:19], v[144:147], v[184:187], v[16:19]
	v_mfma_f32_16x16x32_bf16 v[16:19], v[156:159], v[188:191], v[16:19]
	v_mfma_f32_16x16x32_bf16 v[12:15], v[160:163], v[184:187], v[12:15]
	v_mfma_f32_16x16x32_bf16 v[12:15], v[164:167], v[188:191], v[12:15]
	v_mfma_f32_16x16x32_bf16 v[4:7], v[144:147], v[192:195], v[4:7]
	v_mfma_f32_16x16x32_bf16 v[4:7], v[156:159], v[200:203], v[4:7]
	v_mfma_f32_16x16x32_bf16 v[0:3], v[160:163], v[192:195], v[0:3]
	v_mfma_f32_16x16x32_bf16 v[0:3], v[164:167], v[200:203], v[0:3]
	s_barrier
	s_setprio 0
	s_add_i32 s56, 0, 0x18000
	s_add_i32 s57, 0, 0x1c000
	v_add_u32_e32 v132, s56, v154
	v_add_u32_e32 v148, s57, v154
	ds_read_b128 v[112:115], v132
	ds_read_b128 v[120:123], v132 offset:1024
	ds_read_b128 v[128:131], v132 offset:2048
	ds_read_b128 v[132:135], v132 offset:3072
	ds_read_b128 v[144:147], v148
	ds_read_b128 v[156:159], v148 offset:1024
	ds_read_b128 v[160:163], v148 offset:2048
	ds_read_b128 v[164:167], v148 offset:3072
	s_add_u32 s26, s26, 0x160000
	s_addc_u32 s27, s27, 0
	s_mov_b32 m0, s35
	ds_read_b128 v[168:171], v155 offset:32768
	ds_read_b128 v[172:175], v155 offset:33792
	ds_read_b128 v[176:179], v155 offset:34816
	ds_read_b128 v[180:183], v155 offset:35840
	ds_read_b128 v[184:187], v155 offset:36864
	ds_read_b128 v[188:191], v155 offset:37888
	ds_read_b128 v[192:195], v155 offset:38912
	ds_read_b128 v[200:203], v155 offset:39936
	s_nop 0
	global_load_lds_dwordx4 v151, s[26:27]
	s_mov_b32 m0, s36
	s_nop 0
	global_load_lds_dwordx4 v150, s[26:27]
	s_waitcnt vmcnt(8)
	s_waitcnt lgkmcnt(0)
	s_setprio 1
	s_barrier
	v_mfma_f32_16x16x32_bf16 v[140:143], v[112:115], v[168:171], v[140:143]
	v_mfma_f32_16x16x32_bf16 v[140:143], v[120:123], v[172:175], v[140:143]
	v_mfma_f32_16x16x32_bf16 v[136:139], v[128:131], v[168:171], v[136:139]
	v_mfma_f32_16x16x32_bf16 v[136:139], v[132:135], v[172:175], v[136:139]
	v_mfma_f32_16x16x32_bf16 v[108:111], v[112:115], v[176:179], v[108:111]
	v_mfma_f32_16x16x32_bf16 v[108:111], v[120:123], v[180:183], v[108:111]
	v_mfma_f32_16x16x32_bf16 v[104:107], v[128:131], v[176:179], v[104:107]
	v_mfma_f32_16x16x32_bf16 v[104:107], v[132:135], v[180:183], v[104:107]
	v_mfma_f32_16x16x32_bf16 v[92:95], v[112:115], v[184:187], v[92:95]
	v_mfma_f32_16x16x32_bf16 v[92:95], v[120:123], v[188:191], v[92:95]
	v_mfma_f32_16x16x32_bf16 v[88:91], v[128:131], v[184:187], v[88:91]
	v_mfma_f32_16x16x32_bf16 v[88:91], v[132:135], v[188:191], v[88:91]
	v_mfma_f32_16x16x32_bf16 v[76:79], v[112:115], v[192:195], v[76:79]
	v_mfma_f32_16x16x32_bf16 v[76:79], v[120:123], v[200:203], v[76:79]
	v_mfma_f32_16x16x32_bf16 v[72:75], v[128:131], v[192:195], v[72:75]
	v_mfma_f32_16x16x32_bf16 v[72:75], v[132:135], v[200:203], v[72:75]
	v_mfma_f32_16x16x32_bf16 v[124:127], v[144:147], v[168:171], v[124:127]
	v_mfma_f32_16x16x32_bf16 v[124:127], v[156:159], v[172:175], v[124:127]
	v_mfma_f32_16x16x32_bf16 v[116:119], v[160:163], v[168:171], v[116:119]
	v_mfma_f32_16x16x32_bf16 v[116:119], v[164:167], v[172:175], v[116:119]
	v_mfma_f32_16x16x32_bf16 v[100:103], v[144:147], v[176:179], v[100:103]
	v_mfma_f32_16x16x32_bf16 v[100:103], v[156:159], v[180:183], v[100:103]
	v_mfma_f32_16x16x32_bf16 v[96:99], v[160:163], v[176:179], v[96:99]
	v_mfma_f32_16x16x32_bf16 v[96:99], v[164:167], v[180:183], v[96:99]
	v_mfma_f32_16x16x32_bf16 v[84:87], v[144:147], v[184:187], v[84:87]
	v_mfma_f32_16x16x32_bf16 v[84:87], v[156:159], v[188:191], v[84:87]
	v_mfma_f32_16x16x32_bf16 v[80:83], v[160:163], v[184:187], v[80:83]
	v_mfma_f32_16x16x32_bf16 v[80:83], v[164:167], v[188:191], v[80:83]
	v_mfma_f32_16x16x32_bf16 v[68:71], v[144:147], v[192:195], v[68:71]
	v_mfma_f32_16x16x32_bf16 v[68:71], v[156:159], v[200:203], v[68:71]
	v_mfma_f32_16x16x32_bf16 v[64:67], v[160:163], v[192:195], v[64:67]
	v_mfma_f32_16x16x32_bf16 v[64:67], v[164:167], v[200:203], v[64:67]
	s_barrier
	s_setprio 0
	s_add_u32 s26, s24, 0x80
	s_addc_u32 s27, s25, 0
	s_add_i32 s56, s56, s97
	s_mov_b32 m0, s56
	ds_read_b128 v[168:171], v155 offset:49152
	ds_read_b128 v[172:175], v155 offset:50176
	ds_read_b128 v[176:179], v155 offset:51200
	ds_read_b128 v[180:183], v155 offset:52224
	ds_read_b128 v[184:187], v155 offset:53248
	ds_read_b128 v[188:191], v155 offset:54272
	ds_read_b128 v[192:195], v155 offset:55296
	ds_read_b128 v[200:203], v155 offset:56320
	s_nop 0
	global_load_lds_dwordx4 v152, s[26:27]
	s_add_i32 m0, s56, 0x2000
	s_add_u32 s24, s24, 0x160080
	s_addc_u32 s25, s25, 0
	global_load_lds_dwordx4 v153, s[26:27]
	s_add_i32 s26, s57, s97
	s_mov_b32 m0, s26
	s_nop 0
	global_load_lds_dwordx4 v152, s[24:25]
	s_add_i32 m0, s26, 0x2000
	s_nop 0
	global_load_lds_dwordx4 v153, s[24:25]
	s_mov_b32 m0, s37
	s_nop 0
	global_load_lds_dwordx4 v151, s[22:23]
	s_mov_b32 m0, s38
	s_nop 0
	global_load_lds_dwordx4 v150, s[22:23]
	s_waitcnt vmcnt(8)
	s_waitcnt lgkmcnt(0)
	s_setprio 1
	s_barrier
	v_mfma_f32_16x16x32_bf16 v[60:63], v[112:115], v[168:171], v[60:63]
	v_mfma_f32_16x16x32_bf16 v[60:63], v[120:123], v[172:175], v[60:63]
	v_mfma_f32_16x16x32_bf16 v[56:59], v[128:131], v[168:171], v[56:59]
	v_mfma_f32_16x16x32_bf16 v[56:59], v[132:135], v[172:175], v[56:59]
	v_mfma_f32_16x16x32_bf16 v[52:55], v[112:115], v[176:179], v[52:55]
	v_mfma_f32_16x16x32_bf16 v[52:55], v[120:123], v[180:183], v[52:55]
	v_mfma_f32_16x16x32_bf16 v[44:47], v[128:131], v[176:179], v[44:47]
	v_mfma_f32_16x16x32_bf16 v[44:47], v[132:135], v[180:183], v[44:47]
	v_mfma_f32_16x16x32_bf16 v[36:39], v[112:115], v[184:187], v[36:39]
	v_mfma_f32_16x16x32_bf16 v[36:39], v[120:123], v[188:191], v[36:39]
	v_mfma_f32_16x16x32_bf16 v[28:31], v[128:131], v[184:187], v[28:31]
	v_mfma_f32_16x16x32_bf16 v[28:31], v[132:135], v[188:191], v[28:31]
	v_mfma_f32_16x16x32_bf16 v[20:23], v[112:115], v[192:195], v[20:23]
	v_mfma_f32_16x16x32_bf16 v[20:23], v[120:123], v[200:203], v[20:23]
	v_mfma_f32_16x16x32_bf16 v[8:11], v[128:131], v[192:195], v[8:11]
	v_mfma_f32_16x16x32_bf16 v[8:11], v[132:135], v[200:203], v[8:11]
	v_mfma_f32_16x16x32_bf16 v[48:51], v[144:147], v[168:171], v[48:51]
	v_mfma_f32_16x16x32_bf16 v[48:51], v[156:159], v[172:175], v[48:51]
	v_mfma_f32_16x16x32_bf16 v[40:43], v[160:163], v[168:171], v[40:43]
	v_mfma_f32_16x16x32_bf16 v[40:43], v[164:167], v[172:175], v[40:43]
	v_mfma_f32_16x16x32_bf16 v[32:35], v[144:147], v[176:179], v[32:35]
	v_mfma_f32_16x16x32_bf16 v[32:35], v[156:159], v[180:183], v[32:35]
	v_mfma_f32_16x16x32_bf16 v[24:27], v[160:163], v[176:179], v[24:27]
	v_mfma_f32_16x16x32_bf16 v[24:27], v[164:167], v[180:183], v[24:27]
	v_mfma_f32_16x16x32_bf16 v[16:19], v[144:147], v[184:187], v[16:19]
	v_mfma_f32_16x16x32_bf16 v[16:19], v[156:159], v[188:191], v[16:19]
	v_mfma_f32_16x16x32_bf16 v[12:15], v[160:163], v[184:187], v[12:15]
	v_mfma_f32_16x16x32_bf16 v[12:15], v[164:167], v[188:191], v[12:15]
	v_mfma_f32_16x16x32_bf16 v[4:7], v[144:147], v[192:195], v[4:7]
	v_mfma_f32_16x16x32_bf16 v[4:7], v[156:159], v[200:203], v[4:7]
	v_mfma_f32_16x16x32_bf16 v[0:3], v[160:163], v[192:195], v[0:3]
	v_mfma_f32_16x16x32_bf16 v[0:3], v[164:167], v[200:203], v[0:3]
	s_barrier
	s_setprio 0
	s_add_i32 s49, s49, 2
	s_add_u32 s13, s13, 0x100
	s_addc_u32 s21, s21, 0
	s_add_u32 s47, s47, 0x100
	s_addc_u32 s48, s48, 0
	s_cmp_gt_u32 s49, 5
	s_cbranch_scc0 .LBB0_1579
	s_and_b64 vcc, exec, s[60:61]
	s_cbranch_vccz .LBB0_1582
	s_barrier
